# Proj0/Proj1 epilogue rope8: nested exec-mask regions (3 saveexec + 3 branches per element, 248 sites) replaced by two v_cndmask, bit-exact
# speedup vs baseline: 1.0126x; 1.0126x over previous
; DI void rope8(float (&v)[8], const float* __restrict__ rope, int s, int fq) {
;     const f32x4 c0 = *(const f32x4*)(rope + s * 16), c1 = *(const f32x4*)(rope + s * 16 + 4), s0 = *(const f32x4*)(rope + s * 16 + 8), s1 = *(const f32x4*)(rope + s * 16 + 12);
;     const float cs[8] = {c0[0], c0[1], c0[2], c0[3], c1[0], c1[1], c1[2], c1[3]}, sn[8] = {s0[0], s0[1], s0[2], s0[3], s1[0], s1[1], s1[2], s1[3]};
; #pragma unroll
;     for (int e = 0; e < 8; ++e) {
;         const float other = __shfl_xor(v[e], 16);
;         const float a = v[e] * cs[e], bq = other * sn[e];
;         v[e] = (fq == 0) ? (a - bq) : ((fq == 1) ? (a + bq) : v[e]);
;     }
.LBB0_201:
	s_andn2_b64 vcc, exec, s[6:7]
	s_cbranch_vccnz .LBB0_251
	v_and_b32_e32 v11, 64, v183
	v_xor_b32_e32 v10, 16, v183
	v_add_u32_e32 v11, 64, v11
	v_cmp_lt_i32_e32 vcc, v10, v11
	v_lshlrev_b32_e32 v138, 6, v154
	s_nop 0
	v_cndmask_b32_e32 v10, v183, v10, vcc
	v_lshlrev_b32_e32 v186, 2, v10
	global_load_dwordx4 v[142:145], v138, s[68:69]
	global_load_dwordx4 v[10:13], v138, s[68:69] offset:32
	global_load_dwordx4 v[14:17], v138, s[68:69] offset:48
	s_nop 0
	global_load_dwordx4 v[138:141], v138, s[68:69] offset:16
	ds_bpermute_b32 v187, v186, v2
	v_cmp_lt_i32_e32 vcc, 0, v1
	s_waitcnt vmcnt(3)
	v_mul_f32_e32 v142, v2, v142
	s_waitcnt vmcnt(2) lgkmcnt(0)
	v_mul_f32_e32 v187, v10, v187
	v_sub_f32_e32 v10, v142, v187
	v_add_f32_e32 v142, v142, v187
	v_cmp_eq_u32_e64 s[0:1], 1, v1
	s_nop 1
	v_cndmask_b32_e64 v142, v2, v142, s[0:1]
	v_cndmask_b32_e32 v10, v10, v142, vcc
	ds_bpermute_b32 v187, v186, v3
	v_mul_f32_e32 v142, v3, v143
	v_cmp_lt_i32_e32 vcc, 0, v1
	s_waitcnt lgkmcnt(0)
	v_mul_f32_e32 v143, v11, v187
	v_sub_f32_e32 v11, v142, v143
	v_add_f32_e32 v142, v142, v143
	v_cmp_eq_u32_e64 s[0:1], 1, v1
	s_nop 1
	v_cndmask_b32_e64 v142, v3, v142, s[0:1]
	v_cndmask_b32_e32 v11, v11, v142, vcc
	ds_bpermute_b32 v143, v186, v4
	v_mul_f32_e32 v142, v4, v144
	v_cmp_lt_i32_e32 vcc, 0, v1
	s_waitcnt lgkmcnt(0)
	v_mul_f32_e32 v143, v12, v143
	v_sub_f32_e32 v12, v142, v143
	v_add_f32_e32 v142, v142, v143
	v_cmp_eq_u32_e64 s[0:1], 1, v1
	s_nop 1
	v_cndmask_b32_e64 v142, v4, v142, s[0:1]
	v_cndmask_b32_e32 v12, v12, v142, vcc
	ds_bpermute_b32 v143, v186, v5
	v_mul_f32_e32 v142, v5, v145
	v_cmp_lt_i32_e32 vcc, 0, v1
	s_waitcnt lgkmcnt(0)
	v_mul_f32_e32 v143, v13, v143
	v_sub_f32_e32 v13, v142, v143
	v_add_f32_e32 v142, v142, v143
	v_cmp_eq_u32_e64 s[0:1], 1, v1
	s_nop 1
	v_cndmask_b32_e64 v142, v5, v142, s[0:1]
	v_cndmask_b32_e32 v13, v13, v142, vcc
	ds_bpermute_b32 v142, v186, v6
	s_waitcnt vmcnt(0)
	v_mul_f32_e32 v138, v6, v138
	v_cmp_lt_i32_e32 vcc, 0, v1
	s_waitcnt lgkmcnt(0)
	v_mul_f32_e32 v142, v14, v142
	v_sub_f32_e32 v14, v138, v142
	v_add_f32_e32 v138, v138, v142
	v_cmp_eq_u32_e64 s[0:1], 1, v1
	s_nop 1
	v_cndmask_b32_e64 v138, v6, v138, s[0:1]
	v_cndmask_b32_e32 v14, v14, v138, vcc
	ds_bpermute_b32 v142, v186, v7
	v_mul_f32_e32 v138, v7, v139
	v_cmp_lt_i32_e32 vcc, 0, v1
	s_waitcnt lgkmcnt(0)
	v_mul_f32_e32 v139, v15, v142
	v_sub_f32_e32 v15, v138, v139
	v_add_f32_e32 v138, v138, v139
	v_cmp_eq_u32_e64 s[0:1], 1, v1
	s_nop 1
	v_cndmask_b32_e64 v138, v7, v138, s[0:1]
	v_cndmask_b32_e32 v15, v15, v138, vcc
	ds_bpermute_b32 v139, v186, v8
	v_mul_f32_e32 v138, v8, v140
	v_cmp_lt_i32_e32 vcc, 0, v1
	s_waitcnt lgkmcnt(0)
	v_mul_f32_e32 v139, v16, v139
	v_sub_f32_e32 v16, v138, v139
	v_add_f32_e32 v138, v138, v139
	v_cmp_eq_u32_e64 s[0:1], 1, v1
	s_nop 1
	v_cndmask_b32_e64 v138, v8, v138, s[0:1]
	v_cndmask_b32_e32 v16, v16, v138, vcc
	ds_bpermute_b32 v139, v186, v9
	v_mul_f32_e32 v138, v9, v141
	v_cmp_lt_i32_e32 vcc, 0, v1
	s_waitcnt lgkmcnt(0)
	v_mul_f32_e32 v139, v17, v139
	v_sub_f32_e32 v17, v138, v139
	v_add_f32_e32 v138, v138, v139
	v_cmp_eq_u32_e64 s[0:1], 1, v1
	s_nop 1
	v_cndmask_b32_e64 v138, v9, v138, s[0:1]
	v_cndmask_b32_e32 v17, v17, v138, vcc

; DI void rope8(float (&v)[8], const float* __restrict__ rope, int s, int fq) {
;     const f32x4 c0 = *(const f32x4*)(rope + s * 16), c1 = *(const f32x4*)(rope + s * 16 + 4), s0 = *(const f32x4*)(rope + s * 16 + 8), s1 = *(const f32x4*)(rope + s * 16 + 12);
;     const float cs[8] = {c0[0], c0[1], c0[2], c0[3], c1[0], c1[1], c1[2], c1[3]}, sn[8] = {s0[0], s0[1], s0[2], s0[3], s1[0], s1[1], s1[2], s1[3]};
; #pragma unroll
;     for (int e = 0; e < 8; ++e) {
;         const float other = __shfl_xor(v[e], 16);
;         const float a = v[e] * cs[e], bq = other * sn[e];
;         v[e] = (fq == 0) ? (a - bq) : ((fq == 1) ? (a + bq) : v[e]);
;     }
.LBB0_267:
	s_andn2_b64 vcc, exec, s[8:9]
	s_cbranch_vccnz .LBB0_317
	v_and_b32_e32 v11, 64, v183
	v_xor_b32_e32 v10, 16, v183
	v_add_u32_e32 v11, 64, v11
	v_cmp_lt_i32_e32 vcc, v10, v11
	v_lshlrev_b32_e32 v130, 6, v140
	s_nop 0
	v_cndmask_b32_e32 v10, v183, v10, vcc
	v_lshlrev_b32_e32 v141, 2, v10
	global_load_dwordx4 v[134:137], v130, s[68:69]
	global_load_dwordx4 v[10:13], v130, s[68:69] offset:32
	global_load_dwordx4 v[14:17], v130, s[68:69] offset:48
	s_nop 0
	global_load_dwordx4 v[130:133], v130, s[68:69] offset:16
	ds_bpermute_b32 v142, v141, v2
	v_cmp_lt_i32_e32 vcc, 0, v1
	s_waitcnt vmcnt(3)
	v_mul_f32_e32 v134, v2, v134
	s_waitcnt vmcnt(2) lgkmcnt(0)
	v_mul_f32_e32 v142, v10, v142
	v_sub_f32_e32 v10, v134, v142
	v_add_f32_e32 v134, v134, v142
	v_cmp_eq_u32_e64 s[0:1], 1, v1
	s_nop 1
	v_cndmask_b32_e64 v134, v2, v134, s[0:1]
	v_cndmask_b32_e32 v10, v10, v134, vcc
	ds_bpermute_b32 v142, v141, v3
	v_mul_f32_e32 v134, v3, v135
	v_cmp_lt_i32_e32 vcc, 0, v1
	s_waitcnt lgkmcnt(0)
	v_mul_f32_e32 v135, v11, v142
	v_sub_f32_e32 v11, v134, v135
	v_add_f32_e32 v134, v134, v135
	v_cmp_eq_u32_e64 s[0:1], 1, v1
	s_nop 1
	v_cndmask_b32_e64 v134, v3, v134, s[0:1]
	v_cndmask_b32_e32 v11, v11, v134, vcc
	ds_bpermute_b32 v135, v141, v4
	v_mul_f32_e32 v134, v4, v136
	v_cmp_lt_i32_e32 vcc, 0, v1
	s_waitcnt lgkmcnt(0)
	v_mul_f32_e32 v135, v12, v135
	v_sub_f32_e32 v12, v134, v135
	v_add_f32_e32 v134, v134, v135
	v_cmp_eq_u32_e64 s[0:1], 1, v1
	s_nop 1
	v_cndmask_b32_e64 v134, v4, v134, s[0:1]
	v_cndmask_b32_e32 v12, v12, v134, vcc
	ds_bpermute_b32 v135, v141, v5
	v_mul_f32_e32 v134, v5, v137
	v_cmp_lt_i32_e32 vcc, 0, v1
	s_waitcnt lgkmcnt(0)
	v_mul_f32_e32 v135, v13, v135
	v_sub_f32_e32 v13, v134, v135
	v_add_f32_e32 v134, v134, v135
	v_cmp_eq_u32_e64 s[0:1], 1, v1
	s_nop 1
	v_cndmask_b32_e64 v134, v5, v134, s[0:1]
	v_cndmask_b32_e32 v13, v13, v134, vcc
	ds_bpermute_b32 v134, v141, v6
	s_waitcnt vmcnt(0)
	v_mul_f32_e32 v130, v6, v130
	v_cmp_lt_i32_e32 vcc, 0, v1
	s_waitcnt lgkmcnt(0)
	v_mul_f32_e32 v134, v14, v134
	v_sub_f32_e32 v14, v130, v134
	v_add_f32_e32 v130, v130, v134
	v_cmp_eq_u32_e64 s[0:1], 1, v1
	s_nop 1
	v_cndmask_b32_e64 v130, v6, v130, s[0:1]
	v_cndmask_b32_e32 v14, v14, v130, vcc
	ds_bpermute_b32 v134, v141, v7
	v_mul_f32_e32 v130, v7, v131
	v_cmp_lt_i32_e32 vcc, 0, v1
	s_waitcnt lgkmcnt(0)
	v_mul_f32_e32 v131, v15, v134
	v_sub_f32_e32 v15, v130, v131
	v_add_f32_e32 v130, v130, v131
	v_cmp_eq_u32_e64 s[0:1], 1, v1
	s_nop 1
	v_cndmask_b32_e64 v130, v7, v130, s[0:1]
	v_cndmask_b32_e32 v15, v15, v130, vcc
	ds_bpermute_b32 v131, v141, v8
	v_mul_f32_e32 v130, v8, v132
	v_cmp_lt_i32_e32 vcc, 0, v1
	s_waitcnt lgkmcnt(0)
	v_mul_f32_e32 v131, v16, v131
	v_sub_f32_e32 v16, v130, v131
	v_add_f32_e32 v130, v130, v131
	v_cmp_eq_u32_e64 s[0:1], 1, v1
	s_nop 1
	v_cndmask_b32_e64 v130, v8, v130, s[0:1]
	v_cndmask_b32_e32 v16, v16, v130, vcc
	ds_bpermute_b32 v131, v141, v9
	v_mul_f32_e32 v130, v9, v133
	v_cmp_lt_i32_e32 vcc, 0, v1
	s_waitcnt lgkmcnt(0)
	v_mul_f32_e32 v131, v17, v131
	v_sub_f32_e32 v17, v130, v131
	v_add_f32_e32 v130, v130, v131
	v_cmp_eq_u32_e64 s[0:1], 1, v1
	s_nop 1
	v_cndmask_b32_e64 v130, v9, v130, s[0:1]
	v_cndmask_b32_e32 v17, v17, v130, vcc

; DI void rope8(float (&v)[8], const float* __restrict__ rope, int s, int fq) {
;     const f32x4 c0 = *(const f32x4*)(rope + s * 16), c1 = *(const f32x4*)(rope + s * 16 + 4), s0 = *(const f32x4*)(rope + s * 16 + 8), s1 = *(const f32x4*)(rope + s * 16 + 12);
;     const float cs[8] = {c0[0], c0[1], c0[2], c0[3], c1[0], c1[1], c1[2], c1[3]}, sn[8] = {s0[0], s0[1], s0[2], s0[3], s1[0], s1[1], s1[2], s1[3]};
; #pragma unroll
;     for (int e = 0; e < 8; ++e) {
;         const float other = __shfl_xor(v[e], 16);
;         const float a = v[e] * cs[e], bq = other * sn[e];
;         v[e] = (fq == 0) ? (a - bq) : ((fq == 1) ? (a + bq) : v[e]);
;     }
.LBB0_333:
	s_andn2_b64 vcc, exec, s[8:9]
	s_cbranch_vccnz .LBB0_383
	v_and_b32_e32 v11, 64, v183
	v_xor_b32_e32 v10, 16, v183
	v_add_u32_e32 v11, 64, v11
	v_cmp_lt_i32_e32 vcc, v10, v11
	v_lshlrev_b32_e32 v122, 6, v132
	s_nop 0
	v_cndmask_b32_e32 v10, v183, v10, vcc
	v_lshlrev_b32_e32 v133, 2, v10
	global_load_dwordx4 v[126:129], v122, s[68:69]
	global_load_dwordx4 v[10:13], v122, s[68:69] offset:32
	global_load_dwordx4 v[14:17], v122, s[68:69] offset:48
	s_nop 0
	global_load_dwordx4 v[122:125], v122, s[68:69] offset:16
	ds_bpermute_b32 v134, v133, v2
	v_cmp_lt_i32_e32 vcc, 0, v1
	s_waitcnt vmcnt(3)
	v_mul_f32_e32 v126, v2, v126
	s_waitcnt vmcnt(2) lgkmcnt(0)
	v_mul_f32_e32 v134, v10, v134
	v_sub_f32_e32 v10, v126, v134
	v_add_f32_e32 v126, v126, v134
	v_cmp_eq_u32_e64 s[0:1], 1, v1
	s_nop 1
	v_cndmask_b32_e64 v126, v2, v126, s[0:1]
	v_cndmask_b32_e32 v10, v10, v126, vcc
	ds_bpermute_b32 v134, v133, v3
	v_mul_f32_e32 v126, v3, v127
	v_cmp_lt_i32_e32 vcc, 0, v1
	s_waitcnt lgkmcnt(0)
	v_mul_f32_e32 v127, v11, v134
	v_sub_f32_e32 v11, v126, v127
	v_add_f32_e32 v126, v126, v127
	v_cmp_eq_u32_e64 s[0:1], 1, v1
	s_nop 1
	v_cndmask_b32_e64 v126, v3, v126, s[0:1]
	v_cndmask_b32_e32 v11, v11, v126, vcc
	ds_bpermute_b32 v127, v133, v4
	v_mul_f32_e32 v126, v4, v128
	v_cmp_lt_i32_e32 vcc, 0, v1
	s_waitcnt lgkmcnt(0)
	v_mul_f32_e32 v127, v12, v127
	v_sub_f32_e32 v12, v126, v127
	v_add_f32_e32 v126, v126, v127
	v_cmp_eq_u32_e64 s[0:1], 1, v1
	s_nop 1
	v_cndmask_b32_e64 v126, v4, v126, s[0:1]
	v_cndmask_b32_e32 v12, v12, v126, vcc
	ds_bpermute_b32 v127, v133, v5
	v_mul_f32_e32 v126, v5, v129
	v_cmp_lt_i32_e32 vcc, 0, v1
	s_waitcnt lgkmcnt(0)
	v_mul_f32_e32 v127, v13, v127
	v_sub_f32_e32 v13, v126, v127
	v_add_f32_e32 v126, v126, v127
	v_cmp_eq_u32_e64 s[0:1], 1, v1
	s_nop 1
	v_cndmask_b32_e64 v126, v5, v126, s[0:1]
	v_cndmask_b32_e32 v13, v13, v126, vcc
	ds_bpermute_b32 v126, v133, v6
	s_waitcnt vmcnt(0)
	v_mul_f32_e32 v122, v6, v122
	v_cmp_lt_i32_e32 vcc, 0, v1
	s_waitcnt lgkmcnt(0)
	v_mul_f32_e32 v126, v14, v126
	v_sub_f32_e32 v14, v122, v126
	v_add_f32_e32 v122, v122, v126
	v_cmp_eq_u32_e64 s[0:1], 1, v1
	s_nop 1
	v_cndmask_b32_e64 v122, v6, v122, s[0:1]
	v_cndmask_b32_e32 v14, v14, v122, vcc
	ds_bpermute_b32 v126, v133, v7
	v_mul_f32_e32 v122, v7, v123
	v_cmp_lt_i32_e32 vcc, 0, v1
	s_waitcnt lgkmcnt(0)
	v_mul_f32_e32 v123, v15, v126
	v_sub_f32_e32 v15, v122, v123
	v_add_f32_e32 v122, v122, v123
	v_cmp_eq_u32_e64 s[0:1], 1, v1
	s_nop 1
	v_cndmask_b32_e64 v122, v7, v122, s[0:1]
	v_cndmask_b32_e32 v15, v15, v122, vcc
	ds_bpermute_b32 v123, v133, v8
	v_mul_f32_e32 v122, v8, v124
	v_cmp_lt_i32_e32 vcc, 0, v1
	s_waitcnt lgkmcnt(0)
	v_mul_f32_e32 v123, v16, v123
	v_sub_f32_e32 v16, v122, v123
	v_add_f32_e32 v122, v122, v123
	v_cmp_eq_u32_e64 s[0:1], 1, v1
	s_nop 1
	v_cndmask_b32_e64 v122, v8, v122, s[0:1]
	v_cndmask_b32_e32 v16, v16, v122, vcc
	ds_bpermute_b32 v123, v133, v9
	v_mul_f32_e32 v122, v9, v125
	v_cmp_lt_i32_e32 vcc, 0, v1
	s_waitcnt lgkmcnt(0)
	v_mul_f32_e32 v123, v17, v123
	v_sub_f32_e32 v17, v122, v123
	v_add_f32_e32 v122, v122, v123
	v_cmp_eq_u32_e64 s[0:1], 1, v1
	s_nop 1
	v_cndmask_b32_e64 v122, v9, v122, s[0:1]
	v_cndmask_b32_e32 v17, v17, v122, vcc

; DI void rope8(float (&v)[8], const float* __restrict__ rope, int s, int fq) {
;     const f32x4 c0 = *(const f32x4*)(rope + s * 16), c1 = *(const f32x4*)(rope + s * 16 + 4), s0 = *(const f32x4*)(rope + s * 16 + 8), s1 = *(const f32x4*)(rope + s * 16 + 12);
;     const float cs[8] = {c0[0], c0[1], c0[2], c0[3], c1[0], c1[1], c1[2], c1[3]}, sn[8] = {s0[0], s0[1], s0[2], s0[3], s1[0], s1[1], s1[2], s1[3]};
; #pragma unroll
;     for (int e = 0; e < 8; ++e) {
;         const float other = __shfl_xor(v[e], 16);
;         const float a = v[e] * cs[e], bq = other * sn[e];
;         v[e] = (fq == 0) ? (a - bq) : ((fq == 1) ? (a + bq) : v[e]);
;     }
.LBB0_399:
	s_andn2_b64 vcc, exec, s[8:9]
	s_cbranch_vccnz .LBB0_449
	v_and_b32_e32 v11, 64, v183
	v_xor_b32_e32 v10, 16, v183
	v_add_u32_e32 v11, 64, v11
	v_cmp_lt_i32_e32 vcc, v10, v11
	v_lshlrev_b32_e32 v114, 6, v124
	s_nop 0
	v_cndmask_b32_e32 v10, v183, v10, vcc
	v_lshlrev_b32_e32 v125, 2, v10
	global_load_dwordx4 v[118:121], v114, s[68:69]
	global_load_dwordx4 v[10:13], v114, s[68:69] offset:32
	global_load_dwordx4 v[14:17], v114, s[68:69] offset:48
	s_nop 0
	global_load_dwordx4 v[114:117], v114, s[68:69] offset:16
	ds_bpermute_b32 v126, v125, v2
	v_cmp_lt_i32_e32 vcc, 0, v1
	s_waitcnt vmcnt(3)
	v_mul_f32_e32 v118, v2, v118
	s_waitcnt vmcnt(2) lgkmcnt(0)
	v_mul_f32_e32 v126, v10, v126
	v_sub_f32_e32 v10, v118, v126
	v_add_f32_e32 v118, v118, v126
	v_cmp_eq_u32_e64 s[0:1], 1, v1
	s_nop 1
	v_cndmask_b32_e64 v118, v2, v118, s[0:1]
	v_cndmask_b32_e32 v10, v10, v118, vcc
	ds_bpermute_b32 v126, v125, v3
	v_mul_f32_e32 v118, v3, v119
	v_cmp_lt_i32_e32 vcc, 0, v1
	s_waitcnt lgkmcnt(0)
	v_mul_f32_e32 v119, v11, v126
	v_sub_f32_e32 v11, v118, v119
	v_add_f32_e32 v118, v118, v119
	v_cmp_eq_u32_e64 s[0:1], 1, v1
	s_nop 1
	v_cndmask_b32_e64 v118, v3, v118, s[0:1]
	v_cndmask_b32_e32 v11, v11, v118, vcc
	ds_bpermute_b32 v119, v125, v4
	v_mul_f32_e32 v118, v4, v120
	v_cmp_lt_i32_e32 vcc, 0, v1
	s_waitcnt lgkmcnt(0)
	v_mul_f32_e32 v119, v12, v119
	v_sub_f32_e32 v12, v118, v119
	v_add_f32_e32 v118, v118, v119
	v_cmp_eq_u32_e64 s[0:1], 1, v1
	s_nop 1
	v_cndmask_b32_e64 v118, v4, v118, s[0:1]
	v_cndmask_b32_e32 v12, v12, v118, vcc
	ds_bpermute_b32 v119, v125, v5
	v_mul_f32_e32 v118, v5, v121
	v_cmp_lt_i32_e32 vcc, 0, v1
	s_waitcnt lgkmcnt(0)
	v_mul_f32_e32 v119, v13, v119
	v_sub_f32_e32 v13, v118, v119
	v_add_f32_e32 v118, v118, v119
	v_cmp_eq_u32_e64 s[0:1], 1, v1
	s_nop 1
	v_cndmask_b32_e64 v118, v5, v118, s[0:1]
	v_cndmask_b32_e32 v13, v13, v118, vcc
	ds_bpermute_b32 v118, v125, v6
	s_waitcnt vmcnt(0)
	v_mul_f32_e32 v114, v6, v114
	v_cmp_lt_i32_e32 vcc, 0, v1
	s_waitcnt lgkmcnt(0)
	v_mul_f32_e32 v118, v14, v118
	v_sub_f32_e32 v14, v114, v118
	v_add_f32_e32 v114, v114, v118
	v_cmp_eq_u32_e64 s[0:1], 1, v1
	s_nop 1
	v_cndmask_b32_e64 v114, v6, v114, s[0:1]
	v_cndmask_b32_e32 v14, v14, v114, vcc
	ds_bpermute_b32 v118, v125, v7
	v_mul_f32_e32 v114, v7, v115
	v_cmp_lt_i32_e32 vcc, 0, v1
	s_waitcnt lgkmcnt(0)
	v_mul_f32_e32 v115, v15, v118
	v_sub_f32_e32 v15, v114, v115
	v_add_f32_e32 v114, v114, v115
	v_cmp_eq_u32_e64 s[0:1], 1, v1
	s_nop 1
	v_cndmask_b32_e64 v114, v7, v114, s[0:1]
	v_cndmask_b32_e32 v15, v15, v114, vcc
	ds_bpermute_b32 v115, v125, v8
	v_mul_f32_e32 v114, v8, v116
	v_cmp_lt_i32_e32 vcc, 0, v1
	s_waitcnt lgkmcnt(0)
	v_mul_f32_e32 v115, v16, v115
	v_sub_f32_e32 v16, v114, v115
	v_add_f32_e32 v114, v114, v115
	v_cmp_eq_u32_e64 s[0:1], 1, v1
	s_nop 1
	v_cndmask_b32_e64 v114, v8, v114, s[0:1]
	v_cndmask_b32_e32 v16, v16, v114, vcc
	ds_bpermute_b32 v115, v125, v9
	v_mul_f32_e32 v114, v9, v117
	v_cmp_lt_i32_e32 vcc, 0, v1
	s_waitcnt lgkmcnt(0)
	v_mul_f32_e32 v115, v17, v115
	v_sub_f32_e32 v17, v114, v115
	v_add_f32_e32 v114, v114, v115
	v_cmp_eq_u32_e64 s[0:1], 1, v1
	s_nop 1
	v_cndmask_b32_e64 v114, v9, v114, s[0:1]
	v_cndmask_b32_e32 v17, v17, v114, vcc

; DI void rope8(float (&v)[8], const float* __restrict__ rope, int s, int fq) {
;     const f32x4 c0 = *(const f32x4*)(rope + s * 16), c1 = *(const f32x4*)(rope + s * 16 + 4), s0 = *(const f32x4*)(rope + s * 16 + 8), s1 = *(const f32x4*)(rope + s * 16 + 12);
;     const float cs[8] = {c0[0], c0[1], c0[2], c0[3], c1[0], c1[1], c1[2], c1[3]}, sn[8] = {s0[0], s0[1], s0[2], s0[3], s1[0], s1[1], s1[2], s1[3]};
; #pragma unroll
;     for (int e = 0; e < 8; ++e) {
;         const float other = __shfl_xor(v[e], 16);
;         const float a = v[e] * cs[e], bq = other * sn[e];
;         v[e] = (fq == 0) ? (a - bq) : ((fq == 1) ? (a + bq) : v[e]);
;     }
.LBB0_465:
	s_andn2_b64 vcc, exec, s[8:9]
	s_cbranch_vccnz .LBB0_515
	v_and_b32_e32 v11, 64, v183
	v_xor_b32_e32 v10, 16, v183
	v_add_u32_e32 v11, 64, v11
	v_cmp_lt_i32_e32 vcc, v10, v11
	v_lshlrev_b32_e32 v106, 6, v118
	s_nop 0
	v_cndmask_b32_e32 v10, v183, v10, vcc
	v_lshlrev_b32_e32 v119, 2, v10
	global_load_dwordx4 v[110:113], v106, s[68:69]
	global_load_dwordx4 v[10:13], v106, s[68:69] offset:32
	global_load_dwordx4 v[14:17], v106, s[68:69] offset:48
	s_nop 0
	global_load_dwordx4 v[106:109], v106, s[68:69] offset:16
	ds_bpermute_b32 v120, v119, v2
	v_cmp_lt_i32_e32 vcc, 0, v1
	s_waitcnt vmcnt(3)
	v_mul_f32_e32 v110, v2, v110
	s_waitcnt vmcnt(2) lgkmcnt(0)
	v_mul_f32_e32 v120, v10, v120
	v_sub_f32_e32 v10, v110, v120
	v_add_f32_e32 v110, v110, v120
	v_cmp_eq_u32_e64 s[0:1], 1, v1
	s_nop 1
	v_cndmask_b32_e64 v110, v2, v110, s[0:1]
	v_cndmask_b32_e32 v10, v10, v110, vcc
	ds_bpermute_b32 v120, v119, v3
	v_mul_f32_e32 v110, v3, v111
	v_cmp_lt_i32_e32 vcc, 0, v1
	s_waitcnt lgkmcnt(0)
	v_mul_f32_e32 v111, v11, v120
	v_sub_f32_e32 v11, v110, v111
	v_add_f32_e32 v110, v110, v111
	v_cmp_eq_u32_e64 s[0:1], 1, v1
	s_nop 1
	v_cndmask_b32_e64 v110, v3, v110, s[0:1]
	v_cndmask_b32_e32 v11, v11, v110, vcc
	ds_bpermute_b32 v111, v119, v4
	v_mul_f32_e32 v110, v4, v112
	v_cmp_lt_i32_e32 vcc, 0, v1
	s_waitcnt lgkmcnt(0)
	v_mul_f32_e32 v111, v12, v111
	v_sub_f32_e32 v12, v110, v111
	v_add_f32_e32 v110, v110, v111
	v_cmp_eq_u32_e64 s[0:1], 1, v1
	s_nop 1
	v_cndmask_b32_e64 v110, v4, v110, s[0:1]
	v_cndmask_b32_e32 v12, v12, v110, vcc
	ds_bpermute_b32 v111, v119, v5
	v_mul_f32_e32 v110, v5, v113
	v_cmp_lt_i32_e32 vcc, 0, v1
	s_waitcnt lgkmcnt(0)
	v_mul_f32_e32 v111, v13, v111
	v_sub_f32_e32 v13, v110, v111
	v_add_f32_e32 v110, v110, v111
	v_cmp_eq_u32_e64 s[0:1], 1, v1
	s_nop 1
	v_cndmask_b32_e64 v110, v5, v110, s[0:1]
	v_cndmask_b32_e32 v13, v13, v110, vcc
	ds_bpermute_b32 v110, v119, v6
	s_waitcnt vmcnt(0)
	v_mul_f32_e32 v106, v6, v106
	v_cmp_lt_i32_e32 vcc, 0, v1
	s_waitcnt lgkmcnt(0)
	v_mul_f32_e32 v110, v14, v110
	v_sub_f32_e32 v14, v106, v110
	v_add_f32_e32 v106, v106, v110
	v_cmp_eq_u32_e64 s[0:1], 1, v1
	s_nop 1
	v_cndmask_b32_e64 v106, v6, v106, s[0:1]
	v_cndmask_b32_e32 v14, v14, v106, vcc
	ds_bpermute_b32 v110, v119, v7
	v_mul_f32_e32 v106, v7, v107
	v_cmp_lt_i32_e32 vcc, 0, v1
	s_waitcnt lgkmcnt(0)
	v_mul_f32_e32 v107, v15, v110
	v_sub_f32_e32 v15, v106, v107
	v_add_f32_e32 v106, v106, v107
	v_cmp_eq_u32_e64 s[0:1], 1, v1
	s_nop 1
	v_cndmask_b32_e64 v106, v7, v106, s[0:1]
	v_cndmask_b32_e32 v15, v15, v106, vcc
	ds_bpermute_b32 v107, v119, v8
	v_mul_f32_e32 v106, v8, v108
	v_cmp_lt_i32_e32 vcc, 0, v1
	s_waitcnt lgkmcnt(0)
	v_mul_f32_e32 v107, v16, v107
	v_sub_f32_e32 v16, v106, v107
	v_add_f32_e32 v106, v106, v107
	v_cmp_eq_u32_e64 s[0:1], 1, v1
	s_nop 1
	v_cndmask_b32_e64 v106, v8, v106, s[0:1]
	v_cndmask_b32_e32 v16, v16, v106, vcc
	ds_bpermute_b32 v107, v119, v9
	v_mul_f32_e32 v106, v9, v109
	v_cmp_lt_i32_e32 vcc, 0, v1
	s_waitcnt lgkmcnt(0)
	v_mul_f32_e32 v107, v17, v107
	v_sub_f32_e32 v17, v106, v107
	v_add_f32_e32 v106, v106, v107
	v_cmp_eq_u32_e64 s[0:1], 1, v1
	s_nop 1
	v_cndmask_b32_e64 v106, v9, v106, s[0:1]
	v_cndmask_b32_e32 v17, v17, v106, vcc

; DI void rope8(float (&v)[8], const float* __restrict__ rope, int s, int fq) {
;     const f32x4 c0 = *(const f32x4*)(rope + s * 16), c1 = *(const f32x4*)(rope + s * 16 + 4), s0 = *(const f32x4*)(rope + s * 16 + 8), s1 = *(const f32x4*)(rope + s * 16 + 12);
;     const float cs[8] = {c0[0], c0[1], c0[2], c0[3], c1[0], c1[1], c1[2], c1[3]}, sn[8] = {s0[0], s0[1], s0[2], s0[3], s1[0], s1[1], s1[2], s1[3]};
; #pragma unroll
;     for (int e = 0; e < 8; ++e) {
;         const float other = __shfl_xor(v[e], 16);
;         const float a = v[e] * cs[e], bq = other * sn[e];
;         v[e] = (fq == 0) ? (a - bq) : ((fq == 1) ? (a + bq) : v[e]);
;     }
; }
;     DI void operator()(const pg8::f32x4 (&acc)[2][2][4][2], const pg8::Unit& u, int wr, int wc, int fr, int fq) const {
;     ...
;                         if (region < 2 && (wc & 1) == 0) rope8(v, rope, s, fq);
.LBB0_531:
	s_andn2_b64 vcc, exec, s[8:9]
	s_cbranch_vccnz .LBB0_581
	v_and_b32_e32 v11, 64, v183
	v_xor_b32_e32 v10, 16, v183
	v_add_u32_e32 v11, 64, v11
	v_cmp_lt_i32_e32 vcc, v10, v11
	v_lshlrev_b32_e32 v98, 6, v108
	s_nop 0
	v_cndmask_b32_e32 v10, v183, v10, vcc
	v_lshlrev_b32_e32 v109, 2, v10
	global_load_dwordx4 v[102:105], v98, s[68:69]
	global_load_dwordx4 v[10:13], v98, s[68:69] offset:32
	global_load_dwordx4 v[14:17], v98, s[68:69] offset:48
	s_nop 0
	global_load_dwordx4 v[98:101], v98, s[68:69] offset:16
	ds_bpermute_b32 v110, v109, v2
	v_cmp_lt_i32_e32 vcc, 0, v1
	s_waitcnt vmcnt(3)
	v_mul_f32_e32 v102, v2, v102
	s_waitcnt vmcnt(2) lgkmcnt(0)
	v_mul_f32_e32 v110, v10, v110
	v_sub_f32_e32 v10, v102, v110
	v_add_f32_e32 v102, v102, v110
	v_cmp_eq_u32_e64 s[0:1], 1, v1
	s_nop 1
	v_cndmask_b32_e64 v102, v2, v102, s[0:1]
	v_cndmask_b32_e32 v10, v10, v102, vcc
	ds_bpermute_b32 v110, v109, v3
	v_mul_f32_e32 v102, v3, v103
	v_cmp_lt_i32_e32 vcc, 0, v1
	s_waitcnt lgkmcnt(0)
	v_mul_f32_e32 v103, v11, v110
	v_sub_f32_e32 v11, v102, v103
	v_add_f32_e32 v102, v102, v103
	v_cmp_eq_u32_e64 s[0:1], 1, v1
	s_nop 1
	v_cndmask_b32_e64 v102, v3, v102, s[0:1]
	v_cndmask_b32_e32 v11, v11, v102, vcc
	ds_bpermute_b32 v103, v109, v4
	v_mul_f32_e32 v102, v4, v104
	v_cmp_lt_i32_e32 vcc, 0, v1
	s_waitcnt lgkmcnt(0)
	v_mul_f32_e32 v103, v12, v103
	v_sub_f32_e32 v12, v102, v103
	v_add_f32_e32 v102, v102, v103
	v_cmp_eq_u32_e64 s[0:1], 1, v1
	s_nop 1
	v_cndmask_b32_e64 v102, v4, v102, s[0:1]
	v_cndmask_b32_e32 v12, v12, v102, vcc
	ds_bpermute_b32 v103, v109, v5
	v_mul_f32_e32 v102, v5, v105
	v_cmp_lt_i32_e32 vcc, 0, v1
	s_waitcnt lgkmcnt(0)
	v_mul_f32_e32 v103, v13, v103
	v_sub_f32_e32 v13, v102, v103
	v_add_f32_e32 v102, v102, v103
	v_cmp_eq_u32_e64 s[0:1], 1, v1
	s_nop 1
	v_cndmask_b32_e64 v102, v5, v102, s[0:1]
	v_cndmask_b32_e32 v13, v13, v102, vcc
	ds_bpermute_b32 v102, v109, v6
	s_waitcnt vmcnt(0)
	v_mul_f32_e32 v98, v6, v98
	v_cmp_lt_i32_e32 vcc, 0, v1
	s_waitcnt lgkmcnt(0)
	v_mul_f32_e32 v102, v14, v102
	v_sub_f32_e32 v14, v98, v102
	v_add_f32_e32 v98, v98, v102
	v_cmp_eq_u32_e64 s[0:1], 1, v1
	s_nop 1
	v_cndmask_b32_e64 v98, v6, v98, s[0:1]
	v_cndmask_b32_e32 v14, v14, v98, vcc
	ds_bpermute_b32 v102, v109, v7
	v_mul_f32_e32 v98, v7, v99
	v_cmp_lt_i32_e32 vcc, 0, v1
	s_waitcnt lgkmcnt(0)
	v_mul_f32_e32 v99, v15, v102
	v_sub_f32_e32 v15, v98, v99
	v_add_f32_e32 v98, v98, v99
	v_cmp_eq_u32_e64 s[0:1], 1, v1
	s_nop 1
	v_cndmask_b32_e64 v98, v7, v98, s[0:1]
	v_cndmask_b32_e32 v15, v15, v98, vcc
	ds_bpermute_b32 v99, v109, v8
	v_mul_f32_e32 v98, v8, v100
	v_cmp_lt_i32_e32 vcc, 0, v1
	s_waitcnt lgkmcnt(0)
	v_mul_f32_e32 v99, v16, v99
	v_sub_f32_e32 v16, v98, v99
	v_add_f32_e32 v98, v98, v99
	v_cmp_eq_u32_e64 s[0:1], 1, v1
	s_nop 1
	v_cndmask_b32_e64 v98, v8, v98, s[0:1]
	v_cndmask_b32_e32 v16, v16, v98, vcc
	ds_bpermute_b32 v99, v109, v9
	v_mul_f32_e32 v98, v9, v101
	v_cmp_lt_i32_e32 vcc, 0, v1
	s_waitcnt lgkmcnt(0)
	v_mul_f32_e32 v99, v17, v99
	v_sub_f32_e32 v17, v98, v99
	v_add_f32_e32 v98, v98, v99
	v_cmp_eq_u32_e64 s[0:1], 1, v1
	s_nop 1
	v_cndmask_b32_e64 v98, v9, v98, s[0:1]
	v_cndmask_b32_e32 v17, v17, v98, vcc

; DI void rope8(float (&v)[8], const float* __restrict__ rope, int s, int fq) {
;     const f32x4 c0 = *(const f32x4*)(rope + s * 16), c1 = *(const f32x4*)(rope + s * 16 + 4), s0 = *(const f32x4*)(rope + s * 16 + 8), s1 = *(const f32x4*)(rope + s * 16 + 12);
;     const float cs[8] = {c0[0], c0[1], c0[2], c0[3], c1[0], c1[1], c1[2], c1[3]}, sn[8] = {s0[0], s0[1], s0[2], s0[3], s1[0], s1[1], s1[2], s1[3]};
; #pragma unroll
;     for (int e = 0; e < 8; ++e) {
;         const float other = __shfl_xor(v[e], 16);
;         const float a = v[e] * cs[e], bq = other * sn[e];
;         v[e] = (fq == 0) ? (a - bq) : ((fq == 1) ? (a + bq) : v[e]);
;     }
; }
;     DI void operator()(const pg8::f32x4 (&acc)[2][2][4][2], const pg8::Unit& u, int wr, int wc, int fr, int fq) const {
;     ...
;                         if (region < 2 && (wc & 1) == 0) rope8(v, rope, s, fq);
.LBB0_597:
	s_andn2_b64 vcc, exec, s[8:9]
	s_cbranch_vccnz .LBB0_647
	v_and_b32_e32 v11, 64, v183
	v_xor_b32_e32 v10, 16, v183
	v_add_u32_e32 v11, 64, v11
	v_cmp_lt_i32_e32 vcc, v10, v11
	v_lshlrev_b32_e32 v90, 6, v100
	s_nop 0
	v_cndmask_b32_e32 v10, v183, v10, vcc
	v_lshlrev_b32_e32 v101, 2, v10
	global_load_dwordx4 v[94:97], v90, s[68:69]
	global_load_dwordx4 v[10:13], v90, s[68:69] offset:32
	global_load_dwordx4 v[14:17], v90, s[68:69] offset:48
	s_nop 0
	global_load_dwordx4 v[90:93], v90, s[68:69] offset:16
	ds_bpermute_b32 v102, v101, v2
	v_cmp_lt_i32_e32 vcc, 0, v1
	s_waitcnt vmcnt(3)
	v_mul_f32_e32 v94, v2, v94
	s_waitcnt vmcnt(2) lgkmcnt(0)
	v_mul_f32_e32 v102, v10, v102
	v_sub_f32_e32 v10, v94, v102
	v_add_f32_e32 v94, v94, v102
	v_cmp_eq_u32_e64 s[0:1], 1, v1
	s_nop 1
	v_cndmask_b32_e64 v94, v2, v94, s[0:1]
	v_cndmask_b32_e32 v10, v10, v94, vcc
	ds_bpermute_b32 v102, v101, v3
	v_mul_f32_e32 v94, v3, v95
	v_cmp_lt_i32_e32 vcc, 0, v1
	s_waitcnt lgkmcnt(0)
	v_mul_f32_e32 v95, v11, v102
	v_sub_f32_e32 v11, v94, v95
	v_add_f32_e32 v94, v94, v95
	v_cmp_eq_u32_e64 s[0:1], 1, v1
	s_nop 1
	v_cndmask_b32_e64 v94, v3, v94, s[0:1]
	v_cndmask_b32_e32 v11, v11, v94, vcc
	ds_bpermute_b32 v95, v101, v4
	v_mul_f32_e32 v94, v4, v96
	v_cmp_lt_i32_e32 vcc, 0, v1
	s_waitcnt lgkmcnt(0)
	v_mul_f32_e32 v95, v12, v95
	v_sub_f32_e32 v12, v94, v95
	v_add_f32_e32 v94, v94, v95
	v_cmp_eq_u32_e64 s[0:1], 1, v1
	s_nop 1
	v_cndmask_b32_e64 v94, v4, v94, s[0:1]
	v_cndmask_b32_e32 v12, v12, v94, vcc
	ds_bpermute_b32 v95, v101, v5
	v_mul_f32_e32 v94, v5, v97
	v_cmp_lt_i32_e32 vcc, 0, v1
	s_waitcnt lgkmcnt(0)
	v_mul_f32_e32 v95, v13, v95
	v_sub_f32_e32 v13, v94, v95
	v_add_f32_e32 v94, v94, v95
	v_cmp_eq_u32_e64 s[0:1], 1, v1
	s_nop 1
	v_cndmask_b32_e64 v94, v5, v94, s[0:1]
	v_cndmask_b32_e32 v13, v13, v94, vcc
	ds_bpermute_b32 v94, v101, v6
	s_waitcnt vmcnt(0)
	v_mul_f32_e32 v90, v6, v90
	v_cmp_lt_i32_e32 vcc, 0, v1
	s_waitcnt lgkmcnt(0)
	v_mul_f32_e32 v94, v14, v94
	v_sub_f32_e32 v14, v90, v94
	v_add_f32_e32 v90, v90, v94
	v_cmp_eq_u32_e64 s[0:1], 1, v1
	s_nop 1
	v_cndmask_b32_e64 v90, v6, v90, s[0:1]
	v_cndmask_b32_e32 v14, v14, v90, vcc
	ds_bpermute_b32 v94, v101, v7
	v_mul_f32_e32 v90, v7, v91
	v_cmp_lt_i32_e32 vcc, 0, v1
	s_waitcnt lgkmcnt(0)
	v_mul_f32_e32 v91, v15, v94
	v_sub_f32_e32 v15, v90, v91
	v_add_f32_e32 v90, v90, v91
	v_cmp_eq_u32_e64 s[0:1], 1, v1
	s_nop 1
	v_cndmask_b32_e64 v90, v7, v90, s[0:1]
	v_cndmask_b32_e32 v15, v15, v90, vcc
	ds_bpermute_b32 v91, v101, v8
	v_mul_f32_e32 v90, v8, v92
	v_cmp_lt_i32_e32 vcc, 0, v1
	s_waitcnt lgkmcnt(0)
	v_mul_f32_e32 v91, v16, v91
	v_sub_f32_e32 v16, v90, v91
	v_add_f32_e32 v90, v90, v91
	v_cmp_eq_u32_e64 s[0:1], 1, v1
	s_nop 1
	v_cndmask_b32_e64 v90, v8, v90, s[0:1]
	v_cndmask_b32_e32 v16, v16, v90, vcc
	ds_bpermute_b32 v91, v101, v9
	v_mul_f32_e32 v90, v9, v93
	v_cmp_lt_i32_e32 vcc, 0, v1
	s_waitcnt lgkmcnt(0)
	v_mul_f32_e32 v91, v17, v91
	v_sub_f32_e32 v17, v90, v91
	v_add_f32_e32 v90, v90, v91
	v_cmp_eq_u32_e64 s[0:1], 1, v1
	s_nop 1
	v_cndmask_b32_e64 v90, v9, v90, s[0:1]
	v_cndmask_b32_e32 v17, v17, v90, vcc

; DI void rope8(float (&v)[8], const float* __restrict__ rope, int s, int fq) {
;     const f32x4 c0 = *(const f32x4*)(rope + s * 16), c1 = *(const f32x4*)(rope + s * 16 + 4), s0 = *(const f32x4*)(rope + s * 16 + 8), s1 = *(const f32x4*)(rope + s * 16 + 12);
;     const float cs[8] = {c0[0], c0[1], c0[2], c0[3], c1[0], c1[1], c1[2], c1[3]}, sn[8] = {s0[0], s0[1], s0[2], s0[3], s1[0], s1[1], s1[2], s1[3]};
; #pragma unroll
;     for (int e = 0; e < 8; ++e) {
;         const float other = __shfl_xor(v[e], 16);
;         const float a = v[e] * cs[e], bq = other * sn[e];
;         v[e] = (fq == 0) ? (a - bq) : ((fq == 1) ? (a + bq) : v[e]);
;     }
; }
;     DI void operator()(const pg8::f32x4 (&acc)[2][2][4][2], const pg8::Unit& u, int wr, int wc, int fr, int fq) const {
;     ...
;                         if (region < 2 && (wc & 1) == 0) rope8(v, rope, s, fq);
.LBB0_667:
	s_andn2_b64 vcc, exec, s[8:9]
	s_cbranch_vccnz .LBB0_717
	v_and_b32_e32 v11, 64, v183
	v_xor_b32_e32 v10, 16, v183
	v_add_u32_e32 v11, 64, v11
	v_cmp_lt_i32_e32 vcc, v10, v11
	v_lshlrev_b32_e32 v74, 6, v83
	s_nop 0
	v_cndmask_b32_e32 v10, v183, v10, vcc
	v_lshlrev_b32_e32 v86, 2, v10
	global_load_dwordx4 v[78:81], v74, s[68:69]
	global_load_dwordx4 v[10:13], v74, s[68:69] offset:32
	global_load_dwordx4 v[14:17], v74, s[68:69] offset:48
	s_nop 0
	global_load_dwordx4 v[74:77], v74, s[68:69] offset:16
	ds_bpermute_b32 v87, v86, v2
	v_cmp_lt_i32_e32 vcc, 0, v1
	s_waitcnt vmcnt(3)
	v_mul_f32_e32 v78, v2, v78
	s_waitcnt vmcnt(2) lgkmcnt(0)
	v_mul_f32_e32 v87, v10, v87
	v_sub_f32_e32 v10, v78, v87
	v_add_f32_e32 v78, v78, v87
	v_cmp_eq_u32_e64 s[0:1], 1, v1
	s_nop 1
	v_cndmask_b32_e64 v78, v2, v78, s[0:1]
	v_cndmask_b32_e32 v10, v10, v78, vcc
	ds_bpermute_b32 v87, v86, v3
	v_mul_f32_e32 v78, v3, v79
	v_cmp_lt_i32_e32 vcc, 0, v1
	s_waitcnt lgkmcnt(0)
	v_mul_f32_e32 v79, v11, v87
	v_sub_f32_e32 v11, v78, v79
	v_add_f32_e32 v78, v78, v79
	v_cmp_eq_u32_e64 s[0:1], 1, v1
	s_nop 1
	v_cndmask_b32_e64 v78, v3, v78, s[0:1]
	v_cndmask_b32_e32 v11, v11, v78, vcc
	ds_bpermute_b32 v79, v86, v4
	v_mul_f32_e32 v78, v4, v80
	v_cmp_lt_i32_e32 vcc, 0, v1
	s_waitcnt lgkmcnt(0)
	v_mul_f32_e32 v79, v12, v79
	v_sub_f32_e32 v12, v78, v79
	v_add_f32_e32 v78, v78, v79
	v_cmp_eq_u32_e64 s[0:1], 1, v1
	s_nop 1
	v_cndmask_b32_e64 v78, v4, v78, s[0:1]
	v_cndmask_b32_e32 v12, v12, v78, vcc
	ds_bpermute_b32 v79, v86, v5
	v_mul_f32_e32 v78, v5, v81
	v_cmp_lt_i32_e32 vcc, 0, v1
	s_waitcnt lgkmcnt(0)
	v_mul_f32_e32 v79, v13, v79
	v_sub_f32_e32 v13, v78, v79
	v_add_f32_e32 v78, v78, v79
	v_cmp_eq_u32_e64 s[0:1], 1, v1
	s_nop 1
	v_cndmask_b32_e64 v78, v5, v78, s[0:1]
	v_cndmask_b32_e32 v13, v13, v78, vcc
	ds_bpermute_b32 v78, v86, v6
	s_waitcnt vmcnt(0)
	v_mul_f32_e32 v74, v6, v74
	v_cmp_lt_i32_e32 vcc, 0, v1
	s_waitcnt lgkmcnt(0)
	v_mul_f32_e32 v78, v14, v78
	v_sub_f32_e32 v14, v74, v78
	v_add_f32_e32 v74, v74, v78
	v_cmp_eq_u32_e64 s[0:1], 1, v1
	s_nop 1
	v_cndmask_b32_e64 v74, v6, v74, s[0:1]
	v_cndmask_b32_e32 v14, v14, v74, vcc
	ds_bpermute_b32 v78, v86, v7
	v_mul_f32_e32 v74, v7, v75
	v_cmp_lt_i32_e32 vcc, 0, v1
	s_waitcnt lgkmcnt(0)
	v_mul_f32_e32 v75, v15, v78
	v_sub_f32_e32 v15, v74, v75
	v_add_f32_e32 v74, v74, v75
	v_cmp_eq_u32_e64 s[0:1], 1, v1
	s_nop 1
	v_cndmask_b32_e64 v74, v7, v74, s[0:1]
	v_cndmask_b32_e32 v15, v15, v74, vcc
	ds_bpermute_b32 v75, v86, v8
	v_mul_f32_e32 v74, v8, v76
	v_cmp_lt_i32_e32 vcc, 0, v1
	s_waitcnt lgkmcnt(0)
	v_mul_f32_e32 v75, v16, v75
	v_sub_f32_e32 v16, v74, v75
	v_add_f32_e32 v74, v74, v75
	v_cmp_eq_u32_e64 s[0:1], 1, v1
	s_nop 1
	v_cndmask_b32_e64 v74, v8, v74, s[0:1]
	v_cndmask_b32_e32 v16, v16, v74, vcc
	ds_bpermute_b32 v75, v86, v9
	v_mul_f32_e32 v74, v9, v77
	v_cmp_lt_i32_e32 vcc, 0, v1
	s_waitcnt lgkmcnt(0)
	v_mul_f32_e32 v75, v17, v75
	v_sub_f32_e32 v17, v74, v75
	v_add_f32_e32 v74, v74, v75
	v_cmp_eq_u32_e64 s[0:1], 1, v1
	s_nop 1
	v_cndmask_b32_e64 v74, v9, v74, s[0:1]
	v_cndmask_b32_e32 v17, v17, v74, vcc

; DI void rope8(float (&v)[8], const float* __restrict__ rope, int s, int fq) {
;     const f32x4 c0 = *(const f32x4*)(rope + s * 16), c1 = *(const f32x4*)(rope + s * 16 + 4), s0 = *(const f32x4*)(rope + s * 16 + 8), s1 = *(const f32x4*)(rope + s * 16 + 12);
;     const float cs[8] = {c0[0], c0[1], c0[2], c0[3], c1[0], c1[1], c1[2], c1[3]}, sn[8] = {s0[0], s0[1], s0[2], s0[3], s1[0], s1[1], s1[2], s1[3]};
; #pragma unroll
;     for (int e = 0; e < 8; ++e) {
;         const float other = __shfl_xor(v[e], 16);
;         const float a = v[e] * cs[e], bq = other * sn[e];
;         v[e] = (fq == 0) ? (a - bq) : ((fq == 1) ? (a + bq) : v[e]);
;     }
; }
;     DI void operator()(const pg8::f32x4 (&acc)[2][2][4][2], const pg8::Unit& u, int wr, int wc, int fr, int fq) const {
;     ...
;                         if (region < 2 && (wc & 1) == 0) rope8(v, rope, s, fq);
.LBB0_727:
	s_andn2_b64 vcc, exec, s[8:9]
	s_cbranch_vccnz .LBB0_777
	v_and_b32_e32 v11, 64, v183
	v_xor_b32_e32 v10, 16, v183
	v_add_u32_e32 v11, 64, v11
	v_cmp_lt_i32_e32 vcc, v10, v11
	v_lshlrev_b32_e32 v66, 6, v77
	s_nop 0
	v_cndmask_b32_e32 v10, v183, v10, vcc
	v_lshlrev_b32_e32 v79, 2, v10
	global_load_dwordx4 v[70:73], v66, s[68:69]
	global_load_dwordx4 v[10:13], v66, s[68:69] offset:32
	global_load_dwordx4 v[14:17], v66, s[68:69] offset:48
	s_nop 0
	global_load_dwordx4 v[66:69], v66, s[68:69] offset:16
	ds_bpermute_b32 v80, v79, v2
	v_cmp_lt_i32_e32 vcc, 0, v1
	s_waitcnt vmcnt(3)
	v_mul_f32_e32 v70, v2, v70
	s_waitcnt vmcnt(2) lgkmcnt(0)
	v_mul_f32_e32 v80, v10, v80
	v_sub_f32_e32 v10, v70, v80
	v_add_f32_e32 v70, v70, v80
	v_cmp_eq_u32_e64 s[0:1], 1, v1
	s_nop 1
	v_cndmask_b32_e64 v70, v2, v70, s[0:1]
	v_cndmask_b32_e32 v10, v10, v70, vcc
	ds_bpermute_b32 v80, v79, v3
	v_mul_f32_e32 v70, v3, v71
	v_cmp_lt_i32_e32 vcc, 0, v1
	s_waitcnt lgkmcnt(0)
	v_mul_f32_e32 v71, v11, v80
	v_sub_f32_e32 v11, v70, v71
	v_add_f32_e32 v70, v70, v71
	v_cmp_eq_u32_e64 s[0:1], 1, v1
	s_nop 1
	v_cndmask_b32_e64 v70, v3, v70, s[0:1]
	v_cndmask_b32_e32 v11, v11, v70, vcc
	ds_bpermute_b32 v71, v79, v4
	v_mul_f32_e32 v70, v4, v72
	v_cmp_lt_i32_e32 vcc, 0, v1
	s_waitcnt lgkmcnt(0)
	v_mul_f32_e32 v71, v12, v71
	v_sub_f32_e32 v12, v70, v71
	v_add_f32_e32 v70, v70, v71
	v_cmp_eq_u32_e64 s[0:1], 1, v1
	s_nop 1
	v_cndmask_b32_e64 v70, v4, v70, s[0:1]
	v_cndmask_b32_e32 v12, v12, v70, vcc
	ds_bpermute_b32 v71, v79, v5
	v_mul_f32_e32 v70, v5, v73
	v_cmp_lt_i32_e32 vcc, 0, v1
	s_waitcnt lgkmcnt(0)
	v_mul_f32_e32 v71, v13, v71
	v_sub_f32_e32 v13, v70, v71
	v_add_f32_e32 v70, v70, v71
	v_cmp_eq_u32_e64 s[0:1], 1, v1
	s_nop 1
	v_cndmask_b32_e64 v70, v5, v70, s[0:1]
	v_cndmask_b32_e32 v13, v13, v70, vcc
	ds_bpermute_b32 v70, v79, v6
	s_waitcnt vmcnt(0)
	v_mul_f32_e32 v66, v6, v66
	v_cmp_lt_i32_e32 vcc, 0, v1
	s_waitcnt lgkmcnt(0)
	v_mul_f32_e32 v70, v14, v70
	v_sub_f32_e32 v14, v66, v70
	v_add_f32_e32 v66, v66, v70
	v_cmp_eq_u32_e64 s[0:1], 1, v1
	s_nop 1
	v_cndmask_b32_e64 v66, v6, v66, s[0:1]
	v_cndmask_b32_e32 v14, v14, v66, vcc
	ds_bpermute_b32 v70, v79, v7
	v_mul_f32_e32 v66, v7, v67
	v_cmp_lt_i32_e32 vcc, 0, v1
	s_waitcnt lgkmcnt(0)
	v_mul_f32_e32 v67, v15, v70
	v_sub_f32_e32 v15, v66, v67
	v_add_f32_e32 v66, v66, v67
	v_cmp_eq_u32_e64 s[0:1], 1, v1
	s_nop 1
	v_cndmask_b32_e64 v66, v7, v66, s[0:1]
	v_cndmask_b32_e32 v15, v15, v66, vcc
	ds_bpermute_b32 v67, v79, v8
	v_mul_f32_e32 v66, v8, v68
	v_cmp_lt_i32_e32 vcc, 0, v1
	s_waitcnt lgkmcnt(0)
	v_mul_f32_e32 v67, v16, v67
	v_sub_f32_e32 v16, v66, v67
	v_add_f32_e32 v66, v66, v67
	v_cmp_eq_u32_e64 s[0:1], 1, v1
	s_nop 1
	v_cndmask_b32_e64 v66, v8, v66, s[0:1]
	v_cndmask_b32_e32 v16, v16, v66, vcc
	ds_bpermute_b32 v67, v79, v9
	v_mul_f32_e32 v66, v9, v69
	v_cmp_lt_i32_e32 vcc, 0, v1
	s_waitcnt lgkmcnt(0)
	v_mul_f32_e32 v67, v17, v67
	v_sub_f32_e32 v17, v66, v67
	v_add_f32_e32 v66, v66, v67
	v_cmp_eq_u32_e64 s[0:1], 1, v1
	s_nop 1
	v_cndmask_b32_e64 v66, v9, v66, s[0:1]
	v_cndmask_b32_e32 v17, v17, v66, vcc

; DI void rope8(float (&v)[8], const float* __restrict__ rope, int s, int fq) {
;     const f32x4 c0 = *(const f32x4*)(rope + s * 16), c1 = *(const f32x4*)(rope + s * 16 + 4), s0 = *(const f32x4*)(rope + s * 16 + 8), s1 = *(const f32x4*)(rope + s * 16 + 12);
;     const float cs[8] = {c0[0], c0[1], c0[2], c0[3], c1[0], c1[1], c1[2], c1[3]}, sn[8] = {s0[0], s0[1], s0[2], s0[3], s1[0], s1[1], s1[2], s1[3]};
; #pragma unroll
;     for (int e = 0; e < 8; ++e) {
;         const float other = __shfl_xor(v[e], 16);
;         const float a = v[e] * cs[e], bq = other * sn[e];
;         v[e] = (fq == 0) ? (a - bq) : ((fq == 1) ? (a + bq) : v[e]);
;     }
; }
;     DI void operator()(const pg8::f32x4 (&acc)[2][2][4][2], const pg8::Unit& u, int wr, int wc, int fr, int fq) const {
;     ...
;                         if (region < 2 && (wc & 1) == 0) rope8(v, rope, s, fq);
.LBB0_787:
	s_andn2_b64 vcc, exec, s[8:9]
	s_cbranch_vccnz .LBB0_837
	v_and_b32_e32 v11, 64, v183
	v_xor_b32_e32 v10, 16, v183
	v_add_u32_e32 v11, 64, v11
	v_cmp_lt_i32_e32 vcc, v10, v11
	v_lshlrev_b32_e32 v58, 6, v67
	s_nop 0
	v_cndmask_b32_e32 v10, v183, v10, vcc
	v_lshlrev_b32_e32 v68, 2, v10
	global_load_dwordx4 v[62:65], v58, s[68:69]
	global_load_dwordx4 v[10:13], v58, s[68:69] offset:32
	global_load_dwordx4 v[14:17], v58, s[68:69] offset:48
	s_nop 0
	global_load_dwordx4 v[58:61], v58, s[68:69] offset:16
	ds_bpermute_b32 v69, v68, v2
	v_cmp_lt_i32_e32 vcc, 0, v1
	s_waitcnt vmcnt(3)
	v_mul_f32_e32 v62, v2, v62
	s_waitcnt vmcnt(2) lgkmcnt(0)
	v_mul_f32_e32 v69, v10, v69
	v_sub_f32_e32 v10, v62, v69
	v_add_f32_e32 v62, v62, v69
	v_cmp_eq_u32_e64 s[0:1], 1, v1
	s_nop 1
	v_cndmask_b32_e64 v62, v2, v62, s[0:1]
	v_cndmask_b32_e32 v10, v10, v62, vcc
	ds_bpermute_b32 v69, v68, v3
	v_mul_f32_e32 v62, v3, v63
	v_cmp_lt_i32_e32 vcc, 0, v1
	s_waitcnt lgkmcnt(0)
	v_mul_f32_e32 v63, v11, v69
	v_sub_f32_e32 v11, v62, v63
	v_add_f32_e32 v62, v62, v63
	v_cmp_eq_u32_e64 s[0:1], 1, v1
	s_nop 1
	v_cndmask_b32_e64 v62, v3, v62, s[0:1]
	v_cndmask_b32_e32 v11, v11, v62, vcc
	ds_bpermute_b32 v63, v68, v4
	v_mul_f32_e32 v62, v4, v64
	v_cmp_lt_i32_e32 vcc, 0, v1
	s_waitcnt lgkmcnt(0)
	v_mul_f32_e32 v63, v12, v63
	v_sub_f32_e32 v12, v62, v63
	v_add_f32_e32 v62, v62, v63
	v_cmp_eq_u32_e64 s[0:1], 1, v1
	s_nop 1
	v_cndmask_b32_e64 v62, v4, v62, s[0:1]
	v_cndmask_b32_e32 v12, v12, v62, vcc
	ds_bpermute_b32 v63, v68, v5
	v_mul_f32_e32 v62, v5, v65
	v_cmp_lt_i32_e32 vcc, 0, v1
	s_waitcnt lgkmcnt(0)
	v_mul_f32_e32 v63, v13, v63
	v_sub_f32_e32 v13, v62, v63
	v_add_f32_e32 v62, v62, v63
	v_cmp_eq_u32_e64 s[0:1], 1, v1
	s_nop 1
	v_cndmask_b32_e64 v62, v5, v62, s[0:1]
	v_cndmask_b32_e32 v13, v13, v62, vcc
	ds_bpermute_b32 v62, v68, v6
	s_waitcnt vmcnt(0)
	v_mul_f32_e32 v58, v6, v58
	v_cmp_lt_i32_e32 vcc, 0, v1
	s_waitcnt lgkmcnt(0)
	v_mul_f32_e32 v62, v14, v62
	v_sub_f32_e32 v14, v58, v62
	v_add_f32_e32 v58, v58, v62
	v_cmp_eq_u32_e64 s[0:1], 1, v1
	s_nop 1
	v_cndmask_b32_e64 v58, v6, v58, s[0:1]
	v_cndmask_b32_e32 v14, v14, v58, vcc
	ds_bpermute_b32 v62, v68, v7
	v_mul_f32_e32 v58, v7, v59
	v_cmp_lt_i32_e32 vcc, 0, v1
	s_waitcnt lgkmcnt(0)
	v_mul_f32_e32 v59, v15, v62
	v_sub_f32_e32 v15, v58, v59
	v_add_f32_e32 v58, v58, v59
	v_cmp_eq_u32_e64 s[0:1], 1, v1
	s_nop 1
	v_cndmask_b32_e64 v58, v7, v58, s[0:1]
	v_cndmask_b32_e32 v15, v15, v58, vcc
	ds_bpermute_b32 v59, v68, v8
	v_mul_f32_e32 v58, v8, v60
	v_cmp_lt_i32_e32 vcc, 0, v1
	s_waitcnt lgkmcnt(0)
	v_mul_f32_e32 v59, v16, v59
	v_sub_f32_e32 v16, v58, v59
	v_add_f32_e32 v58, v58, v59
	v_cmp_eq_u32_e64 s[0:1], 1, v1
	s_nop 1
	v_cndmask_b32_e64 v58, v8, v58, s[0:1]
	v_cndmask_b32_e32 v16, v16, v58, vcc
	ds_bpermute_b32 v59, v68, v9
	v_mul_f32_e32 v58, v9, v61
	v_cmp_lt_i32_e32 vcc, 0, v1
	s_waitcnt lgkmcnt(0)
	v_mul_f32_e32 v59, v17, v59
	v_sub_f32_e32 v17, v58, v59
	v_add_f32_e32 v58, v58, v59
	v_cmp_eq_u32_e64 s[0:1], 1, v1
	s_nop 1
	v_cndmask_b32_e64 v58, v9, v58, s[0:1]
	v_cndmask_b32_e32 v17, v17, v58, vcc

; DI void rope8(float (&v)[8], const float* __restrict__ rope, int s, int fq) {
;     const f32x4 c0 = *(const f32x4*)(rope + s * 16), c1 = *(const f32x4*)(rope + s * 16 + 4), s0 = *(const f32x4*)(rope + s * 16 + 8), s1 = *(const f32x4*)(rope + s * 16 + 12);
;     const float cs[8] = {c0[0], c0[1], c0[2], c0[3], c1[0], c1[1], c1[2], c1[3]}, sn[8] = {s0[0], s0[1], s0[2], s0[3], s1[0], s1[1], s1[2], s1[3]};
; #pragma unroll
;     for (int e = 0; e < 8; ++e) {
;         const float other = __shfl_xor(v[e], 16);
;         const float a = v[e] * cs[e], bq = other * sn[e];
;         v[e] = (fq == 0) ? (a - bq) : ((fq == 1) ? (a + bq) : v[e]);
;     }
; }
;     DI void operator()(const pg8::f32x4 (&acc)[2][2][4][2], const pg8::Unit& u, int wr, int wc, int fr, int fq) const {
;     ...
;                         if (region < 2 && (wc & 1) == 0) rope8(v, rope, s, fq);
.LBB0_847:
	s_andn2_b64 vcc, exec, s[8:9]
	s_cbranch_vccnz .LBB0_897
	v_and_b32_e32 v11, 64, v183
	v_xor_b32_e32 v10, 16, v183
	v_add_u32_e32 v11, 64, v11
	v_cmp_lt_i32_e32 vcc, v10, v11
	v_lshlrev_b32_e32 v50, 6, v59
	s_nop 0
	v_cndmask_b32_e32 v10, v183, v10, vcc
	v_lshlrev_b32_e32 v60, 2, v10
	global_load_dwordx4 v[54:57], v50, s[68:69]
	global_load_dwordx4 v[10:13], v50, s[68:69] offset:32
	global_load_dwordx4 v[14:17], v50, s[68:69] offset:48
	s_nop 0
	global_load_dwordx4 v[50:53], v50, s[68:69] offset:16
	ds_bpermute_b32 v61, v60, v2
	v_cmp_lt_i32_e32 vcc, 0, v1
	s_waitcnt vmcnt(3)
	v_mul_f32_e32 v54, v2, v54
	s_waitcnt vmcnt(2) lgkmcnt(0)
	v_mul_f32_e32 v61, v10, v61
	v_sub_f32_e32 v10, v54, v61
	v_add_f32_e32 v54, v54, v61
	v_cmp_eq_u32_e64 s[0:1], 1, v1
	s_nop 1
	v_cndmask_b32_e64 v54, v2, v54, s[0:1]
	v_cndmask_b32_e32 v10, v10, v54, vcc
	ds_bpermute_b32 v61, v60, v3
	v_mul_f32_e32 v54, v3, v55
	v_cmp_lt_i32_e32 vcc, 0, v1
	s_waitcnt lgkmcnt(0)
	v_mul_f32_e32 v55, v11, v61
	v_sub_f32_e32 v11, v54, v55
	v_add_f32_e32 v54, v54, v55
	v_cmp_eq_u32_e64 s[0:1], 1, v1
	s_nop 1
	v_cndmask_b32_e64 v54, v3, v54, s[0:1]
	v_cndmask_b32_e32 v11, v11, v54, vcc
	ds_bpermute_b32 v55, v60, v4
	v_mul_f32_e32 v54, v4, v56
	v_cmp_lt_i32_e32 vcc, 0, v1
	s_waitcnt lgkmcnt(0)
	v_mul_f32_e32 v55, v12, v55
	v_sub_f32_e32 v12, v54, v55
	v_add_f32_e32 v54, v54, v55
	v_cmp_eq_u32_e64 s[0:1], 1, v1
	s_nop 1
	v_cndmask_b32_e64 v54, v4, v54, s[0:1]
	v_cndmask_b32_e32 v12, v12, v54, vcc
	ds_bpermute_b32 v55, v60, v5
	v_mul_f32_e32 v54, v5, v57
	v_cmp_lt_i32_e32 vcc, 0, v1
	s_waitcnt lgkmcnt(0)
	v_mul_f32_e32 v55, v13, v55
	v_sub_f32_e32 v13, v54, v55
	v_add_f32_e32 v54, v54, v55
	v_cmp_eq_u32_e64 s[0:1], 1, v1
	s_nop 1
	v_cndmask_b32_e64 v54, v5, v54, s[0:1]
	v_cndmask_b32_e32 v13, v13, v54, vcc
	ds_bpermute_b32 v54, v60, v6
	s_waitcnt vmcnt(0)
	v_mul_f32_e32 v50, v6, v50
	v_cmp_lt_i32_e32 vcc, 0, v1
	s_waitcnt lgkmcnt(0)
	v_mul_f32_e32 v54, v14, v54
	v_sub_f32_e32 v14, v50, v54
	v_add_f32_e32 v50, v50, v54
	v_cmp_eq_u32_e64 s[0:1], 1, v1
	s_nop 1
	v_cndmask_b32_e64 v50, v6, v50, s[0:1]
	v_cndmask_b32_e32 v14, v14, v50, vcc
	ds_bpermute_b32 v54, v60, v7
	v_mul_f32_e32 v50, v7, v51
	v_cmp_lt_i32_e32 vcc, 0, v1
	s_waitcnt lgkmcnt(0)
	v_mul_f32_e32 v51, v15, v54
	v_sub_f32_e32 v15, v50, v51
	v_add_f32_e32 v50, v50, v51
	v_cmp_eq_u32_e64 s[0:1], 1, v1
	s_nop 1
	v_cndmask_b32_e64 v50, v7, v50, s[0:1]
	v_cndmask_b32_e32 v15, v15, v50, vcc
	ds_bpermute_b32 v51, v60, v8
	v_mul_f32_e32 v50, v8, v52
	v_cmp_lt_i32_e32 vcc, 0, v1
	s_waitcnt lgkmcnt(0)
	v_mul_f32_e32 v51, v16, v51
	v_sub_f32_e32 v16, v50, v51
	v_add_f32_e32 v50, v50, v51
	v_cmp_eq_u32_e64 s[0:1], 1, v1
	s_nop 1
	v_cndmask_b32_e64 v50, v8, v50, s[0:1]
	v_cndmask_b32_e32 v16, v16, v50, vcc
	ds_bpermute_b32 v51, v60, v9
	v_mul_f32_e32 v50, v9, v53
	v_cmp_lt_i32_e32 vcc, 0, v1
	s_waitcnt lgkmcnt(0)
	v_mul_f32_e32 v51, v17, v51
	v_sub_f32_e32 v17, v50, v51
	v_add_f32_e32 v50, v50, v51
	v_cmp_eq_u32_e64 s[0:1], 1, v1
	s_nop 1
	v_cndmask_b32_e64 v50, v9, v50, s[0:1]
	v_cndmask_b32_e32 v17, v17, v50, vcc

; DI void rope8(float (&v)[8], const float* __restrict__ rope, int s, int fq) {
;     const f32x4 c0 = *(const f32x4*)(rope + s * 16), c1 = *(const f32x4*)(rope + s * 16 + 4), s0 = *(const f32x4*)(rope + s * 16 + 8), s1 = *(const f32x4*)(rope + s * 16 + 12);
;     const float cs[8] = {c0[0], c0[1], c0[2], c0[3], c1[0], c1[1], c1[2], c1[3]}, sn[8] = {s0[0], s0[1], s0[2], s0[3], s1[0], s1[1], s1[2], s1[3]};
; #pragma unroll
;     for (int e = 0; e < 8; ++e) {
;         const float other = __shfl_xor(v[e], 16);
;         const float a = v[e] * cs[e], bq = other * sn[e];
;         v[e] = (fq == 0) ? (a - bq) : ((fq == 1) ? (a + bq) : v[e]);
;     }
; }
;     DI void operator()(const pg8::f32x4 (&acc)[2][2][4][2], const pg8::Unit& u, int wr, int wc, int fr, int fq) const {
;     ...
;                         if (region < 2 && (wc & 1) == 0) rope8(v, rope, s, fq);
.LBB0_907:
	s_andn2_b64 vcc, exec, s[8:9]
	s_cbranch_vccnz .LBB0_957
	v_and_b32_e32 v11, 64, v183
	v_xor_b32_e32 v10, 16, v183
	v_add_u32_e32 v11, 64, v11
	v_cmp_lt_i32_e32 vcc, v10, v11
	v_lshlrev_b32_e32 v42, 6, v51
	s_nop 0
	v_cndmask_b32_e32 v10, v183, v10, vcc
	v_lshlrev_b32_e32 v52, 2, v10
	global_load_dwordx4 v[46:49], v42, s[68:69]
	global_load_dwordx4 v[10:13], v42, s[68:69] offset:32
	global_load_dwordx4 v[14:17], v42, s[68:69] offset:48
	s_nop 0
	global_load_dwordx4 v[42:45], v42, s[68:69] offset:16
	ds_bpermute_b32 v53, v52, v2
	v_cmp_lt_i32_e32 vcc, 0, v1
	s_waitcnt vmcnt(3)
	v_mul_f32_e32 v46, v2, v46
	s_waitcnt vmcnt(2) lgkmcnt(0)
	v_mul_f32_e32 v53, v10, v53
	v_sub_f32_e32 v10, v46, v53
	v_add_f32_e32 v46, v46, v53
	v_cmp_eq_u32_e64 s[0:1], 1, v1
	s_nop 1
	v_cndmask_b32_e64 v46, v2, v46, s[0:1]
	v_cndmask_b32_e32 v10, v10, v46, vcc
	ds_bpermute_b32 v53, v52, v3
	v_mul_f32_e32 v46, v3, v47
	v_cmp_lt_i32_e32 vcc, 0, v1
	s_waitcnt lgkmcnt(0)
	v_mul_f32_e32 v47, v11, v53
	v_sub_f32_e32 v11, v46, v47
	v_add_f32_e32 v46, v46, v47
	v_cmp_eq_u32_e64 s[0:1], 1, v1
	s_nop 1
	v_cndmask_b32_e64 v46, v3, v46, s[0:1]
	v_cndmask_b32_e32 v11, v11, v46, vcc
	ds_bpermute_b32 v47, v52, v4
	v_mul_f32_e32 v46, v4, v48
	v_cmp_lt_i32_e32 vcc, 0, v1
	s_waitcnt lgkmcnt(0)
	v_mul_f32_e32 v47, v12, v47
	v_sub_f32_e32 v12, v46, v47
	v_add_f32_e32 v46, v46, v47
	v_cmp_eq_u32_e64 s[0:1], 1, v1
	s_nop 1
	v_cndmask_b32_e64 v46, v4, v46, s[0:1]
	v_cndmask_b32_e32 v12, v12, v46, vcc
	ds_bpermute_b32 v47, v52, v5
	v_mul_f32_e32 v46, v5, v49
	v_cmp_lt_i32_e32 vcc, 0, v1
	s_waitcnt lgkmcnt(0)
	v_mul_f32_e32 v47, v13, v47
	v_sub_f32_e32 v13, v46, v47
	v_add_f32_e32 v46, v46, v47
	v_cmp_eq_u32_e64 s[0:1], 1, v1
	s_nop 1
	v_cndmask_b32_e64 v46, v5, v46, s[0:1]
	v_cndmask_b32_e32 v13, v13, v46, vcc
	ds_bpermute_b32 v46, v52, v6
	s_waitcnt vmcnt(0)
	v_mul_f32_e32 v42, v6, v42
	v_cmp_lt_i32_e32 vcc, 0, v1
	s_waitcnt lgkmcnt(0)
	v_mul_f32_e32 v46, v14, v46
	v_sub_f32_e32 v14, v42, v46
	v_add_f32_e32 v42, v42, v46
	v_cmp_eq_u32_e64 s[0:1], 1, v1
	s_nop 1
	v_cndmask_b32_e64 v42, v6, v42, s[0:1]
	v_cndmask_b32_e32 v14, v14, v42, vcc
	ds_bpermute_b32 v46, v52, v7
	v_mul_f32_e32 v42, v7, v43
	v_cmp_lt_i32_e32 vcc, 0, v1
	s_waitcnt lgkmcnt(0)
	v_mul_f32_e32 v43, v15, v46
	v_sub_f32_e32 v15, v42, v43
	v_add_f32_e32 v42, v42, v43
	v_cmp_eq_u32_e64 s[0:1], 1, v1
	s_nop 1
	v_cndmask_b32_e64 v42, v7, v42, s[0:1]
	v_cndmask_b32_e32 v15, v15, v42, vcc
	ds_bpermute_b32 v43, v52, v8
	v_mul_f32_e32 v42, v8, v44
	v_cmp_lt_i32_e32 vcc, 0, v1
	s_waitcnt lgkmcnt(0)
	v_mul_f32_e32 v43, v16, v43
	v_sub_f32_e32 v16, v42, v43
	v_add_f32_e32 v42, v42, v43
	v_cmp_eq_u32_e64 s[0:1], 1, v1
	s_nop 1
	v_cndmask_b32_e64 v42, v8, v42, s[0:1]
	v_cndmask_b32_e32 v16, v16, v42, vcc
	ds_bpermute_b32 v43, v52, v9
	v_mul_f32_e32 v42, v9, v45
	v_cmp_lt_i32_e32 vcc, 0, v1
	s_waitcnt lgkmcnt(0)
	v_mul_f32_e32 v43, v17, v43
	v_sub_f32_e32 v17, v42, v43
	v_add_f32_e32 v42, v42, v43
	v_cmp_eq_u32_e64 s[0:1], 1, v1
	s_nop 1
	v_cndmask_b32_e64 v42, v9, v42, s[0:1]
	v_cndmask_b32_e32 v17, v17, v42, vcc

; DI void rope8(float (&v)[8], const float* __restrict__ rope, int s, int fq) {
;     const f32x4 c0 = *(const f32x4*)(rope + s * 16), c1 = *(const f32x4*)(rope + s * 16 + 4), s0 = *(const f32x4*)(rope + s * 16 + 8), s1 = *(const f32x4*)(rope + s * 16 + 12);
;     const float cs[8] = {c0[0], c0[1], c0[2], c0[3], c1[0], c1[1], c1[2], c1[3]}, sn[8] = {s0[0], s0[1], s0[2], s0[3], s1[0], s1[1], s1[2], s1[3]};
; #pragma unroll
;     for (int e = 0; e < 8; ++e) {
;         const float other = __shfl_xor(v[e], 16);
;         const float a = v[e] * cs[e], bq = other * sn[e];
;         v[e] = (fq == 0) ? (a - bq) : ((fq == 1) ? (a + bq) : v[e]);
;     }
; }
;     DI void operator()(const pg8::f32x4 (&acc)[2][2][4][2], const pg8::Unit& u, int wr, int wc, int fr, int fq) const {
;     ...
;                         if (region < 2 && (wc & 1) == 0) rope8(v, rope, s, fq);
.LBB0_967:
	s_andn2_b64 vcc, exec, s[8:9]
	s_cbranch_vccnz .LBB0_1017
	v_and_b32_e32 v11, 64, v183
	v_xor_b32_e32 v10, 16, v183
	v_add_u32_e32 v11, 64, v11
	v_cmp_lt_i32_e32 vcc, v10, v11
	v_lshlrev_b32_e32 v34, 6, v45
	s_nop 0
	v_cndmask_b32_e32 v10, v183, v10, vcc
	v_lshlrev_b32_e32 v46, 2, v10
	global_load_dwordx4 v[38:41], v34, s[68:69]
	global_load_dwordx4 v[10:13], v34, s[68:69] offset:32
	global_load_dwordx4 v[14:17], v34, s[68:69] offset:48
	s_nop 0
	global_load_dwordx4 v[34:37], v34, s[68:69] offset:16
	ds_bpermute_b32 v47, v46, v2
	v_cmp_lt_i32_e32 vcc, 0, v1
	s_waitcnt vmcnt(3)
	v_mul_f32_e32 v38, v2, v38
	s_waitcnt vmcnt(2) lgkmcnt(0)
	v_mul_f32_e32 v47, v10, v47
	v_sub_f32_e32 v10, v38, v47
	v_add_f32_e32 v38, v38, v47
	v_cmp_eq_u32_e64 s[0:1], 1, v1
	s_nop 1
	v_cndmask_b32_e64 v38, v2, v38, s[0:1]
	v_cndmask_b32_e32 v10, v10, v38, vcc
	ds_bpermute_b32 v47, v46, v3
	v_mul_f32_e32 v38, v3, v39
	v_cmp_lt_i32_e32 vcc, 0, v1
	s_waitcnt lgkmcnt(0)
	v_mul_f32_e32 v39, v11, v47
	v_sub_f32_e32 v11, v38, v39
	v_add_f32_e32 v38, v38, v39
	v_cmp_eq_u32_e64 s[0:1], 1, v1
	s_nop 1
	v_cndmask_b32_e64 v38, v3, v38, s[0:1]
	v_cndmask_b32_e32 v11, v11, v38, vcc
	ds_bpermute_b32 v39, v46, v4
	v_mul_f32_e32 v38, v4, v40
	v_cmp_lt_i32_e32 vcc, 0, v1
	s_waitcnt lgkmcnt(0)
	v_mul_f32_e32 v39, v12, v39
	v_sub_f32_e32 v12, v38, v39
	v_add_f32_e32 v38, v38, v39
	v_cmp_eq_u32_e64 s[0:1], 1, v1
	s_nop 1
	v_cndmask_b32_e64 v38, v4, v38, s[0:1]
	v_cndmask_b32_e32 v12, v12, v38, vcc
	ds_bpermute_b32 v39, v46, v5
	v_mul_f32_e32 v38, v5, v41
	v_cmp_lt_i32_e32 vcc, 0, v1
	s_waitcnt lgkmcnt(0)
	v_mul_f32_e32 v39, v13, v39
	v_sub_f32_e32 v13, v38, v39
	v_add_f32_e32 v38, v38, v39
	v_cmp_eq_u32_e64 s[0:1], 1, v1
	s_nop 1
	v_cndmask_b32_e64 v38, v5, v38, s[0:1]
	v_cndmask_b32_e32 v13, v13, v38, vcc
	ds_bpermute_b32 v38, v46, v6
	s_waitcnt vmcnt(0)
	v_mul_f32_e32 v34, v6, v34
	v_cmp_lt_i32_e32 vcc, 0, v1
	s_waitcnt lgkmcnt(0)
	v_mul_f32_e32 v38, v14, v38
	v_sub_f32_e32 v14, v34, v38
	v_add_f32_e32 v34, v34, v38
	v_cmp_eq_u32_e64 s[0:1], 1, v1
	s_nop 1
	v_cndmask_b32_e64 v34, v6, v34, s[0:1]
	v_cndmask_b32_e32 v14, v14, v34, vcc
	ds_bpermute_b32 v38, v46, v7
	v_mul_f32_e32 v34, v7, v35
	v_cmp_lt_i32_e32 vcc, 0, v1
	s_waitcnt lgkmcnt(0)
	v_mul_f32_e32 v35, v15, v38
	v_sub_f32_e32 v15, v34, v35
	v_add_f32_e32 v34, v34, v35
	v_cmp_eq_u32_e64 s[0:1], 1, v1
	s_nop 1
	v_cndmask_b32_e64 v34, v7, v34, s[0:1]
	v_cndmask_b32_e32 v15, v15, v34, vcc
	ds_bpermute_b32 v35, v46, v8
	v_mul_f32_e32 v34, v8, v36
	v_cmp_lt_i32_e32 vcc, 0, v1
	s_waitcnt lgkmcnt(0)
	v_mul_f32_e32 v35, v16, v35
	v_sub_f32_e32 v16, v34, v35
	v_add_f32_e32 v34, v34, v35
	v_cmp_eq_u32_e64 s[0:1], 1, v1
	s_nop 1
	v_cndmask_b32_e64 v34, v8, v34, s[0:1]
	v_cndmask_b32_e32 v16, v16, v34, vcc
	ds_bpermute_b32 v35, v46, v9
	v_mul_f32_e32 v34, v9, v37
	v_cmp_lt_i32_e32 vcc, 0, v1
	s_waitcnt lgkmcnt(0)
	v_mul_f32_e32 v35, v17, v35
	v_sub_f32_e32 v17, v34, v35
	v_add_f32_e32 v34, v34, v35
	v_cmp_eq_u32_e64 s[0:1], 1, v1
	s_nop 1
	v_cndmask_b32_e64 v34, v9, v34, s[0:1]
	v_cndmask_b32_e32 v17, v17, v34, vcc

; DI void rope8(float (&v)[8], const float* __restrict__ rope, int s, int fq) {
;     const f32x4 c0 = *(const f32x4*)(rope + s * 16), c1 = *(const f32x4*)(rope + s * 16 + 4), s0 = *(const f32x4*)(rope + s * 16 + 8), s1 = *(const f32x4*)(rope + s * 16 + 12);
;     const float cs[8] = {c0[0], c0[1], c0[2], c0[3], c1[0], c1[1], c1[2], c1[3]}, sn[8] = {s0[0], s0[1], s0[2], s0[3], s1[0], s1[1], s1[2], s1[3]};
; #pragma unroll
;     for (int e = 0; e < 8; ++e) {
;         const float other = __shfl_xor(v[e], 16);
;         const float a = v[e] * cs[e], bq = other * sn[e];
;         v[e] = (fq == 0) ? (a - bq) : ((fq == 1) ? (a + bq) : v[e]);
;     }
; }
;     DI void operator()(const pg8::f32x4 (&acc)[2][2][4][2], const pg8::Unit& u, int wr, int wc, int fr, int fq) const {
;     ...
;                         if (region < 2 && (wc & 1) == 0) rope8(v, rope, s, fq);
.LBB0_1027:
	s_andn2_b64 vcc, exec, s[8:9]
	s_cbranch_vccnz .LBB0_1077
	v_and_b32_e32 v11, 64, v183
	v_xor_b32_e32 v10, 16, v183
	v_add_u32_e32 v11, 64, v11
	v_cmp_lt_i32_e32 vcc, v10, v11
	v_lshlrev_b32_e32 v26, 6, v35
	s_nop 0
	v_cndmask_b32_e32 v10, v183, v10, vcc
	v_lshlrev_b32_e32 v36, 2, v10
	global_load_dwordx4 v[30:33], v26, s[68:69]
	global_load_dwordx4 v[10:13], v26, s[68:69] offset:32
	global_load_dwordx4 v[14:17], v26, s[68:69] offset:48
	s_nop 0
	global_load_dwordx4 v[26:29], v26, s[68:69] offset:16
	ds_bpermute_b32 v37, v36, v2
	v_cmp_lt_i32_e32 vcc, 0, v1
	s_waitcnt vmcnt(3)
	v_mul_f32_e32 v30, v2, v30
	s_waitcnt vmcnt(2) lgkmcnt(0)
	v_mul_f32_e32 v37, v10, v37
	v_sub_f32_e32 v10, v30, v37
	v_add_f32_e32 v30, v30, v37
	v_cmp_eq_u32_e64 s[0:1], 1, v1
	s_nop 1
	v_cndmask_b32_e64 v30, v2, v30, s[0:1]
	v_cndmask_b32_e32 v10, v10, v30, vcc
	ds_bpermute_b32 v37, v36, v3
	v_mul_f32_e32 v30, v3, v31
	v_cmp_lt_i32_e32 vcc, 0, v1
	s_waitcnt lgkmcnt(0)
	v_mul_f32_e32 v31, v11, v37
	v_sub_f32_e32 v11, v30, v31
	v_add_f32_e32 v30, v30, v31
	v_cmp_eq_u32_e64 s[0:1], 1, v1
	s_nop 1
	v_cndmask_b32_e64 v30, v3, v30, s[0:1]
	v_cndmask_b32_e32 v11, v11, v30, vcc
	ds_bpermute_b32 v31, v36, v4
	v_mul_f32_e32 v30, v4, v32
	v_cmp_lt_i32_e32 vcc, 0, v1
	s_waitcnt lgkmcnt(0)
	v_mul_f32_e32 v31, v12, v31
	v_sub_f32_e32 v12, v30, v31
	v_add_f32_e32 v30, v30, v31
	v_cmp_eq_u32_e64 s[0:1], 1, v1
	s_nop 1
	v_cndmask_b32_e64 v30, v4, v30, s[0:1]
	v_cndmask_b32_e32 v12, v12, v30, vcc
	ds_bpermute_b32 v31, v36, v5
	v_mul_f32_e32 v30, v5, v33
	v_cmp_lt_i32_e32 vcc, 0, v1
	s_waitcnt lgkmcnt(0)
	v_mul_f32_e32 v31, v13, v31
	v_sub_f32_e32 v13, v30, v31
	v_add_f32_e32 v30, v30, v31
	v_cmp_eq_u32_e64 s[0:1], 1, v1
	s_nop 1
	v_cndmask_b32_e64 v30, v5, v30, s[0:1]
	v_cndmask_b32_e32 v13, v13, v30, vcc
	ds_bpermute_b32 v30, v36, v6
	s_waitcnt vmcnt(0)
	v_mul_f32_e32 v26, v6, v26
	v_cmp_lt_i32_e32 vcc, 0, v1
	s_waitcnt lgkmcnt(0)
	v_mul_f32_e32 v30, v14, v30
	v_sub_f32_e32 v14, v26, v30
	v_add_f32_e32 v26, v26, v30
	v_cmp_eq_u32_e64 s[0:1], 1, v1
	s_nop 1
	v_cndmask_b32_e64 v26, v6, v26, s[0:1]
	v_cndmask_b32_e32 v14, v14, v26, vcc
	ds_bpermute_b32 v30, v36, v7
	v_mul_f32_e32 v26, v7, v27
	v_cmp_lt_i32_e32 vcc, 0, v1
	s_waitcnt lgkmcnt(0)
	v_mul_f32_e32 v27, v15, v30
	v_sub_f32_e32 v15, v26, v27
	v_add_f32_e32 v26, v26, v27
	v_cmp_eq_u32_e64 s[0:1], 1, v1
	s_nop 1
	v_cndmask_b32_e64 v26, v7, v26, s[0:1]
	v_cndmask_b32_e32 v15, v15, v26, vcc
	ds_bpermute_b32 v27, v36, v8
	v_mul_f32_e32 v26, v8, v28
	v_cmp_lt_i32_e32 vcc, 0, v1
	s_waitcnt lgkmcnt(0)
	v_mul_f32_e32 v27, v16, v27
	v_sub_f32_e32 v16, v26, v27
	v_add_f32_e32 v26, v26, v27
	v_cmp_eq_u32_e64 s[0:1], 1, v1
	s_nop 1
	v_cndmask_b32_e64 v26, v8, v26, s[0:1]
	v_cndmask_b32_e32 v16, v16, v26, vcc
	ds_bpermute_b32 v27, v36, v9
	v_mul_f32_e32 v26, v9, v29
	v_cmp_lt_i32_e32 vcc, 0, v1
	s_waitcnt lgkmcnt(0)
	v_mul_f32_e32 v27, v17, v27
	v_sub_f32_e32 v17, v26, v27
	v_add_f32_e32 v26, v26, v27
	v_cmp_eq_u32_e64 s[0:1], 1, v1
	s_nop 1
	v_cndmask_b32_e64 v26, v9, v26, s[0:1]
	v_cndmask_b32_e32 v17, v17, v26, vcc

; DI void rope8(float (&v)[8], const float* __restrict__ rope, int s, int fq) {
;     const f32x4 c0 = *(const f32x4*)(rope + s * 16), c1 = *(const f32x4*)(rope + s * 16 + 4), s0 = *(const f32x4*)(rope + s * 16 + 8), s1 = *(const f32x4*)(rope + s * 16 + 12);
;     const float cs[8] = {c0[0], c0[1], c0[2], c0[3], c1[0], c1[1], c1[2], c1[3]}, sn[8] = {s0[0], s0[1], s0[2], s0[3], s1[0], s1[1], s1[2], s1[3]};
; #pragma unroll
;     for (int e = 0; e < 8; ++e) {
;         const float other = __shfl_xor(v[e], 16);
;         const float a = v[e] * cs[e], bq = other * sn[e];
;         v[e] = (fq == 0) ? (a - bq) : ((fq == 1) ? (a + bq) : v[e]);
;     }
; }
;     DI void operator()(const pg8::f32x4 (&acc)[2][2][4][2], const pg8::Unit& u, int wr, int wc, int fr, int fq) const {
;     ...
;                         if (region < 2 && (wc & 1) == 0) rope8(v, rope, s, fq);
.LBB0_1087:
	s_andn2_b64 vcc, exec, s[6:7]
	s_cbranch_vccnz .LBB0_1137
	v_and_b32_e32 v11, 64, v183
	v_xor_b32_e32 v10, 16, v183
	v_add_u32_e32 v11, 64, v11
	v_cmp_lt_i32_e32 vcc, v10, v11
	v_lshlrev_b32_e32 v18, 6, v27
	s_nop 0
	v_cndmask_b32_e32 v10, v183, v10, vcc
	v_lshlrev_b32_e32 v28, 2, v10
	global_load_dwordx4 v[22:25], v18, s[68:69]
	global_load_dwordx4 v[10:13], v18, s[68:69] offset:32
	global_load_dwordx4 v[14:17], v18, s[68:69] offset:48
	s_nop 0
	global_load_dwordx4 v[18:21], v18, s[68:69] offset:16
	ds_bpermute_b32 v29, v28, v2
	v_cmp_lt_i32_e32 vcc, 0, v1
	s_waitcnt vmcnt(3)
	v_mul_f32_e32 v22, v2, v22
	s_waitcnt vmcnt(2) lgkmcnt(0)
	v_mul_f32_e32 v29, v10, v29
	v_sub_f32_e32 v10, v22, v29
	v_add_f32_e32 v22, v22, v29
	v_cmp_eq_u32_e64 s[0:1], 1, v1
	s_nop 1
	v_cndmask_b32_e64 v22, v2, v22, s[0:1]
	v_cndmask_b32_e32 v10, v10, v22, vcc
	ds_bpermute_b32 v29, v28, v3
	v_mul_f32_e32 v22, v3, v23
	v_cmp_lt_i32_e32 vcc, 0, v1
	s_waitcnt lgkmcnt(0)
	v_mul_f32_e32 v23, v11, v29
	v_sub_f32_e32 v11, v22, v23
	v_add_f32_e32 v22, v22, v23
	v_cmp_eq_u32_e64 s[0:1], 1, v1
	s_nop 1
	v_cndmask_b32_e64 v22, v3, v22, s[0:1]
	v_cndmask_b32_e32 v11, v11, v22, vcc
	ds_bpermute_b32 v23, v28, v4
	v_mul_f32_e32 v22, v4, v24
	v_cmp_lt_i32_e32 vcc, 0, v1
	s_waitcnt lgkmcnt(0)
	v_mul_f32_e32 v23, v12, v23
	v_sub_f32_e32 v12, v22, v23
	v_add_f32_e32 v22, v22, v23
	v_cmp_eq_u32_e64 s[0:1], 1, v1
	s_nop 1
	v_cndmask_b32_e64 v22, v4, v22, s[0:1]
	v_cndmask_b32_e32 v12, v12, v22, vcc
	ds_bpermute_b32 v23, v28, v5
	v_mul_f32_e32 v22, v5, v25
	v_cmp_lt_i32_e32 vcc, 0, v1
	s_waitcnt lgkmcnt(0)
	v_mul_f32_e32 v23, v13, v23
	v_sub_f32_e32 v13, v22, v23
	v_add_f32_e32 v22, v22, v23
	v_cmp_eq_u32_e64 s[0:1], 1, v1
	s_nop 1
	v_cndmask_b32_e64 v22, v5, v22, s[0:1]
	v_cndmask_b32_e32 v13, v13, v22, vcc
	ds_bpermute_b32 v22, v28, v6
	s_waitcnt vmcnt(0)
	v_mul_f32_e32 v18, v6, v18
	v_cmp_lt_i32_e32 vcc, 0, v1
	s_waitcnt lgkmcnt(0)
	v_mul_f32_e32 v22, v14, v22
	v_sub_f32_e32 v14, v18, v22
	v_add_f32_e32 v18, v18, v22
	v_cmp_eq_u32_e64 s[0:1], 1, v1
	s_nop 1
	v_cndmask_b32_e64 v18, v6, v18, s[0:1]
	v_cndmask_b32_e32 v14, v14, v18, vcc
	ds_bpermute_b32 v22, v28, v7
	v_mul_f32_e32 v18, v7, v19
	v_cmp_lt_i32_e32 vcc, 0, v1
	s_waitcnt lgkmcnt(0)
	v_mul_f32_e32 v19, v15, v22
	v_sub_f32_e32 v15, v18, v19
	v_add_f32_e32 v18, v18, v19
	v_cmp_eq_u32_e64 s[0:1], 1, v1
	s_nop 1
	v_cndmask_b32_e64 v18, v7, v18, s[0:1]
	v_cndmask_b32_e32 v15, v15, v18, vcc
	ds_bpermute_b32 v19, v28, v8
	v_mul_f32_e32 v18, v8, v20
	v_cmp_lt_i32_e32 vcc, 0, v1
	s_waitcnt lgkmcnt(0)
	v_mul_f32_e32 v19, v16, v19
	v_sub_f32_e32 v16, v18, v19
	v_add_f32_e32 v18, v18, v19
	v_cmp_eq_u32_e64 s[0:1], 1, v1
	s_nop 1
	v_cndmask_b32_e64 v18, v8, v18, s[0:1]
	v_cndmask_b32_e32 v16, v16, v18, vcc
	ds_bpermute_b32 v19, v28, v9
	v_mul_f32_e32 v18, v9, v21
	v_cmp_lt_i32_e32 vcc, 0, v1
	s_waitcnt lgkmcnt(0)
	v_mul_f32_e32 v19, v17, v19
	v_sub_f32_e32 v17, v18, v19
	v_add_f32_e32 v18, v18, v19
	v_cmp_eq_u32_e64 s[0:1], 1, v1
	s_nop 1
	v_cndmask_b32_e64 v18, v9, v18, s[0:1]
	v_cndmask_b32_e32 v17, v17, v18, vcc

; DI void rope8(float (&v)[8], const float* __restrict__ rope, int s, int fq) {
;     const f32x4 c0 = *(const f32x4*)(rope + s * 16), c1 = *(const f32x4*)(rope + s * 16 + 4), s0 = *(const f32x4*)(rope + s * 16 + 8), s1 = *(const f32x4*)(rope + s * 16 + 12);
;     const float cs[8] = {c0[0], c0[1], c0[2], c0[3], c1[0], c1[1], c1[2], c1[3]}, sn[8] = {s0[0], s0[1], s0[2], s0[3], s1[0], s1[1], s1[2], s1[3]};
; #pragma unroll
;     for (int e = 0; e < 8; ++e) {
;         const float other = __shfl_xor(v[e], 16);
;         const float a = v[e] * cs[e], bq = other * sn[e];
;         v[e] = (fq == 0) ? (a - bq) : ((fq == 1) ? (a + bq) : v[e]);
;     }
; }
;     DI void operator()(const pg8::f32x4 (&acc)[2][2][4][2], const pg8::Unit& u, int wr, int wc, int fr, int fq) const {
;     ...
;                         if (region < 2 && (wc & 1) == 0) rope8(v, rope, s, fq);
.LBB0_1145:
	s_andn2_b64 vcc, exec, s[6:7]
	s_cbranch_vccnz .LBB0_1195
	v_and_b32_e32 v11, 64, v183
	v_xor_b32_e32 v10, 16, v183
	v_add_u32_e32 v11, 64, v11
	v_cmp_lt_i32_e32 vcc, v10, v11
	v_lshlrev_b32_e32 v82, 6, v92
	s_nop 0
	v_cndmask_b32_e32 v10, v183, v10, vcc
	v_lshlrev_b32_e32 v93, 2, v10
	global_load_dwordx4 v[86:89], v82, s[68:69]
	global_load_dwordx4 v[10:13], v82, s[68:69] offset:32
	global_load_dwordx4 v[14:17], v82, s[68:69] offset:48
	s_nop 0
	global_load_dwordx4 v[82:85], v82, s[68:69] offset:16
	ds_bpermute_b32 v94, v93, v2
	v_cmp_lt_i32_e32 vcc, 0, v1
	s_waitcnt vmcnt(3)
	v_mul_f32_e32 v86, v2, v86
	s_waitcnt vmcnt(2) lgkmcnt(0)
	v_mul_f32_e32 v94, v10, v94
	v_sub_f32_e32 v10, v86, v94
	v_add_f32_e32 v86, v86, v94
	v_cmp_eq_u32_e64 s[0:1], 1, v1
	s_nop 1
	v_cndmask_b32_e64 v86, v2, v86, s[0:1]
	v_cndmask_b32_e32 v10, v10, v86, vcc
	ds_bpermute_b32 v94, v93, v3
	v_mul_f32_e32 v86, v3, v87
	v_cmp_lt_i32_e32 vcc, 0, v1
	s_waitcnt lgkmcnt(0)
	v_mul_f32_e32 v87, v11, v94
	v_sub_f32_e32 v11, v86, v87
	v_add_f32_e32 v86, v86, v87
	v_cmp_eq_u32_e64 s[0:1], 1, v1
	s_nop 1
	v_cndmask_b32_e64 v86, v3, v86, s[0:1]
	v_cndmask_b32_e32 v11, v11, v86, vcc
	ds_bpermute_b32 v87, v93, v4
	v_mul_f32_e32 v86, v4, v88
	v_cmp_lt_i32_e32 vcc, 0, v1
	s_waitcnt lgkmcnt(0)
	v_mul_f32_e32 v87, v12, v87
	v_sub_f32_e32 v12, v86, v87
	v_add_f32_e32 v86, v86, v87
	v_cmp_eq_u32_e64 s[0:1], 1, v1
	s_nop 1
	v_cndmask_b32_e64 v86, v4, v86, s[0:1]
	v_cndmask_b32_e32 v12, v12, v86, vcc
	ds_bpermute_b32 v87, v93, v5
	v_mul_f32_e32 v86, v5, v89
	v_cmp_lt_i32_e32 vcc, 0, v1
	s_waitcnt lgkmcnt(0)
	v_mul_f32_e32 v87, v13, v87
	v_sub_f32_e32 v13, v86, v87
	v_add_f32_e32 v86, v86, v87
	v_cmp_eq_u32_e64 s[0:1], 1, v1
	s_nop 1
	v_cndmask_b32_e64 v86, v5, v86, s[0:1]
	v_cndmask_b32_e32 v13, v13, v86, vcc
	ds_bpermute_b32 v86, v93, v6
	s_waitcnt vmcnt(0)
	v_mul_f32_e32 v82, v6, v82
	v_cmp_lt_i32_e32 vcc, 0, v1
	s_waitcnt lgkmcnt(0)
	v_mul_f32_e32 v86, v14, v86
	v_sub_f32_e32 v14, v82, v86
	v_add_f32_e32 v82, v82, v86
	v_cmp_eq_u32_e64 s[0:1], 1, v1
	s_nop 1
	v_cndmask_b32_e64 v82, v6, v82, s[0:1]
	v_cndmask_b32_e32 v14, v14, v82, vcc
	ds_bpermute_b32 v86, v93, v7
	v_mul_f32_e32 v82, v7, v83
	v_cmp_lt_i32_e32 vcc, 0, v1
	s_waitcnt lgkmcnt(0)
	v_mul_f32_e32 v83, v15, v86
	v_sub_f32_e32 v15, v82, v83
	v_add_f32_e32 v82, v82, v83
	v_cmp_eq_u32_e64 s[0:1], 1, v1
	s_nop 1
	v_cndmask_b32_e64 v82, v7, v82, s[0:1]
	v_cndmask_b32_e32 v15, v15, v82, vcc
	ds_bpermute_b32 v83, v93, v8
	v_mul_f32_e32 v82, v8, v84
	v_cmp_lt_i32_e32 vcc, 0, v1
	s_waitcnt lgkmcnt(0)
	v_mul_f32_e32 v83, v16, v83
	v_sub_f32_e32 v16, v82, v83
	v_add_f32_e32 v82, v82, v83
	v_cmp_eq_u32_e64 s[0:1], 1, v1
	s_nop 1
	v_cndmask_b32_e64 v82, v8, v82, s[0:1]
	v_cndmask_b32_e32 v16, v16, v82, vcc
	ds_bpermute_b32 v83, v93, v9
	v_mul_f32_e32 v82, v9, v85
	v_cmp_lt_i32_e32 vcc, 0, v1
	s_waitcnt lgkmcnt(0)
	v_mul_f32_e32 v83, v17, v83
	v_sub_f32_e32 v17, v82, v83
	v_add_f32_e32 v82, v82, v83
	v_cmp_eq_u32_e64 s[0:1], 1, v1
	s_nop 1
	v_cndmask_b32_e64 v82, v9, v82, s[0:1]
	v_cndmask_b32_e32 v17, v17, v82, vcc

; DI void rope8(float (&v)[8], const float* __restrict__ rope, int s, int fq) {
;     const f32x4 c0 = *(const f32x4*)(rope + s * 16), c1 = *(const f32x4*)(rope + s * 16 + 4), s0 = *(const f32x4*)(rope + s * 16 + 8), s1 = *(const f32x4*)(rope + s * 16 + 12);
;     const float cs[8] = {c0[0], c0[1], c0[2], c0[3], c1[0], c1[1], c1[2], c1[3]}, sn[8] = {s0[0], s0[1], s0[2], s0[3], s1[0], s1[1], s1[2], s1[3]};
; #pragma unroll
;     for (int e = 0; e < 8; ++e) {
;         const float other = __shfl_xor(v[e], 16);
;         const float a = v[e] * cs[e], bq = other * sn[e];
;         v[e] = (fq == 0) ? (a - bq) : ((fq == 1) ? (a + bq) : v[e]);
;     }
; }
;     DI void operator()(const pg8::f32x4 (&acc)[2][2][4][2], const pg8::Unit& u, int wr, int wc, int fr, int fq) const {
;     ...
;                         if ((wc & 1) == 0) rope8(v, rope, s, fq);
.LBB0_1561:
	s_andn2_b64 vcc, exec, s[6:7]
	s_cbranch_vccnz .LBB0_1611
	v_and_b32_e32 v11, 64, v188
	v_xor_b32_e32 v10, 16, v188
	v_add_u32_e32 v11, 64, v11
	v_cmp_lt_i32_e32 vcc, v10, v11
	v_lshlrev_b32_e32 v11, 6, v158
	global_load_dwordx4 v[146:149], v11, s[68:69]
	global_load_dwordx4 v[142:145], v11, s[68:69] offset:32
	global_load_dwordx4 v[14:17], v11, s[68:69] offset:48
	global_load_dwordx4 v[138:141], v11, s[68:69] offset:16
	v_cndmask_b32_e32 v10, v188, v10, vcc
	v_lshlrev_b32_e32 v190, 2, v10
	ds_bpermute_b32 v12, v190, v2
	v_cmp_lt_i32_e32 vcc, 0, v177
	s_waitcnt vmcnt(3)
	v_mul_f32_e32 v11, v2, v146
	s_waitcnt vmcnt(2) lgkmcnt(0)
	v_mul_f32_e32 v12, v142, v12
	v_sub_f32_e32 v10, v11, v12
	v_add_f32_e32 v11, v11, v12
	v_cmp_eq_u32_e64 s[0:1], 1, v177
	s_nop 1
	v_cndmask_b32_e64 v11, v2, v11, s[0:1]
	v_cndmask_b32_e32 v10, v10, v11, vcc
	ds_bpermute_b32 v11, v190, v3
	v_mul_f32_e32 v12, v3, v147
	v_cmp_lt_i32_e32 vcc, 0, v177
	s_waitcnt lgkmcnt(0)
	v_mul_f32_e32 v13, v143, v11
	v_sub_f32_e32 v11, v12, v13
	v_add_f32_e32 v12, v12, v13
	v_cmp_eq_u32_e64 s[0:1], 1, v177
	s_nop 1
	v_cndmask_b32_e64 v12, v3, v12, s[0:1]
	v_cndmask_b32_e32 v11, v11, v12, vcc
	ds_bpermute_b32 v12, v190, v4
	v_mul_f32_e32 v13, v4, v148
	v_cmp_lt_i32_e32 vcc, 0, v177
	s_waitcnt lgkmcnt(0)
	v_mul_f32_e32 v142, v144, v12
	v_sub_f32_e32 v12, v13, v142
	v_add_f32_e32 v13, v13, v142
	v_cmp_eq_u32_e64 s[0:1], 1, v177
	s_nop 1
	v_cndmask_b32_e64 v13, v4, v13, s[0:1]
	v_cndmask_b32_e32 v12, v12, v13, vcc
	ds_bpermute_b32 v13, v190, v5
	v_mul_f32_e32 v142, v5, v149
	v_cmp_lt_i32_e32 vcc, 0, v177
	s_waitcnt lgkmcnt(0)
	v_mul_f32_e32 v143, v145, v13
	v_sub_f32_e32 v13, v142, v143
	v_add_f32_e32 v142, v142, v143
	v_cmp_eq_u32_e64 s[0:1], 1, v177
	s_nop 1
	v_cndmask_b32_e64 v142, v5, v142, s[0:1]
	v_cndmask_b32_e32 v13, v13, v142, vcc
	ds_bpermute_b32 v142, v190, v6
	s_waitcnt vmcnt(0)
	v_mul_f32_e32 v138, v6, v138
	v_cmp_lt_i32_e32 vcc, 0, v177
	s_waitcnt lgkmcnt(0)
	v_mul_f32_e32 v142, v14, v142
	v_sub_f32_e32 v14, v138, v142
	v_add_f32_e32 v138, v138, v142
	v_cmp_eq_u32_e64 s[0:1], 1, v177
	s_nop 1
	v_cndmask_b32_e64 v138, v6, v138, s[0:1]
	v_cndmask_b32_e32 v14, v14, v138, vcc
	ds_bpermute_b32 v142, v190, v7
	v_mul_f32_e32 v138, v7, v139
	v_cmp_lt_i32_e32 vcc, 0, v177
	s_waitcnt lgkmcnt(0)
	v_mul_f32_e32 v139, v15, v142
	v_sub_f32_e32 v15, v138, v139
	v_add_f32_e32 v138, v138, v139
	v_cmp_eq_u32_e64 s[0:1], 1, v177
	s_nop 1
	v_cndmask_b32_e64 v138, v7, v138, s[0:1]
	v_cndmask_b32_e32 v15, v15, v138, vcc
	ds_bpermute_b32 v139, v190, v8
	v_mul_f32_e32 v138, v8, v140
	v_cmp_lt_i32_e32 vcc, 0, v177
	s_waitcnt lgkmcnt(0)
	v_mul_f32_e32 v139, v16, v139
	v_sub_f32_e32 v16, v138, v139
	v_add_f32_e32 v138, v138, v139
	v_cmp_eq_u32_e64 s[0:1], 1, v177
	s_nop 1
	v_cndmask_b32_e64 v138, v8, v138, s[0:1]
	v_cndmask_b32_e32 v16, v16, v138, vcc
	ds_bpermute_b32 v139, v190, v9
	v_mul_f32_e32 v138, v9, v141
	v_cmp_lt_i32_e32 vcc, 0, v177
	s_waitcnt lgkmcnt(0)
	v_mul_f32_e32 v139, v17, v139
	v_sub_f32_e32 v17, v138, v139
	v_add_f32_e32 v138, v138, v139
	v_cmp_eq_u32_e64 s[0:1], 1, v177
	s_nop 1
	v_cndmask_b32_e64 v138, v9, v138, s[0:1]
	v_cndmask_b32_e32 v17, v17, v138, vcc

; DI void rope8(float (&v)[8], const float* __restrict__ rope, int s, int fq) {
;     const f32x4 c0 = *(const f32x4*)(rope + s * 16), c1 = *(const f32x4*)(rope + s * 16 + 4), s0 = *(const f32x4*)(rope + s * 16 + 8), s1 = *(const f32x4*)(rope + s * 16 + 12);
;     const float cs[8] = {c0[0], c0[1], c0[2], c0[3], c1[0], c1[1], c1[2], c1[3]}, sn[8] = {s0[0], s0[1], s0[2], s0[3], s1[0], s1[1], s1[2], s1[3]};
; #pragma unroll
;     for (int e = 0; e < 8; ++e) {
;         const float other = __shfl_xor(v[e], 16);
;         const float a = v[e] * cs[e], bq = other * sn[e];
;         v[e] = (fq == 0) ? (a - bq) : ((fq == 1) ? (a + bq) : v[e]);
;     }
; }
;     DI void operator()(const pg8::f32x4 (&acc)[2][2][4][2], const pg8::Unit& u, int wr, int wc, int fr, int fq) const {
;     ...
;                         if ((wc & 1) == 0) rope8(v, rope, s, fq);
.LBB0_1626:
	s_andn2_b64 vcc, exec, s[8:9]
	s_cbranch_vccnz .LBB0_1676
	v_and_b32_e32 v11, 64, v188
	v_xor_b32_e32 v10, 16, v188
	v_add_u32_e32 v11, 64, v11
	v_cmp_lt_i32_e32 vcc, v10, v11
	v_lshlrev_b32_e32 v11, 6, v144
	global_load_dwordx4 v[138:141], v11, s[68:69]
	global_load_dwordx4 v[134:137], v11, s[68:69] offset:32
	global_load_dwordx4 v[14:17], v11, s[68:69] offset:48
	global_load_dwordx4 v[130:133], v11, s[68:69] offset:16
	v_cndmask_b32_e32 v10, v188, v10, vcc
	v_lshlrev_b32_e32 v145, 2, v10
	ds_bpermute_b32 v12, v145, v2
	v_cmp_lt_i32_e32 vcc, 0, v177
	s_waitcnt vmcnt(3)
	v_mul_f32_e32 v11, v2, v138
	s_waitcnt vmcnt(2) lgkmcnt(0)
	v_mul_f32_e32 v12, v134, v12
	v_sub_f32_e32 v10, v11, v12
	v_add_f32_e32 v11, v11, v12
	v_cmp_eq_u32_e64 s[0:1], 1, v177
	s_nop 1
	v_cndmask_b32_e64 v11, v2, v11, s[0:1]
	v_cndmask_b32_e32 v10, v10, v11, vcc
	ds_bpermute_b32 v11, v145, v3
	v_mul_f32_e32 v12, v3, v139
	v_cmp_lt_i32_e32 vcc, 0, v177
	s_waitcnt lgkmcnt(0)
	v_mul_f32_e32 v13, v135, v11
	v_sub_f32_e32 v11, v12, v13
	v_add_f32_e32 v12, v12, v13
	v_cmp_eq_u32_e64 s[0:1], 1, v177
	s_nop 1
	v_cndmask_b32_e64 v12, v3, v12, s[0:1]
	v_cndmask_b32_e32 v11, v11, v12, vcc
	ds_bpermute_b32 v12, v145, v4
	v_mul_f32_e32 v13, v4, v140
	v_cmp_lt_i32_e32 vcc, 0, v177
	s_waitcnt lgkmcnt(0)
	v_mul_f32_e32 v134, v136, v12
	v_sub_f32_e32 v12, v13, v134
	v_add_f32_e32 v13, v13, v134
	v_cmp_eq_u32_e64 s[0:1], 1, v177
	s_nop 1
	v_cndmask_b32_e64 v13, v4, v13, s[0:1]
	v_cndmask_b32_e32 v12, v12, v13, vcc
	ds_bpermute_b32 v13, v145, v5
	v_mul_f32_e32 v134, v5, v141
	v_cmp_lt_i32_e32 vcc, 0, v177
	s_waitcnt lgkmcnt(0)
	v_mul_f32_e32 v135, v137, v13
	v_sub_f32_e32 v13, v134, v135
	v_add_f32_e32 v134, v134, v135
	v_cmp_eq_u32_e64 s[0:1], 1, v177
	s_nop 1
	v_cndmask_b32_e64 v134, v5, v134, s[0:1]
	v_cndmask_b32_e32 v13, v13, v134, vcc
	ds_bpermute_b32 v134, v145, v6
	s_waitcnt vmcnt(0)
	v_mul_f32_e32 v130, v6, v130
	v_cmp_lt_i32_e32 vcc, 0, v177
	s_waitcnt lgkmcnt(0)
	v_mul_f32_e32 v134, v14, v134
	v_sub_f32_e32 v14, v130, v134
	v_add_f32_e32 v130, v130, v134
	v_cmp_eq_u32_e64 s[0:1], 1, v177
	s_nop 1
	v_cndmask_b32_e64 v130, v6, v130, s[0:1]
	v_cndmask_b32_e32 v14, v14, v130, vcc
	ds_bpermute_b32 v134, v145, v7
	v_mul_f32_e32 v130, v7, v131
	v_cmp_lt_i32_e32 vcc, 0, v177
	s_waitcnt lgkmcnt(0)
	v_mul_f32_e32 v131, v15, v134
	v_sub_f32_e32 v15, v130, v131
	v_add_f32_e32 v130, v130, v131
	v_cmp_eq_u32_e64 s[0:1], 1, v177
	s_nop 1
	v_cndmask_b32_e64 v130, v7, v130, s[0:1]
	v_cndmask_b32_e32 v15, v15, v130, vcc
	ds_bpermute_b32 v131, v145, v8
	v_mul_f32_e32 v130, v8, v132
	v_cmp_lt_i32_e32 vcc, 0, v177
	s_waitcnt lgkmcnt(0)
	v_mul_f32_e32 v131, v16, v131
	v_sub_f32_e32 v16, v130, v131
	v_add_f32_e32 v130, v130, v131
	v_cmp_eq_u32_e64 s[0:1], 1, v177
	s_nop 1
	v_cndmask_b32_e64 v130, v8, v130, s[0:1]
	v_cndmask_b32_e32 v16, v16, v130, vcc
	ds_bpermute_b32 v131, v145, v9
	v_mul_f32_e32 v130, v9, v133
	v_cmp_lt_i32_e32 vcc, 0, v177
	s_waitcnt lgkmcnt(0)
	v_mul_f32_e32 v131, v17, v131
	v_sub_f32_e32 v17, v130, v131
	v_add_f32_e32 v130, v130, v131
	v_cmp_eq_u32_e64 s[0:1], 1, v177
	s_nop 1
	v_cndmask_b32_e64 v130, v9, v130, s[0:1]
	v_cndmask_b32_e32 v17, v17, v130, vcc

; DI void rope8(float (&v)[8], const float* __restrict__ rope, int s, int fq) {
;     const f32x4 c0 = *(const f32x4*)(rope + s * 16), c1 = *(const f32x4*)(rope + s * 16 + 4), s0 = *(const f32x4*)(rope + s * 16 + 8), s1 = *(const f32x4*)(rope + s * 16 + 12);
;     const float cs[8] = {c0[0], c0[1], c0[2], c0[3], c1[0], c1[1], c1[2], c1[3]}, sn[8] = {s0[0], s0[1], s0[2], s0[3], s1[0], s1[1], s1[2], s1[3]};
; #pragma unroll
;     for (int e = 0; e < 8; ++e) {
;         const float other = __shfl_xor(v[e], 16);
;         const float a = v[e] * cs[e], bq = other * sn[e];
;         v[e] = (fq == 0) ? (a - bq) : ((fq == 1) ? (a + bq) : v[e]);
;     }
; }
;     DI void operator()(const pg8::f32x4 (&acc)[2][2][4][2], const pg8::Unit& u, int wr, int wc, int fr, int fq) const {
;     ...
;                         if ((wc & 1) == 0) rope8(v, rope, s, fq);
.LBB0_1691:
	s_andn2_b64 vcc, exec, s[8:9]
	s_cbranch_vccnz .LBB0_1741
	v_and_b32_e32 v11, 64, v188
	v_xor_b32_e32 v10, 16, v188
	v_add_u32_e32 v11, 64, v11
	v_cmp_lt_i32_e32 vcc, v10, v11
	v_lshlrev_b32_e32 v11, 6, v136
	global_load_dwordx4 v[130:133], v11, s[68:69]
	global_load_dwordx4 v[126:129], v11, s[68:69] offset:32
	global_load_dwordx4 v[14:17], v11, s[68:69] offset:48
	global_load_dwordx4 v[122:125], v11, s[68:69] offset:16
	v_cndmask_b32_e32 v10, v188, v10, vcc
	v_lshlrev_b32_e32 v137, 2, v10
	ds_bpermute_b32 v12, v137, v2
	v_cmp_lt_i32_e32 vcc, 0, v177
	s_waitcnt vmcnt(3)
	v_mul_f32_e32 v11, v2, v130
	s_waitcnt vmcnt(2) lgkmcnt(0)
	v_mul_f32_e32 v12, v126, v12
	v_sub_f32_e32 v10, v11, v12
	v_add_f32_e32 v11, v11, v12
	v_cmp_eq_u32_e64 s[0:1], 1, v177
	s_nop 1
	v_cndmask_b32_e64 v11, v2, v11, s[0:1]
	v_cndmask_b32_e32 v10, v10, v11, vcc
	ds_bpermute_b32 v11, v137, v3
	v_mul_f32_e32 v12, v3, v131
	v_cmp_lt_i32_e32 vcc, 0, v177
	s_waitcnt lgkmcnt(0)
	v_mul_f32_e32 v13, v127, v11
	v_sub_f32_e32 v11, v12, v13
	v_add_f32_e32 v12, v12, v13
	v_cmp_eq_u32_e64 s[0:1], 1, v177
	s_nop 1
	v_cndmask_b32_e64 v12, v3, v12, s[0:1]
	v_cndmask_b32_e32 v11, v11, v12, vcc
	ds_bpermute_b32 v12, v137, v4
	v_mul_f32_e32 v13, v4, v132
	v_cmp_lt_i32_e32 vcc, 0, v177
	s_waitcnt lgkmcnt(0)
	v_mul_f32_e32 v126, v128, v12
	v_sub_f32_e32 v12, v13, v126
	v_add_f32_e32 v13, v13, v126
	v_cmp_eq_u32_e64 s[0:1], 1, v177
	s_nop 1
	v_cndmask_b32_e64 v13, v4, v13, s[0:1]
	v_cndmask_b32_e32 v12, v12, v13, vcc
	ds_bpermute_b32 v13, v137, v5
	v_mul_f32_e32 v126, v5, v133
	v_cmp_lt_i32_e32 vcc, 0, v177
	s_waitcnt lgkmcnt(0)
	v_mul_f32_e32 v127, v129, v13
	v_sub_f32_e32 v13, v126, v127
	v_add_f32_e32 v126, v126, v127
	v_cmp_eq_u32_e64 s[0:1], 1, v177
	s_nop 1
	v_cndmask_b32_e64 v126, v5, v126, s[0:1]
	v_cndmask_b32_e32 v13, v13, v126, vcc
	ds_bpermute_b32 v126, v137, v6
	s_waitcnt vmcnt(0)
	v_mul_f32_e32 v122, v6, v122
	v_cmp_lt_i32_e32 vcc, 0, v177
	s_waitcnt lgkmcnt(0)
	v_mul_f32_e32 v126, v14, v126
	v_sub_f32_e32 v14, v122, v126
	v_add_f32_e32 v122, v122, v126
	v_cmp_eq_u32_e64 s[0:1], 1, v177
	s_nop 1
	v_cndmask_b32_e64 v122, v6, v122, s[0:1]
	v_cndmask_b32_e32 v14, v14, v122, vcc
	ds_bpermute_b32 v126, v137, v7
	v_mul_f32_e32 v122, v7, v123
	v_cmp_lt_i32_e32 vcc, 0, v177
	s_waitcnt lgkmcnt(0)
	v_mul_f32_e32 v123, v15, v126
	v_sub_f32_e32 v15, v122, v123
	v_add_f32_e32 v122, v122, v123
	v_cmp_eq_u32_e64 s[0:1], 1, v177
	s_nop 1
	v_cndmask_b32_e64 v122, v7, v122, s[0:1]
	v_cndmask_b32_e32 v15, v15, v122, vcc
	ds_bpermute_b32 v123, v137, v8
	v_mul_f32_e32 v122, v8, v124
	v_cmp_lt_i32_e32 vcc, 0, v177
	s_waitcnt lgkmcnt(0)
	v_mul_f32_e32 v123, v16, v123
	v_sub_f32_e32 v16, v122, v123
	v_add_f32_e32 v122, v122, v123
	v_cmp_eq_u32_e64 s[0:1], 1, v177
	s_nop 1
	v_cndmask_b32_e64 v122, v8, v122, s[0:1]
	v_cndmask_b32_e32 v16, v16, v122, vcc
	ds_bpermute_b32 v123, v137, v9
	v_mul_f32_e32 v122, v9, v125
	v_cmp_lt_i32_e32 vcc, 0, v177
	s_waitcnt lgkmcnt(0)
	v_mul_f32_e32 v123, v17, v123
	v_sub_f32_e32 v17, v122, v123
	v_add_f32_e32 v122, v122, v123
	v_cmp_eq_u32_e64 s[0:1], 1, v177
	s_nop 1
	v_cndmask_b32_e64 v122, v9, v122, s[0:1]
	v_cndmask_b32_e32 v17, v17, v122, vcc

; DI void rope8(float (&v)[8], const float* __restrict__ rope, int s, int fq) {
;     const f32x4 c0 = *(const f32x4*)(rope + s * 16), c1 = *(const f32x4*)(rope + s * 16 + 4), s0 = *(const f32x4*)(rope + s * 16 + 8), s1 = *(const f32x4*)(rope + s * 16 + 12);
;     const float cs[8] = {c0[0], c0[1], c0[2], c0[3], c1[0], c1[1], c1[2], c1[3]}, sn[8] = {s0[0], s0[1], s0[2], s0[3], s1[0], s1[1], s1[2], s1[3]};
; #pragma unroll
;     for (int e = 0; e < 8; ++e) {
;         const float other = __shfl_xor(v[e], 16);
;         const float a = v[e] * cs[e], bq = other * sn[e];
;         v[e] = (fq == 0) ? (a - bq) : ((fq == 1) ? (a + bq) : v[e]);
;     }
; }
;     DI void operator()(const pg8::f32x4 (&acc)[2][2][4][2], const pg8::Unit& u, int wr, int wc, int fr, int fq) const {
;     ...
;                         if ((wc & 1) == 0) rope8(v, rope, s, fq);
.LBB0_1756:
	s_andn2_b64 vcc, exec, s[8:9]
	s_cbranch_vccnz .LBB0_1806
	v_and_b32_e32 v11, 64, v188
	v_xor_b32_e32 v10, 16, v188
	v_add_u32_e32 v11, 64, v11
	v_cmp_lt_i32_e32 vcc, v10, v11
	v_lshlrev_b32_e32 v11, 6, v128
	global_load_dwordx4 v[122:125], v11, s[68:69]
	global_load_dwordx4 v[118:121], v11, s[68:69] offset:32
	global_load_dwordx4 v[14:17], v11, s[68:69] offset:48
	global_load_dwordx4 v[114:117], v11, s[68:69] offset:16
	v_cndmask_b32_e32 v10, v188, v10, vcc
	v_lshlrev_b32_e32 v129, 2, v10
	ds_bpermute_b32 v12, v129, v2
	v_cmp_lt_i32_e32 vcc, 0, v177
	s_waitcnt vmcnt(3)
	v_mul_f32_e32 v11, v2, v122
	s_waitcnt vmcnt(2) lgkmcnt(0)
	v_mul_f32_e32 v12, v118, v12
	v_sub_f32_e32 v10, v11, v12
	v_add_f32_e32 v11, v11, v12
	v_cmp_eq_u32_e64 s[0:1], 1, v177
	s_nop 1
	v_cndmask_b32_e64 v11, v2, v11, s[0:1]
	v_cndmask_b32_e32 v10, v10, v11, vcc
	ds_bpermute_b32 v11, v129, v3
	v_mul_f32_e32 v12, v3, v123
	v_cmp_lt_i32_e32 vcc, 0, v177
	s_waitcnt lgkmcnt(0)
	v_mul_f32_e32 v13, v119, v11
	v_sub_f32_e32 v11, v12, v13
	v_add_f32_e32 v12, v12, v13
	v_cmp_eq_u32_e64 s[0:1], 1, v177
	s_nop 1
	v_cndmask_b32_e64 v12, v3, v12, s[0:1]
	v_cndmask_b32_e32 v11, v11, v12, vcc
	ds_bpermute_b32 v12, v129, v4
	v_mul_f32_e32 v13, v4, v124
	v_cmp_lt_i32_e32 vcc, 0, v177
	s_waitcnt lgkmcnt(0)
	v_mul_f32_e32 v118, v120, v12
	v_sub_f32_e32 v12, v13, v118
	v_add_f32_e32 v13, v13, v118
	v_cmp_eq_u32_e64 s[0:1], 1, v177
	s_nop 1
	v_cndmask_b32_e64 v13, v4, v13, s[0:1]
	v_cndmask_b32_e32 v12, v12, v13, vcc
	ds_bpermute_b32 v13, v129, v5
	v_mul_f32_e32 v118, v5, v125
	v_cmp_lt_i32_e32 vcc, 0, v177
	s_waitcnt lgkmcnt(0)
	v_mul_f32_e32 v119, v121, v13
	v_sub_f32_e32 v13, v118, v119
	v_add_f32_e32 v118, v118, v119
	v_cmp_eq_u32_e64 s[0:1], 1, v177
	s_nop 1
	v_cndmask_b32_e64 v118, v5, v118, s[0:1]
	v_cndmask_b32_e32 v13, v13, v118, vcc
	ds_bpermute_b32 v118, v129, v6
	s_waitcnt vmcnt(0)
	v_mul_f32_e32 v114, v6, v114
	v_cmp_lt_i32_e32 vcc, 0, v177
	s_waitcnt lgkmcnt(0)
	v_mul_f32_e32 v118, v14, v118
	v_sub_f32_e32 v14, v114, v118
	v_add_f32_e32 v114, v114, v118
	v_cmp_eq_u32_e64 s[0:1], 1, v177
	s_nop 1
	v_cndmask_b32_e64 v114, v6, v114, s[0:1]
	v_cndmask_b32_e32 v14, v14, v114, vcc
	ds_bpermute_b32 v118, v129, v7
	v_mul_f32_e32 v114, v7, v115
	v_cmp_lt_i32_e32 vcc, 0, v177
	s_waitcnt lgkmcnt(0)
	v_mul_f32_e32 v115, v15, v118
	v_sub_f32_e32 v15, v114, v115
	v_add_f32_e32 v114, v114, v115
	v_cmp_eq_u32_e64 s[0:1], 1, v177
	s_nop 1
	v_cndmask_b32_e64 v114, v7, v114, s[0:1]
	v_cndmask_b32_e32 v15, v15, v114, vcc
	ds_bpermute_b32 v115, v129, v8
	v_mul_f32_e32 v114, v8, v116
	v_cmp_lt_i32_e32 vcc, 0, v177
	s_waitcnt lgkmcnt(0)
	v_mul_f32_e32 v115, v16, v115
	v_sub_f32_e32 v16, v114, v115
	v_add_f32_e32 v114, v114, v115
	v_cmp_eq_u32_e64 s[0:1], 1, v177
	s_nop 1
	v_cndmask_b32_e64 v114, v8, v114, s[0:1]
	v_cndmask_b32_e32 v16, v16, v114, vcc
	ds_bpermute_b32 v115, v129, v9
	v_mul_f32_e32 v114, v9, v117
	v_cmp_lt_i32_e32 vcc, 0, v177
	s_waitcnt lgkmcnt(0)
	v_mul_f32_e32 v115, v17, v115
	v_sub_f32_e32 v17, v114, v115
	v_add_f32_e32 v114, v114, v115
	v_cmp_eq_u32_e64 s[0:1], 1, v177
	s_nop 1
	v_cndmask_b32_e64 v114, v9, v114, s[0:1]
	v_cndmask_b32_e32 v17, v17, v114, vcc

; DI void rope8(float (&v)[8], const float* __restrict__ rope, int s, int fq) {
;     const f32x4 c0 = *(const f32x4*)(rope + s * 16), c1 = *(const f32x4*)(rope + s * 16 + 4), s0 = *(const f32x4*)(rope + s * 16 + 8), s1 = *(const f32x4*)(rope + s * 16 + 12);
;     const float cs[8] = {c0[0], c0[1], c0[2], c0[3], c1[0], c1[1], c1[2], c1[3]}, sn[8] = {s0[0], s0[1], s0[2], s0[3], s1[0], s1[1], s1[2], s1[3]};
; #pragma unroll
;     for (int e = 0; e < 8; ++e) {
;         const float other = __shfl_xor(v[e], 16);
;         const float a = v[e] * cs[e], bq = other * sn[e];
;         v[e] = (fq == 0) ? (a - bq) : ((fq == 1) ? (a + bq) : v[e]);
;     }
; }
;     DI void operator()(const pg8::f32x4 (&acc)[2][2][4][2], const pg8::Unit& u, int wr, int wc, int fr, int fq) const {
;     ...
;                         if ((wc & 1) == 0) rope8(v, rope, s, fq);
.LBB0_1821:
	s_andn2_b64 vcc, exec, s[8:9]
	s_cbranch_vccnz .LBB0_1871
	v_and_b32_e32 v11, 64, v188
	v_xor_b32_e32 v10, 16, v188
	v_add_u32_e32 v11, 64, v11
	v_cmp_lt_i32_e32 vcc, v10, v11
	v_lshlrev_b32_e32 v11, 6, v122
	global_load_dwordx4 v[114:117], v11, s[68:69]
	global_load_dwordx4 v[110:113], v11, s[68:69] offset:32
	global_load_dwordx4 v[14:17], v11, s[68:69] offset:48
	global_load_dwordx4 v[106:109], v11, s[68:69] offset:16
	v_cndmask_b32_e32 v10, v188, v10, vcc
	v_lshlrev_b32_e32 v123, 2, v10
	ds_bpermute_b32 v12, v123, v2
	v_cmp_lt_i32_e32 vcc, 0, v177
	s_waitcnt vmcnt(3)
	v_mul_f32_e32 v11, v2, v114
	s_waitcnt vmcnt(2) lgkmcnt(0)
	v_mul_f32_e32 v12, v110, v12
	v_sub_f32_e32 v10, v11, v12
	v_add_f32_e32 v11, v11, v12
	v_cmp_eq_u32_e64 s[0:1], 1, v177
	s_nop 1
	v_cndmask_b32_e64 v11, v2, v11, s[0:1]
	v_cndmask_b32_e32 v10, v10, v11, vcc
	ds_bpermute_b32 v11, v123, v3
	v_mul_f32_e32 v12, v3, v115
	v_cmp_lt_i32_e32 vcc, 0, v177
	s_waitcnt lgkmcnt(0)
	v_mul_f32_e32 v13, v111, v11
	v_sub_f32_e32 v11, v12, v13
	v_add_f32_e32 v12, v12, v13
	v_cmp_eq_u32_e64 s[0:1], 1, v177
	s_nop 1
	v_cndmask_b32_e64 v12, v3, v12, s[0:1]
	v_cndmask_b32_e32 v11, v11, v12, vcc
	ds_bpermute_b32 v12, v123, v4
	v_mul_f32_e32 v13, v4, v116
	v_cmp_lt_i32_e32 vcc, 0, v177
	s_waitcnt lgkmcnt(0)
	v_mul_f32_e32 v110, v112, v12
	v_sub_f32_e32 v12, v13, v110
	v_add_f32_e32 v13, v13, v110
	v_cmp_eq_u32_e64 s[0:1], 1, v177
	s_nop 1
	v_cndmask_b32_e64 v13, v4, v13, s[0:1]
	v_cndmask_b32_e32 v12, v12, v13, vcc
	ds_bpermute_b32 v13, v123, v5
	v_mul_f32_e32 v110, v5, v117
	v_cmp_lt_i32_e32 vcc, 0, v177
	s_waitcnt lgkmcnt(0)
	v_mul_f32_e32 v111, v113, v13
	v_sub_f32_e32 v13, v110, v111
	v_add_f32_e32 v110, v110, v111
	v_cmp_eq_u32_e64 s[0:1], 1, v177
	s_nop 1
	v_cndmask_b32_e64 v110, v5, v110, s[0:1]
	v_cndmask_b32_e32 v13, v13, v110, vcc
	ds_bpermute_b32 v110, v123, v6
	s_waitcnt vmcnt(0)
	v_mul_f32_e32 v106, v6, v106
	v_cmp_lt_i32_e32 vcc, 0, v177
	s_waitcnt lgkmcnt(0)
	v_mul_f32_e32 v110, v14, v110
	v_sub_f32_e32 v14, v106, v110
	v_add_f32_e32 v106, v106, v110
	v_cmp_eq_u32_e64 s[0:1], 1, v177
	s_nop 1
	v_cndmask_b32_e64 v106, v6, v106, s[0:1]
	v_cndmask_b32_e32 v14, v14, v106, vcc
	ds_bpermute_b32 v110, v123, v7
	v_mul_f32_e32 v106, v7, v107
	v_cmp_lt_i32_e32 vcc, 0, v177
	s_waitcnt lgkmcnt(0)
	v_mul_f32_e32 v107, v15, v110
	v_sub_f32_e32 v15, v106, v107
	v_add_f32_e32 v106, v106, v107
	v_cmp_eq_u32_e64 s[0:1], 1, v177
	s_nop 1
	v_cndmask_b32_e64 v106, v7, v106, s[0:1]
	v_cndmask_b32_e32 v15, v15, v106, vcc
	ds_bpermute_b32 v107, v123, v8
	v_mul_f32_e32 v106, v8, v108
	v_cmp_lt_i32_e32 vcc, 0, v177
	s_waitcnt lgkmcnt(0)
	v_mul_f32_e32 v107, v16, v107
	v_sub_f32_e32 v16, v106, v107
	v_add_f32_e32 v106, v106, v107
	v_cmp_eq_u32_e64 s[0:1], 1, v177
	s_nop 1
	v_cndmask_b32_e64 v106, v8, v106, s[0:1]
	v_cndmask_b32_e32 v16, v16, v106, vcc
	ds_bpermute_b32 v107, v123, v9
	v_mul_f32_e32 v106, v9, v109
	v_cmp_lt_i32_e32 vcc, 0, v177
	s_waitcnt lgkmcnt(0)
	v_mul_f32_e32 v107, v17, v107
	v_sub_f32_e32 v17, v106, v107
	v_add_f32_e32 v106, v106, v107
	v_cmp_eq_u32_e64 s[0:1], 1, v177
	s_nop 1
	v_cndmask_b32_e64 v106, v9, v106, s[0:1]
	v_cndmask_b32_e32 v17, v17, v106, vcc

; DI void rope8(float (&v)[8], const float* __restrict__ rope, int s, int fq) {
;     const f32x4 c0 = *(const f32x4*)(rope + s * 16), c1 = *(const f32x4*)(rope + s * 16 + 4), s0 = *(const f32x4*)(rope + s * 16 + 8), s1 = *(const f32x4*)(rope + s * 16 + 12);
;     const float cs[8] = {c0[0], c0[1], c0[2], c0[3], c1[0], c1[1], c1[2], c1[3]}, sn[8] = {s0[0], s0[1], s0[2], s0[3], s1[0], s1[1], s1[2], s1[3]};
; #pragma unroll
;     for (int e = 0; e < 8; ++e) {
;         const float other = __shfl_xor(v[e], 16);
;         const float a = v[e] * cs[e], bq = other * sn[e];
;         v[e] = (fq == 0) ? (a - bq) : ((fq == 1) ? (a + bq) : v[e]);
;     }
; }
;     DI void operator()(const pg8::f32x4 (&acc)[2][2][4][2], const pg8::Unit& u, int wr, int wc, int fr, int fq) const {
;     ...
;                         if ((wc & 1) == 0) rope8(v, rope, s, fq);
.LBB0_1886:
	s_andn2_b64 vcc, exec, s[8:9]
	s_cbranch_vccnz .LBB0_1936
	v_and_b32_e32 v11, 64, v188
	v_xor_b32_e32 v10, 16, v188
	v_add_u32_e32 v11, 64, v11
	v_cmp_lt_i32_e32 vcc, v10, v11
	v_lshlrev_b32_e32 v11, 6, v112
	global_load_dwordx4 v[106:109], v11, s[68:69]
	global_load_dwordx4 v[102:105], v11, s[68:69] offset:32
	global_load_dwordx4 v[14:17], v11, s[68:69] offset:48
	global_load_dwordx4 v[98:101], v11, s[68:69] offset:16
	v_cndmask_b32_e32 v10, v188, v10, vcc
	v_lshlrev_b32_e32 v113, 2, v10
	ds_bpermute_b32 v12, v113, v2
	v_cmp_lt_i32_e32 vcc, 0, v177
	s_waitcnt vmcnt(3)
	v_mul_f32_e32 v11, v2, v106
	s_waitcnt vmcnt(2) lgkmcnt(0)
	v_mul_f32_e32 v12, v102, v12
	v_sub_f32_e32 v10, v11, v12
	v_add_f32_e32 v11, v11, v12
	v_cmp_eq_u32_e64 s[0:1], 1, v177
	s_nop 1
	v_cndmask_b32_e64 v11, v2, v11, s[0:1]
	v_cndmask_b32_e32 v10, v10, v11, vcc
	ds_bpermute_b32 v11, v113, v3
	v_mul_f32_e32 v12, v3, v107
	v_cmp_lt_i32_e32 vcc, 0, v177
	s_waitcnt lgkmcnt(0)
	v_mul_f32_e32 v13, v103, v11
	v_sub_f32_e32 v11, v12, v13
	v_add_f32_e32 v12, v12, v13
	v_cmp_eq_u32_e64 s[0:1], 1, v177
	s_nop 1
	v_cndmask_b32_e64 v12, v3, v12, s[0:1]
	v_cndmask_b32_e32 v11, v11, v12, vcc
	ds_bpermute_b32 v12, v113, v4
	v_mul_f32_e32 v13, v4, v108
	v_cmp_lt_i32_e32 vcc, 0, v177
	s_waitcnt lgkmcnt(0)
	v_mul_f32_e32 v102, v104, v12
	v_sub_f32_e32 v12, v13, v102
	v_add_f32_e32 v13, v13, v102
	v_cmp_eq_u32_e64 s[0:1], 1, v177
	s_nop 1
	v_cndmask_b32_e64 v13, v4, v13, s[0:1]
	v_cndmask_b32_e32 v12, v12, v13, vcc
	ds_bpermute_b32 v13, v113, v5
	v_mul_f32_e32 v102, v5, v109
	v_cmp_lt_i32_e32 vcc, 0, v177
	s_waitcnt lgkmcnt(0)
	v_mul_f32_e32 v103, v105, v13
	v_sub_f32_e32 v13, v102, v103
	v_add_f32_e32 v102, v102, v103
	v_cmp_eq_u32_e64 s[0:1], 1, v177
	s_nop 1
	v_cndmask_b32_e64 v102, v5, v102, s[0:1]
	v_cndmask_b32_e32 v13, v13, v102, vcc
	ds_bpermute_b32 v102, v113, v6
	s_waitcnt vmcnt(0)
	v_mul_f32_e32 v98, v6, v98
	v_cmp_lt_i32_e32 vcc, 0, v177
	s_waitcnt lgkmcnt(0)
	v_mul_f32_e32 v102, v14, v102
	v_sub_f32_e32 v14, v98, v102
	v_add_f32_e32 v98, v98, v102
	v_cmp_eq_u32_e64 s[0:1], 1, v177
	s_nop 1
	v_cndmask_b32_e64 v98, v6, v98, s[0:1]
	v_cndmask_b32_e32 v14, v14, v98, vcc
	ds_bpermute_b32 v102, v113, v7
	v_mul_f32_e32 v98, v7, v99
	v_cmp_lt_i32_e32 vcc, 0, v177
	s_waitcnt lgkmcnt(0)
	v_mul_f32_e32 v99, v15, v102
	v_sub_f32_e32 v15, v98, v99
	v_add_f32_e32 v98, v98, v99
	v_cmp_eq_u32_e64 s[0:1], 1, v177
	s_nop 1
	v_cndmask_b32_e64 v98, v7, v98, s[0:1]
	v_cndmask_b32_e32 v15, v15, v98, vcc
	ds_bpermute_b32 v99, v113, v8
	v_mul_f32_e32 v98, v8, v100
	v_cmp_lt_i32_e32 vcc, 0, v177
	s_waitcnt lgkmcnt(0)
	v_mul_f32_e32 v99, v16, v99
	v_sub_f32_e32 v16, v98, v99
	v_add_f32_e32 v98, v98, v99
	v_cmp_eq_u32_e64 s[0:1], 1, v177
	s_nop 1
	v_cndmask_b32_e64 v98, v8, v98, s[0:1]
	v_cndmask_b32_e32 v16, v16, v98, vcc
	ds_bpermute_b32 v99, v113, v9
	v_mul_f32_e32 v98, v9, v101
	v_cmp_lt_i32_e32 vcc, 0, v177
	s_waitcnt lgkmcnt(0)
	v_mul_f32_e32 v99, v17, v99
	v_sub_f32_e32 v17, v98, v99
	v_add_f32_e32 v98, v98, v99
	v_cmp_eq_u32_e64 s[0:1], 1, v177
	s_nop 1
	v_cndmask_b32_e64 v98, v9, v98, s[0:1]
	v_cndmask_b32_e32 v17, v17, v98, vcc

; DI void rope8(float (&v)[8], const float* __restrict__ rope, int s, int fq) {
;     const f32x4 c0 = *(const f32x4*)(rope + s * 16), c1 = *(const f32x4*)(rope + s * 16 + 4), s0 = *(const f32x4*)(rope + s * 16 + 8), s1 = *(const f32x4*)(rope + s * 16 + 12);
;     const float cs[8] = {c0[0], c0[1], c0[2], c0[3], c1[0], c1[1], c1[2], c1[3]}, sn[8] = {s0[0], s0[1], s0[2], s0[3], s1[0], s1[1], s1[2], s1[3]};
; #pragma unroll
;     for (int e = 0; e < 8; ++e) {
;         const float other = __shfl_xor(v[e], 16);
;         const float a = v[e] * cs[e], bq = other * sn[e];
;         v[e] = (fq == 0) ? (a - bq) : ((fq == 1) ? (a + bq) : v[e]);
;     }
; }
;     DI void operator()(const pg8::f32x4 (&acc)[2][2][4][2], const pg8::Unit& u, int wr, int wc, int fr, int fq) const {
;     ...
;                         if ((wc & 1) == 0) rope8(v, rope, s, fq);
.LBB0_1951:
	s_andn2_b64 vcc, exec, s[8:9]
	s_cbranch_vccnz .LBB0_2001
	v_and_b32_e32 v11, 64, v188
	v_xor_b32_e32 v10, 16, v188
	v_add_u32_e32 v11, 64, v11
	v_cmp_lt_i32_e32 vcc, v10, v11
	v_lshlrev_b32_e32 v11, 6, v104
	global_load_dwordx4 v[98:101], v11, s[68:69]
	global_load_dwordx4 v[94:97], v11, s[68:69] offset:32
	global_load_dwordx4 v[14:17], v11, s[68:69] offset:48
	global_load_dwordx4 v[90:93], v11, s[68:69] offset:16
	v_cndmask_b32_e32 v10, v188, v10, vcc
	v_lshlrev_b32_e32 v105, 2, v10
	ds_bpermute_b32 v12, v105, v2
	v_cmp_lt_i32_e32 vcc, 0, v177
	s_waitcnt vmcnt(3)
	v_mul_f32_e32 v11, v2, v98
	s_waitcnt vmcnt(2) lgkmcnt(0)
	v_mul_f32_e32 v12, v94, v12
	v_sub_f32_e32 v10, v11, v12
	v_add_f32_e32 v11, v11, v12
	v_cmp_eq_u32_e64 s[0:1], 1, v177
	s_nop 1
	v_cndmask_b32_e64 v11, v2, v11, s[0:1]
	v_cndmask_b32_e32 v10, v10, v11, vcc
	ds_bpermute_b32 v11, v105, v3
	v_mul_f32_e32 v12, v3, v99
	v_cmp_lt_i32_e32 vcc, 0, v177
	s_waitcnt lgkmcnt(0)
	v_mul_f32_e32 v13, v95, v11
	v_sub_f32_e32 v11, v12, v13
	v_add_f32_e32 v12, v12, v13
	v_cmp_eq_u32_e64 s[0:1], 1, v177
	s_nop 1
	v_cndmask_b32_e64 v12, v3, v12, s[0:1]
	v_cndmask_b32_e32 v11, v11, v12, vcc
	ds_bpermute_b32 v12, v105, v4
	v_mul_f32_e32 v13, v4, v100
	v_cmp_lt_i32_e32 vcc, 0, v177
	s_waitcnt lgkmcnt(0)
	v_mul_f32_e32 v94, v96, v12
	v_sub_f32_e32 v12, v13, v94
	v_add_f32_e32 v13, v13, v94
	v_cmp_eq_u32_e64 s[0:1], 1, v177
	s_nop 1
	v_cndmask_b32_e64 v13, v4, v13, s[0:1]
	v_cndmask_b32_e32 v12, v12, v13, vcc
	ds_bpermute_b32 v13, v105, v5
	v_mul_f32_e32 v94, v5, v101
	v_cmp_lt_i32_e32 vcc, 0, v177
	s_waitcnt lgkmcnt(0)
	v_mul_f32_e32 v95, v97, v13
	v_sub_f32_e32 v13, v94, v95
	v_add_f32_e32 v94, v94, v95
	v_cmp_eq_u32_e64 s[0:1], 1, v177
	s_nop 1
	v_cndmask_b32_e64 v94, v5, v94, s[0:1]
	v_cndmask_b32_e32 v13, v13, v94, vcc
	ds_bpermute_b32 v94, v105, v6
	s_waitcnt vmcnt(0)
	v_mul_f32_e32 v90, v6, v90
	v_cmp_lt_i32_e32 vcc, 0, v177
	s_waitcnt lgkmcnt(0)
	v_mul_f32_e32 v94, v14, v94
	v_sub_f32_e32 v14, v90, v94
	v_add_f32_e32 v90, v90, v94
	v_cmp_eq_u32_e64 s[0:1], 1, v177
	s_nop 1
	v_cndmask_b32_e64 v90, v6, v90, s[0:1]
	v_cndmask_b32_e32 v14, v14, v90, vcc
	ds_bpermute_b32 v94, v105, v7
	v_mul_f32_e32 v90, v7, v91
	v_cmp_lt_i32_e32 vcc, 0, v177
	s_waitcnt lgkmcnt(0)
	v_mul_f32_e32 v91, v15, v94
	v_sub_f32_e32 v15, v90, v91
	v_add_f32_e32 v90, v90, v91
	v_cmp_eq_u32_e64 s[0:1], 1, v177
	s_nop 1
	v_cndmask_b32_e64 v90, v7, v90, s[0:1]
	v_cndmask_b32_e32 v15, v15, v90, vcc
	ds_bpermute_b32 v91, v105, v8
	v_mul_f32_e32 v90, v8, v92
	v_cmp_lt_i32_e32 vcc, 0, v177
	s_waitcnt lgkmcnt(0)
	v_mul_f32_e32 v91, v16, v91
	v_sub_f32_e32 v16, v90, v91
	v_add_f32_e32 v90, v90, v91
	v_cmp_eq_u32_e64 s[0:1], 1, v177
	s_nop 1
	v_cndmask_b32_e64 v90, v8, v90, s[0:1]
	v_cndmask_b32_e32 v16, v16, v90, vcc
	ds_bpermute_b32 v91, v105, v9
	v_mul_f32_e32 v90, v9, v93
	v_cmp_lt_i32_e32 vcc, 0, v177
	s_waitcnt lgkmcnt(0)
	v_mul_f32_e32 v91, v17, v91
	v_sub_f32_e32 v17, v90, v91
	v_add_f32_e32 v90, v90, v91
	v_cmp_eq_u32_e64 s[0:1], 1, v177
	s_nop 1
	v_cndmask_b32_e64 v90, v9, v90, s[0:1]
	v_cndmask_b32_e32 v17, v17, v90, vcc

; DI void rope8(float (&v)[8], const float* __restrict__ rope, int s, int fq) {
;     const f32x4 c0 = *(const f32x4*)(rope + s * 16), c1 = *(const f32x4*)(rope + s * 16 + 4), s0 = *(const f32x4*)(rope + s * 16 + 8), s1 = *(const f32x4*)(rope + s * 16 + 12);
;     const float cs[8] = {c0[0], c0[1], c0[2], c0[3], c1[0], c1[1], c1[2], c1[3]}, sn[8] = {s0[0], s0[1], s0[2], s0[3], s1[0], s1[1], s1[2], s1[3]};
; #pragma unroll
;     for (int e = 0; e < 8; ++e) {
;         const float other = __shfl_xor(v[e], 16);
;         const float a = v[e] * cs[e], bq = other * sn[e];
;         v[e] = (fq == 0) ? (a - bq) : ((fq == 1) ? (a + bq) : v[e]);
;     }
; }
;     DI void operator()(const pg8::f32x4 (&acc)[2][2][4][2], const pg8::Unit& u, int wr, int wc, int fr, int fq) const {
;     ...
;                         if ((wc & 1) == 0) rope8(v, rope, s, fq);
.LBB0_2016:
	s_andn2_b64 vcc, exec, s[6:7]
	s_cbranch_vccnz .LBB0_2066
	v_and_b32_e32 v11, 64, v188
	v_xor_b32_e32 v10, 16, v188
	v_add_u32_e32 v11, 64, v11
	v_cmp_lt_i32_e32 vcc, v10, v11
	v_lshlrev_b32_e32 v11, 6, v96
	global_load_dwordx4 v[90:93], v11, s[68:69]
	global_load_dwordx4 v[86:89], v11, s[68:69] offset:32
	global_load_dwordx4 v[14:17], v11, s[68:69] offset:48
	global_load_dwordx4 v[82:85], v11, s[68:69] offset:16
	v_cndmask_b32_e32 v10, v188, v10, vcc
	v_lshlrev_b32_e32 v97, 2, v10
	ds_bpermute_b32 v12, v97, v2
	v_cmp_lt_i32_e32 vcc, 0, v177
	s_waitcnt vmcnt(3)
	v_mul_f32_e32 v11, v2, v90
	s_waitcnt vmcnt(2) lgkmcnt(0)
	v_mul_f32_e32 v12, v86, v12
	v_sub_f32_e32 v10, v11, v12
	v_add_f32_e32 v11, v11, v12
	v_cmp_eq_u32_e64 s[0:1], 1, v177
	s_nop 1
	v_cndmask_b32_e64 v11, v2, v11, s[0:1]
	v_cndmask_b32_e32 v10, v10, v11, vcc
	ds_bpermute_b32 v11, v97, v3
	v_mul_f32_e32 v12, v3, v91
	v_cmp_lt_i32_e32 vcc, 0, v177
	s_waitcnt lgkmcnt(0)
	v_mul_f32_e32 v13, v87, v11
	v_sub_f32_e32 v11, v12, v13
	v_add_f32_e32 v12, v12, v13
	v_cmp_eq_u32_e64 s[0:1], 1, v177
	s_nop 1
	v_cndmask_b32_e64 v12, v3, v12, s[0:1]
	v_cndmask_b32_e32 v11, v11, v12, vcc
	ds_bpermute_b32 v12, v97, v4
	v_mul_f32_e32 v13, v4, v92
	v_cmp_lt_i32_e32 vcc, 0, v177
	s_waitcnt lgkmcnt(0)
	v_mul_f32_e32 v86, v88, v12
	v_sub_f32_e32 v12, v13, v86
	v_add_f32_e32 v13, v13, v86
	v_cmp_eq_u32_e64 s[0:1], 1, v177
	s_nop 1
	v_cndmask_b32_e64 v13, v4, v13, s[0:1]
	v_cndmask_b32_e32 v12, v12, v13, vcc
	ds_bpermute_b32 v13, v97, v5
	v_mul_f32_e32 v86, v5, v93
	v_cmp_lt_i32_e32 vcc, 0, v177
	s_waitcnt lgkmcnt(0)
	v_mul_f32_e32 v87, v89, v13
	v_sub_f32_e32 v13, v86, v87
	v_add_f32_e32 v86, v86, v87
	v_cmp_eq_u32_e64 s[0:1], 1, v177
	s_nop 1
	v_cndmask_b32_e64 v86, v5, v86, s[0:1]
	v_cndmask_b32_e32 v13, v13, v86, vcc
	ds_bpermute_b32 v86, v97, v6
	s_waitcnt vmcnt(0)
	v_mul_f32_e32 v82, v6, v82
	v_cmp_lt_i32_e32 vcc, 0, v177
	s_waitcnt lgkmcnt(0)
	v_mul_f32_e32 v86, v14, v86
	v_sub_f32_e32 v14, v82, v86
	v_add_f32_e32 v82, v82, v86
	v_cmp_eq_u32_e64 s[0:1], 1, v177
	s_nop 1
	v_cndmask_b32_e64 v82, v6, v82, s[0:1]
	v_cndmask_b32_e32 v14, v14, v82, vcc
	ds_bpermute_b32 v86, v97, v7
	v_mul_f32_e32 v82, v7, v83
	v_cmp_lt_i32_e32 vcc, 0, v177
	s_waitcnt lgkmcnt(0)
	v_mul_f32_e32 v83, v15, v86
	v_sub_f32_e32 v15, v82, v83
	v_add_f32_e32 v82, v82, v83
	v_cmp_eq_u32_e64 s[0:1], 1, v177
	s_nop 1
	v_cndmask_b32_e64 v82, v7, v82, s[0:1]
	v_cndmask_b32_e32 v15, v15, v82, vcc
	ds_bpermute_b32 v83, v97, v8
	v_mul_f32_e32 v82, v8, v84
	v_cmp_lt_i32_e32 vcc, 0, v177
	s_waitcnt lgkmcnt(0)
	v_mul_f32_e32 v83, v16, v83
	v_sub_f32_e32 v16, v82, v83
	v_add_f32_e32 v82, v82, v83
	v_cmp_eq_u32_e64 s[0:1], 1, v177
	s_nop 1
	v_cndmask_b32_e64 v82, v8, v82, s[0:1]
	v_cndmask_b32_e32 v16, v16, v82, vcc
	ds_bpermute_b32 v83, v97, v9
	v_mul_f32_e32 v82, v9, v85
	v_cmp_lt_i32_e32 vcc, 0, v177
	s_waitcnt lgkmcnt(0)
	v_mul_f32_e32 v83, v17, v83
	v_sub_f32_e32 v17, v82, v83
	v_add_f32_e32 v82, v82, v83
	v_cmp_eq_u32_e64 s[0:1], 1, v177
	s_nop 1
	v_cndmask_b32_e64 v82, v9, v82, s[0:1]
	v_cndmask_b32_e32 v17, v17, v82, vcc

; DI void rope8(float (&v)[8], const float* __restrict__ rope, int s, int fq) {
;     const f32x4 c0 = *(const f32x4*)(rope + s * 16), c1 = *(const f32x4*)(rope + s * 16 + 4), s0 = *(const f32x4*)(rope + s * 16 + 8), s1 = *(const f32x4*)(rope + s * 16 + 12);
;     const float cs[8] = {c0[0], c0[1], c0[2], c0[3], c1[0], c1[1], c1[2], c1[3]}, sn[8] = {s0[0], s0[1], s0[2], s0[3], s1[0], s1[1], s1[2], s1[3]};
; #pragma unroll
;     for (int e = 0; e < 8; ++e) {
;         const float other = __shfl_xor(v[e], 16);
;         const float a = v[e] * cs[e], bq = other * sn[e];
;         v[e] = (fq == 0) ? (a - bq) : ((fq == 1) ? (a + bq) : v[e]);
;     }
; }
;     DI void operator()(const pg8::f32x4 (&acc)[2][2][4][2], const pg8::Unit& u, int wr, int wc, int fr, int fq) const {
;     ...
;                         if ((wc & 1) == 0) rope8(v, rope, s, fq);
.LBB0_2138:
	s_andn2_b64 vcc, exec, s[10:11]
	s_cbranch_vccnz .LBB0_2188
	v_and_b32_e32 v11, 64, v188
	v_xor_b32_e32 v10, 16, v188
	v_add_u32_e32 v11, 64, v11
	v_cmp_lt_i32_e32 vcc, v10, v11
	v_lshlrev_b32_e32 v66, 6, v77
	s_nop 0
	v_cndmask_b32_e32 v10, v188, v10, vcc
	v_lshlrev_b32_e32 v79, 2, v10
	global_load_dwordx4 v[70:73], v66, s[68:69]
	global_load_dwordx4 v[10:13], v66, s[68:69] offset:32
	global_load_dwordx4 v[14:17], v66, s[68:69] offset:48
	s_nop 0
	global_load_dwordx4 v[66:69], v66, s[68:69] offset:16
	ds_bpermute_b32 v80, v79, v2
	v_cmp_lt_i32_e32 vcc, 0, v177
	s_waitcnt vmcnt(3)
	v_mul_f32_e32 v70, v2, v70
	s_waitcnt vmcnt(2) lgkmcnt(0)
	v_mul_f32_e32 v80, v10, v80
	v_sub_f32_e32 v10, v70, v80
	v_add_f32_e32 v70, v70, v80
	v_cmp_eq_u32_e64 s[0:1], 1, v177
	s_nop 1
	v_cndmask_b32_e64 v70, v2, v70, s[0:1]
	v_cndmask_b32_e32 v10, v10, v70, vcc
	ds_bpermute_b32 v80, v79, v3
	v_mul_f32_e32 v70, v3, v71
	v_cmp_lt_i32_e32 vcc, 0, v177
	s_waitcnt lgkmcnt(0)
	v_mul_f32_e32 v71, v11, v80
	v_sub_f32_e32 v11, v70, v71
	v_add_f32_e32 v70, v70, v71
	v_cmp_eq_u32_e64 s[0:1], 1, v177
	s_nop 1
	v_cndmask_b32_e64 v70, v3, v70, s[0:1]
	v_cndmask_b32_e32 v11, v11, v70, vcc
	ds_bpermute_b32 v71, v79, v4
	v_mul_f32_e32 v70, v4, v72
	v_cmp_lt_i32_e32 vcc, 0, v177
	s_waitcnt lgkmcnt(0)
	v_mul_f32_e32 v71, v12, v71
	v_sub_f32_e32 v12, v70, v71
	v_add_f32_e32 v70, v70, v71
	v_cmp_eq_u32_e64 s[0:1], 1, v177
	s_nop 1
	v_cndmask_b32_e64 v70, v4, v70, s[0:1]
	v_cndmask_b32_e32 v12, v12, v70, vcc
	ds_bpermute_b32 v71, v79, v5
	v_mul_f32_e32 v70, v5, v73
	v_cmp_lt_i32_e32 vcc, 0, v177
	s_waitcnt lgkmcnt(0)
	v_mul_f32_e32 v71, v13, v71
	v_sub_f32_e32 v13, v70, v71
	v_add_f32_e32 v70, v70, v71
	v_cmp_eq_u32_e64 s[0:1], 1, v177
	s_nop 1
	v_cndmask_b32_e64 v70, v5, v70, s[0:1]
	v_cndmask_b32_e32 v13, v13, v70, vcc
	ds_bpermute_b32 v70, v79, v6
	s_waitcnt vmcnt(0)
	v_mul_f32_e32 v66, v6, v66
	v_cmp_lt_i32_e32 vcc, 0, v177
	s_waitcnt lgkmcnt(0)
	v_mul_f32_e32 v70, v14, v70
	v_sub_f32_e32 v14, v66, v70
	v_add_f32_e32 v66, v66, v70
	v_cmp_eq_u32_e64 s[0:1], 1, v177
	s_nop 1
	v_cndmask_b32_e64 v66, v6, v66, s[0:1]
	v_cndmask_b32_e32 v14, v14, v66, vcc
	ds_bpermute_b32 v70, v79, v7
	v_mul_f32_e32 v66, v7, v67
	v_cmp_lt_i32_e32 vcc, 0, v177
	s_waitcnt lgkmcnt(0)
	v_mul_f32_e32 v67, v15, v70
	v_sub_f32_e32 v15, v66, v67
	v_add_f32_e32 v66, v66, v67
	v_cmp_eq_u32_e64 s[0:1], 1, v177
	s_nop 1
	v_cndmask_b32_e64 v66, v7, v66, s[0:1]
	v_cndmask_b32_e32 v15, v15, v66, vcc
	ds_bpermute_b32 v67, v79, v8
	v_mul_f32_e32 v66, v8, v68
	v_cmp_lt_i32_e32 vcc, 0, v177
	s_waitcnt lgkmcnt(0)
	v_mul_f32_e32 v67, v16, v67
	v_sub_f32_e32 v16, v66, v67
	v_add_f32_e32 v66, v66, v67
	v_cmp_eq_u32_e64 s[0:1], 1, v177
	s_nop 1
	v_cndmask_b32_e64 v66, v8, v66, s[0:1]
	v_cndmask_b32_e32 v16, v16, v66, vcc
	ds_bpermute_b32 v67, v79, v9
	v_mul_f32_e32 v66, v9, v69
	v_cmp_lt_i32_e32 vcc, 0, v177
	s_waitcnt lgkmcnt(0)
	v_mul_f32_e32 v67, v17, v67
	v_sub_f32_e32 v17, v66, v67
	v_add_f32_e32 v66, v66, v67
	v_cmp_eq_u32_e64 s[0:1], 1, v177
	s_nop 1
	v_cndmask_b32_e64 v66, v9, v66, s[0:1]
	v_cndmask_b32_e32 v17, v17, v66, vcc

; DI void rope8(float (&v)[8], const float* __restrict__ rope, int s, int fq) {
;     const f32x4 c0 = *(const f32x4*)(rope + s * 16), c1 = *(const f32x4*)(rope + s * 16 + 4), s0 = *(const f32x4*)(rope + s * 16 + 8), s1 = *(const f32x4*)(rope + s * 16 + 12);
;     const float cs[8] = {c0[0], c0[1], c0[2], c0[3], c1[0], c1[1], c1[2], c1[3]}, sn[8] = {s0[0], s0[1], s0[2], s0[3], s1[0], s1[1], s1[2], s1[3]};
; #pragma unroll
;     for (int e = 0; e < 8; ++e) {
;         const float other = __shfl_xor(v[e], 16);
;         const float a = v[e] * cs[e], bq = other * sn[e];
;         v[e] = (fq == 0) ? (a - bq) : ((fq == 1) ? (a + bq) : v[e]);
;     }
; }
;     DI void operator()(const pg8::f32x4 (&acc)[2][2][4][2], const pg8::Unit& u, int wr, int wc, int fr, int fq) const {
;     ...
;                         if ((wc & 1) == 0) rope8(v, rope, s, fq);
.LBB0_2194:
	s_andn2_b64 vcc, exec, s[10:11]
	s_cbranch_vccnz .LBB0_2244
	v_and_b32_e32 v11, 64, v188
	v_xor_b32_e32 v10, 16, v188
	v_add_u32_e32 v11, 64, v11
	v_cmp_lt_i32_e32 vcc, v10, v11
	v_lshlrev_b32_e32 v58, 6, v67
	s_nop 0
	v_cndmask_b32_e32 v10, v188, v10, vcc
	v_lshlrev_b32_e32 v68, 2, v10
	global_load_dwordx4 v[62:65], v58, s[68:69]
	global_load_dwordx4 v[10:13], v58, s[68:69] offset:32
	global_load_dwordx4 v[14:17], v58, s[68:69] offset:48
	s_nop 0
	global_load_dwordx4 v[58:61], v58, s[68:69] offset:16
	ds_bpermute_b32 v69, v68, v2
	v_cmp_lt_i32_e32 vcc, 0, v177
	s_waitcnt vmcnt(3)
	v_mul_f32_e32 v62, v2, v62
	s_waitcnt vmcnt(2) lgkmcnt(0)
	v_mul_f32_e32 v69, v10, v69
	v_sub_f32_e32 v10, v62, v69
	v_add_f32_e32 v62, v62, v69
	v_cmp_eq_u32_e64 s[0:1], 1, v177
	s_nop 1
	v_cndmask_b32_e64 v62, v2, v62, s[0:1]
	v_cndmask_b32_e32 v10, v10, v62, vcc
	ds_bpermute_b32 v69, v68, v3
	v_mul_f32_e32 v62, v3, v63
	v_cmp_lt_i32_e32 vcc, 0, v177
	s_waitcnt lgkmcnt(0)
	v_mul_f32_e32 v63, v11, v69
	v_sub_f32_e32 v11, v62, v63
	v_add_f32_e32 v62, v62, v63
	v_cmp_eq_u32_e64 s[0:1], 1, v177
	s_nop 1
	v_cndmask_b32_e64 v62, v3, v62, s[0:1]
	v_cndmask_b32_e32 v11, v11, v62, vcc
	ds_bpermute_b32 v63, v68, v4
	v_mul_f32_e32 v62, v4, v64
	v_cmp_lt_i32_e32 vcc, 0, v177
	s_waitcnt lgkmcnt(0)
	v_mul_f32_e32 v63, v12, v63
	v_sub_f32_e32 v12, v62, v63
	v_add_f32_e32 v62, v62, v63
	v_cmp_eq_u32_e64 s[0:1], 1, v177
	s_nop 1
	v_cndmask_b32_e64 v62, v4, v62, s[0:1]
	v_cndmask_b32_e32 v12, v12, v62, vcc
	ds_bpermute_b32 v63, v68, v5
	v_mul_f32_e32 v62, v5, v65
	v_cmp_lt_i32_e32 vcc, 0, v177
	s_waitcnt lgkmcnt(0)
	v_mul_f32_e32 v63, v13, v63
	v_sub_f32_e32 v13, v62, v63
	v_add_f32_e32 v62, v62, v63
	v_cmp_eq_u32_e64 s[0:1], 1, v177
	s_nop 1
	v_cndmask_b32_e64 v62, v5, v62, s[0:1]
	v_cndmask_b32_e32 v13, v13, v62, vcc
	ds_bpermute_b32 v62, v68, v6
	s_waitcnt vmcnt(0)
	v_mul_f32_e32 v58, v6, v58
	v_cmp_lt_i32_e32 vcc, 0, v177
	s_waitcnt lgkmcnt(0)
	v_mul_f32_e32 v62, v14, v62
	v_sub_f32_e32 v14, v58, v62
	v_add_f32_e32 v58, v58, v62
	v_cmp_eq_u32_e64 s[0:1], 1, v177
	s_nop 1
	v_cndmask_b32_e64 v58, v6, v58, s[0:1]
	v_cndmask_b32_e32 v14, v14, v58, vcc
	ds_bpermute_b32 v62, v68, v7
	v_mul_f32_e32 v58, v7, v59
	v_cmp_lt_i32_e32 vcc, 0, v177
	s_waitcnt lgkmcnt(0)
	v_mul_f32_e32 v59, v15, v62
	v_sub_f32_e32 v15, v58, v59
	v_add_f32_e32 v58, v58, v59
	v_cmp_eq_u32_e64 s[0:1], 1, v177
	s_nop 1
	v_cndmask_b32_e64 v58, v7, v58, s[0:1]
	v_cndmask_b32_e32 v15, v15, v58, vcc
	ds_bpermute_b32 v59, v68, v8
	v_mul_f32_e32 v58, v8, v60
	v_cmp_lt_i32_e32 vcc, 0, v177
	s_waitcnt lgkmcnt(0)
	v_mul_f32_e32 v59, v16, v59
	v_sub_f32_e32 v16, v58, v59
	v_add_f32_e32 v58, v58, v59
	v_cmp_eq_u32_e64 s[0:1], 1, v177
	s_nop 1
	v_cndmask_b32_e64 v58, v8, v58, s[0:1]
	v_cndmask_b32_e32 v16, v16, v58, vcc
	ds_bpermute_b32 v59, v68, v9
	v_mul_f32_e32 v58, v9, v61
	v_cmp_lt_i32_e32 vcc, 0, v177
	s_waitcnt lgkmcnt(0)
	v_mul_f32_e32 v59, v17, v59
	v_sub_f32_e32 v17, v58, v59
	v_add_f32_e32 v58, v58, v59
	v_cmp_eq_u32_e64 s[0:1], 1, v177
	s_nop 1
	v_cndmask_b32_e64 v58, v9, v58, s[0:1]
	v_cndmask_b32_e32 v17, v17, v58, vcc

; DI void rope8(float (&v)[8], const float* __restrict__ rope, int s, int fq) {
;     const f32x4 c0 = *(const f32x4*)(rope + s * 16), c1 = *(const f32x4*)(rope + s * 16 + 4), s0 = *(const f32x4*)(rope + s * 16 + 8), s1 = *(const f32x4*)(rope + s * 16 + 12);
;     const float cs[8] = {c0[0], c0[1], c0[2], c0[3], c1[0], c1[1], c1[2], c1[3]}, sn[8] = {s0[0], s0[1], s0[2], s0[3], s1[0], s1[1], s1[2], s1[3]};
; #pragma unroll
;     for (int e = 0; e < 8; ++e) {
;         const float other = __shfl_xor(v[e], 16);
;         const float a = v[e] * cs[e], bq = other * sn[e];
;         v[e] = (fq == 0) ? (a - bq) : ((fq == 1) ? (a + bq) : v[e]);
;     }
;     DI void operator()(const pg8::f32x4 (&acc)[2][2][4][2], const pg8::Unit& u, int wr, int wc, int fr, int fq) const {
;     ...
;                         if ((wc & 1) == 0) rope8(v, rope, s, fq);
.LBB0_2250:
	s_andn2_b64 vcc, exec, s[10:11]
	s_cbranch_vccnz .LBB0_2300
	v_and_b32_e32 v11, 64, v188
	v_xor_b32_e32 v10, 16, v188
	v_add_u32_e32 v11, 64, v11
	v_cmp_lt_i32_e32 vcc, v10, v11
	v_lshlrev_b32_e32 v50, 6, v59
	s_nop 0
	v_cndmask_b32_e32 v10, v188, v10, vcc
	v_lshlrev_b32_e32 v60, 2, v10
	global_load_dwordx4 v[54:57], v50, s[68:69]
	global_load_dwordx4 v[10:13], v50, s[68:69] offset:32
	global_load_dwordx4 v[14:17], v50, s[68:69] offset:48
	s_nop 0
	global_load_dwordx4 v[50:53], v50, s[68:69] offset:16
	ds_bpermute_b32 v61, v60, v2
	v_cmp_lt_i32_e32 vcc, 0, v177
	s_waitcnt vmcnt(3)
	v_mul_f32_e32 v54, v2, v54
	s_waitcnt vmcnt(2) lgkmcnt(0)
	v_mul_f32_e32 v61, v10, v61
	v_sub_f32_e32 v10, v54, v61
	v_add_f32_e32 v54, v54, v61
	v_cmp_eq_u32_e64 s[0:1], 1, v177
	s_nop 1
	v_cndmask_b32_e64 v54, v2, v54, s[0:1]
	v_cndmask_b32_e32 v10, v10, v54, vcc
	ds_bpermute_b32 v61, v60, v3
	v_mul_f32_e32 v54, v3, v55
	v_cmp_lt_i32_e32 vcc, 0, v177
	s_waitcnt lgkmcnt(0)
	v_mul_f32_e32 v55, v11, v61
	v_sub_f32_e32 v11, v54, v55
	v_add_f32_e32 v54, v54, v55
	v_cmp_eq_u32_e64 s[0:1], 1, v177
	s_nop 1
	v_cndmask_b32_e64 v54, v3, v54, s[0:1]
	v_cndmask_b32_e32 v11, v11, v54, vcc
	ds_bpermute_b32 v55, v60, v4
	v_mul_f32_e32 v54, v4, v56
	v_cmp_lt_i32_e32 vcc, 0, v177
	s_waitcnt lgkmcnt(0)
	v_mul_f32_e32 v55, v12, v55
	v_sub_f32_e32 v12, v54, v55
	v_add_f32_e32 v54, v54, v55
	v_cmp_eq_u32_e64 s[0:1], 1, v177
	s_nop 1
	v_cndmask_b32_e64 v54, v4, v54, s[0:1]
	v_cndmask_b32_e32 v12, v12, v54, vcc
	ds_bpermute_b32 v55, v60, v5
	v_mul_f32_e32 v54, v5, v57
	v_cmp_lt_i32_e32 vcc, 0, v177
	s_waitcnt lgkmcnt(0)
	v_mul_f32_e32 v55, v13, v55
	v_sub_f32_e32 v13, v54, v55
	v_add_f32_e32 v54, v54, v55
	v_cmp_eq_u32_e64 s[0:1], 1, v177
	s_nop 1
	v_cndmask_b32_e64 v54, v5, v54, s[0:1]
	v_cndmask_b32_e32 v13, v13, v54, vcc
	ds_bpermute_b32 v54, v60, v6
	s_waitcnt vmcnt(0)
	v_mul_f32_e32 v50, v6, v50
	v_cmp_lt_i32_e32 vcc, 0, v177
	s_waitcnt lgkmcnt(0)
	v_mul_f32_e32 v54, v14, v54
	v_sub_f32_e32 v14, v50, v54
	v_add_f32_e32 v50, v50, v54
	v_cmp_eq_u32_e64 s[0:1], 1, v177
	s_nop 1
	v_cndmask_b32_e64 v50, v6, v50, s[0:1]
	v_cndmask_b32_e32 v14, v14, v50, vcc
	ds_bpermute_b32 v54, v60, v7
	v_mul_f32_e32 v50, v7, v51
	v_cmp_lt_i32_e32 vcc, 0, v177
	s_waitcnt lgkmcnt(0)
	v_mul_f32_e32 v51, v15, v54
	v_sub_f32_e32 v15, v50, v51
	v_add_f32_e32 v50, v50, v51
	v_cmp_eq_u32_e64 s[0:1], 1, v177
	s_nop 1
	v_cndmask_b32_e64 v50, v7, v50, s[0:1]
	v_cndmask_b32_e32 v15, v15, v50, vcc
	ds_bpermute_b32 v51, v60, v8
	v_mul_f32_e32 v50, v8, v52
	v_cmp_lt_i32_e32 vcc, 0, v177
	s_waitcnt lgkmcnt(0)
	v_mul_f32_e32 v51, v16, v51
	v_sub_f32_e32 v16, v50, v51
	v_add_f32_e32 v50, v50, v51
	v_cmp_eq_u32_e64 s[0:1], 1, v177
	s_nop 1
	v_cndmask_b32_e64 v50, v8, v50, s[0:1]
	v_cndmask_b32_e32 v16, v16, v50, vcc
	ds_bpermute_b32 v51, v60, v9
	v_mul_f32_e32 v50, v9, v53
	v_cmp_lt_i32_e32 vcc, 0, v177
	s_waitcnt lgkmcnt(0)
	v_mul_f32_e32 v51, v17, v51
	v_sub_f32_e32 v17, v50, v51
	v_add_f32_e32 v50, v50, v51
	v_cmp_eq_u32_e64 s[0:1], 1, v177
	s_nop 1
	v_cndmask_b32_e64 v50, v9, v50, s[0:1]
	v_cndmask_b32_e32 v17, v17, v50, vcc

; DI void rope8(float (&v)[8], const float* __restrict__ rope, int s, int fq) {
;     const f32x4 c0 = *(const f32x4*)(rope + s * 16), c1 = *(const f32x4*)(rope + s * 16 + 4), s0 = *(const f32x4*)(rope + s * 16 + 8), s1 = *(const f32x4*)(rope + s * 16 + 12);
;     const float cs[8] = {c0[0], c0[1], c0[2], c0[3], c1[0], c1[1], c1[2], c1[3]}, sn[8] = {s0[0], s0[1], s0[2], s0[3], s1[0], s1[1], s1[2], s1[3]};
; #pragma unroll
;     for (int e = 0; e < 8; ++e) {
;         const float other = __shfl_xor(v[e], 16);
;         const float a = v[e] * cs[e], bq = other * sn[e];
;         v[e] = (fq == 0) ? (a - bq) : ((fq == 1) ? (a + bq) : v[e]);
;     }
;     DI void operator()(const pg8::f32x4 (&acc)[2][2][4][2], const pg8::Unit& u, int wr, int wc, int fr, int fq) const {
;     ...
;                         if ((wc & 1) == 0) rope8(v, rope, s, fq);
.LBB0_2306:
	s_andn2_b64 vcc, exec, s[10:11]
	s_cbranch_vccnz .LBB0_2356
	v_and_b32_e32 v11, 64, v188
	v_xor_b32_e32 v10, 16, v188
	v_add_u32_e32 v11, 64, v11
	v_cmp_lt_i32_e32 vcc, v10, v11
	v_lshlrev_b32_e32 v42, 6, v51
	s_nop 0
	v_cndmask_b32_e32 v10, v188, v10, vcc
	v_lshlrev_b32_e32 v52, 2, v10
	global_load_dwordx4 v[46:49], v42, s[68:69]
	global_load_dwordx4 v[10:13], v42, s[68:69] offset:32
	global_load_dwordx4 v[14:17], v42, s[68:69] offset:48
	s_nop 0
	global_load_dwordx4 v[42:45], v42, s[68:69] offset:16
	ds_bpermute_b32 v53, v52, v2
	v_cmp_lt_i32_e32 vcc, 0, v177
	s_waitcnt vmcnt(3)
	v_mul_f32_e32 v46, v2, v46
	s_waitcnt vmcnt(2) lgkmcnt(0)
	v_mul_f32_e32 v53, v10, v53
	v_sub_f32_e32 v10, v46, v53
	v_add_f32_e32 v46, v46, v53
	v_cmp_eq_u32_e64 s[0:1], 1, v177
	s_nop 1
	v_cndmask_b32_e64 v46, v2, v46, s[0:1]
	v_cndmask_b32_e32 v10, v10, v46, vcc
	ds_bpermute_b32 v53, v52, v3
	v_mul_f32_e32 v46, v3, v47
	v_cmp_lt_i32_e32 vcc, 0, v177
	s_waitcnt lgkmcnt(0)
	v_mul_f32_e32 v47, v11, v53
	v_sub_f32_e32 v11, v46, v47
	v_add_f32_e32 v46, v46, v47
	v_cmp_eq_u32_e64 s[0:1], 1, v177
	s_nop 1
	v_cndmask_b32_e64 v46, v3, v46, s[0:1]
	v_cndmask_b32_e32 v11, v11, v46, vcc
	ds_bpermute_b32 v47, v52, v4
	v_mul_f32_e32 v46, v4, v48
	v_cmp_lt_i32_e32 vcc, 0, v177
	s_waitcnt lgkmcnt(0)
	v_mul_f32_e32 v47, v12, v47
	v_sub_f32_e32 v12, v46, v47
	v_add_f32_e32 v46, v46, v47
	v_cmp_eq_u32_e64 s[0:1], 1, v177
	s_nop 1
	v_cndmask_b32_e64 v46, v4, v46, s[0:1]
	v_cndmask_b32_e32 v12, v12, v46, vcc
	ds_bpermute_b32 v47, v52, v5
	v_mul_f32_e32 v46, v5, v49
	v_cmp_lt_i32_e32 vcc, 0, v177
	s_waitcnt lgkmcnt(0)
	v_mul_f32_e32 v47, v13, v47
	v_sub_f32_e32 v13, v46, v47
	v_add_f32_e32 v46, v46, v47
	v_cmp_eq_u32_e64 s[0:1], 1, v177
	s_nop 1
	v_cndmask_b32_e64 v46, v5, v46, s[0:1]
	v_cndmask_b32_e32 v13, v13, v46, vcc
	ds_bpermute_b32 v46, v52, v6
	s_waitcnt vmcnt(0)
	v_mul_f32_e32 v42, v6, v42
	v_cmp_lt_i32_e32 vcc, 0, v177
	s_waitcnt lgkmcnt(0)
	v_mul_f32_e32 v46, v14, v46
	v_sub_f32_e32 v14, v42, v46
	v_add_f32_e32 v42, v42, v46
	v_cmp_eq_u32_e64 s[0:1], 1, v177
	s_nop 1
	v_cndmask_b32_e64 v42, v6, v42, s[0:1]
	v_cndmask_b32_e32 v14, v14, v42, vcc
	ds_bpermute_b32 v46, v52, v7
	v_mul_f32_e32 v42, v7, v43
	v_cmp_lt_i32_e32 vcc, 0, v177
	s_waitcnt lgkmcnt(0)
	v_mul_f32_e32 v43, v15, v46
	v_sub_f32_e32 v15, v42, v43
	v_add_f32_e32 v42, v42, v43
	v_cmp_eq_u32_e64 s[0:1], 1, v177
	s_nop 1
	v_cndmask_b32_e64 v42, v7, v42, s[0:1]
	v_cndmask_b32_e32 v15, v15, v42, vcc
	ds_bpermute_b32 v43, v52, v8
	v_mul_f32_e32 v42, v8, v44
	v_cmp_lt_i32_e32 vcc, 0, v177
	s_waitcnt lgkmcnt(0)
	v_mul_f32_e32 v43, v16, v43
	v_sub_f32_e32 v16, v42, v43
	v_add_f32_e32 v42, v42, v43
	v_cmp_eq_u32_e64 s[0:1], 1, v177
	s_nop 1
	v_cndmask_b32_e64 v42, v8, v42, s[0:1]
	v_cndmask_b32_e32 v16, v16, v42, vcc
	ds_bpermute_b32 v43, v52, v9
	v_mul_f32_e32 v42, v9, v45
	v_cmp_lt_i32_e32 vcc, 0, v177
	s_waitcnt lgkmcnt(0)
	v_mul_f32_e32 v43, v17, v43
	v_sub_f32_e32 v17, v42, v43
	v_add_f32_e32 v42, v42, v43
	v_cmp_eq_u32_e64 s[0:1], 1, v177
	s_nop 1
	v_cndmask_b32_e64 v42, v9, v42, s[0:1]
	v_cndmask_b32_e32 v17, v17, v42, vcc

; DI void rope8(float (&v)[8], const float* __restrict__ rope, int s, int fq) {
;     const f32x4 c0 = *(const f32x4*)(rope + s * 16), c1 = *(const f32x4*)(rope + s * 16 + 4), s0 = *(const f32x4*)(rope + s * 16 + 8), s1 = *(const f32x4*)(rope + s * 16 + 12);
;     const float cs[8] = {c0[0], c0[1], c0[2], c0[3], c1[0], c1[1], c1[2], c1[3]}, sn[8] = {s0[0], s0[1], s0[2], s0[3], s1[0], s1[1], s1[2], s1[3]};
; #pragma unroll
;     for (int e = 0; e < 8; ++e) {
;         const float other = __shfl_xor(v[e], 16);
;         const float a = v[e] * cs[e], bq = other * sn[e];
;         v[e] = (fq == 0) ? (a - bq) : ((fq == 1) ? (a + bq) : v[e]);
;     }
;     DI void operator()(const pg8::f32x4 (&acc)[2][2][4][2], const pg8::Unit& u, int wr, int wc, int fr, int fq) const {
;     ...
;                         if ((wc & 1) == 0) rope8(v, rope, s, fq);
.LBB0_2362:
	s_andn2_b64 vcc, exec, s[10:11]
	s_cbranch_vccnz .LBB0_2412
	v_and_b32_e32 v11, 64, v188
	v_xor_b32_e32 v10, 16, v188
	v_add_u32_e32 v11, 64, v11
	v_cmp_lt_i32_e32 vcc, v10, v11
	v_lshlrev_b32_e32 v34, 6, v45
	s_nop 0
	v_cndmask_b32_e32 v10, v188, v10, vcc
	v_lshlrev_b32_e32 v46, 2, v10
	global_load_dwordx4 v[38:41], v34, s[68:69]
	global_load_dwordx4 v[10:13], v34, s[68:69] offset:32
	global_load_dwordx4 v[14:17], v34, s[68:69] offset:48
	s_nop 0
	global_load_dwordx4 v[34:37], v34, s[68:69] offset:16
	ds_bpermute_b32 v47, v46, v2
	v_cmp_lt_i32_e32 vcc, 0, v177
	s_waitcnt vmcnt(3)
	v_mul_f32_e32 v38, v2, v38
	s_waitcnt vmcnt(2) lgkmcnt(0)
	v_mul_f32_e32 v47, v10, v47
	v_sub_f32_e32 v10, v38, v47
	v_add_f32_e32 v38, v38, v47
	v_cmp_eq_u32_e64 s[0:1], 1, v177
	s_nop 1
	v_cndmask_b32_e64 v38, v2, v38, s[0:1]
	v_cndmask_b32_e32 v10, v10, v38, vcc
	ds_bpermute_b32 v47, v46, v3
	v_mul_f32_e32 v38, v3, v39
	v_cmp_lt_i32_e32 vcc, 0, v177
	s_waitcnt lgkmcnt(0)
	v_mul_f32_e32 v39, v11, v47
	v_sub_f32_e32 v11, v38, v39
	v_add_f32_e32 v38, v38, v39
	v_cmp_eq_u32_e64 s[0:1], 1, v177
	s_nop 1
	v_cndmask_b32_e64 v38, v3, v38, s[0:1]
	v_cndmask_b32_e32 v11, v11, v38, vcc
	ds_bpermute_b32 v39, v46, v4
	v_mul_f32_e32 v38, v4, v40
	v_cmp_lt_i32_e32 vcc, 0, v177
	s_waitcnt lgkmcnt(0)
	v_mul_f32_e32 v39, v12, v39
	v_sub_f32_e32 v12, v38, v39
	v_add_f32_e32 v38, v38, v39
	v_cmp_eq_u32_e64 s[0:1], 1, v177
	s_nop 1
	v_cndmask_b32_e64 v38, v4, v38, s[0:1]
	v_cndmask_b32_e32 v12, v12, v38, vcc
	ds_bpermute_b32 v39, v46, v5
	v_mul_f32_e32 v38, v5, v41
	v_cmp_lt_i32_e32 vcc, 0, v177
	s_waitcnt lgkmcnt(0)
	v_mul_f32_e32 v39, v13, v39
	v_sub_f32_e32 v13, v38, v39
	v_add_f32_e32 v38, v38, v39
	v_cmp_eq_u32_e64 s[0:1], 1, v177
	s_nop 1
	v_cndmask_b32_e64 v38, v5, v38, s[0:1]
	v_cndmask_b32_e32 v13, v13, v38, vcc
	ds_bpermute_b32 v38, v46, v6
	s_waitcnt vmcnt(0)
	v_mul_f32_e32 v34, v6, v34
	v_cmp_lt_i32_e32 vcc, 0, v177
	s_waitcnt lgkmcnt(0)
	v_mul_f32_e32 v38, v14, v38
	v_sub_f32_e32 v14, v34, v38
	v_add_f32_e32 v34, v34, v38
	v_cmp_eq_u32_e64 s[0:1], 1, v177
	s_nop 1
	v_cndmask_b32_e64 v34, v6, v34, s[0:1]
	v_cndmask_b32_e32 v14, v14, v34, vcc
	ds_bpermute_b32 v38, v46, v7
	v_mul_f32_e32 v34, v7, v35
	v_cmp_lt_i32_e32 vcc, 0, v177
	s_waitcnt lgkmcnt(0)
	v_mul_f32_e32 v35, v15, v38
	v_sub_f32_e32 v15, v34, v35
	v_add_f32_e32 v34, v34, v35
	v_cmp_eq_u32_e64 s[0:1], 1, v177
	s_nop 1
	v_cndmask_b32_e64 v34, v7, v34, s[0:1]
	v_cndmask_b32_e32 v15, v15, v34, vcc
	ds_bpermute_b32 v35, v46, v8
	v_mul_f32_e32 v34, v8, v36
	v_cmp_lt_i32_e32 vcc, 0, v177
	s_waitcnt lgkmcnt(0)
	v_mul_f32_e32 v35, v16, v35
	v_sub_f32_e32 v16, v34, v35
	v_add_f32_e32 v34, v34, v35
	v_cmp_eq_u32_e64 s[0:1], 1, v177
	s_nop 1
	v_cndmask_b32_e64 v34, v8, v34, s[0:1]
	v_cndmask_b32_e32 v16, v16, v34, vcc
	ds_bpermute_b32 v35, v46, v9
	v_mul_f32_e32 v34, v9, v37
	v_cmp_lt_i32_e32 vcc, 0, v177
	s_waitcnt lgkmcnt(0)
	v_mul_f32_e32 v35, v17, v35
	v_sub_f32_e32 v17, v34, v35
	v_add_f32_e32 v34, v34, v35
	v_cmp_eq_u32_e64 s[0:1], 1, v177
	s_nop 1
	v_cndmask_b32_e64 v34, v9, v34, s[0:1]
	v_cndmask_b32_e32 v17, v17, v34, vcc

; DI void rope8(float (&v)[8], const float* __restrict__ rope, int s, int fq) {
;     const f32x4 c0 = *(const f32x4*)(rope + s * 16), c1 = *(const f32x4*)(rope + s * 16 + 4), s0 = *(const f32x4*)(rope + s * 16 + 8), s1 = *(const f32x4*)(rope + s * 16 + 12);
;     const float cs[8] = {c0[0], c0[1], c0[2], c0[3], c1[0], c1[1], c1[2], c1[3]}, sn[8] = {s0[0], s0[1], s0[2], s0[3], s1[0], s1[1], s1[2], s1[3]};
; #pragma unroll
;     for (int e = 0; e < 8; ++e) {
;         const float other = __shfl_xor(v[e], 16);
;         const float a = v[e] * cs[e], bq = other * sn[e];
;         v[e] = (fq == 0) ? (a - bq) : ((fq == 1) ? (a + bq) : v[e]);
;     }
;     DI void operator()(const pg8::f32x4 (&acc)[2][2][4][2], const pg8::Unit& u, int wr, int wc, int fr, int fq) const {
;     ...
;                         if ((wc & 1) == 0) rope8(v, rope, s, fq);
.LBB0_2418:
	s_andn2_b64 vcc, exec, s[10:11]
	s_cbranch_vccnz .LBB0_2468
	v_and_b32_e32 v11, 64, v188
	v_xor_b32_e32 v10, 16, v188
	v_add_u32_e32 v11, 64, v11
	v_cmp_lt_i32_e32 vcc, v10, v11
	v_lshlrev_b32_e32 v26, 6, v35
	s_nop 0
	v_cndmask_b32_e32 v10, v188, v10, vcc
	v_lshlrev_b32_e32 v36, 2, v10
	global_load_dwordx4 v[30:33], v26, s[68:69]
	global_load_dwordx4 v[10:13], v26, s[68:69] offset:32
	global_load_dwordx4 v[14:17], v26, s[68:69] offset:48
	s_nop 0
	global_load_dwordx4 v[26:29], v26, s[68:69] offset:16
	ds_bpermute_b32 v37, v36, v2
	v_cmp_lt_i32_e32 vcc, 0, v177
	s_waitcnt vmcnt(3)
	v_mul_f32_e32 v30, v2, v30
	s_waitcnt vmcnt(2) lgkmcnt(0)
	v_mul_f32_e32 v37, v10, v37
	v_sub_f32_e32 v10, v30, v37
	v_add_f32_e32 v30, v30, v37
	v_cmp_eq_u32_e64 s[0:1], 1, v177
	s_nop 1
	v_cndmask_b32_e64 v30, v2, v30, s[0:1]
	v_cndmask_b32_e32 v10, v10, v30, vcc
	ds_bpermute_b32 v37, v36, v3
	v_mul_f32_e32 v30, v3, v31
	v_cmp_lt_i32_e32 vcc, 0, v177
	s_waitcnt lgkmcnt(0)
	v_mul_f32_e32 v31, v11, v37
	v_sub_f32_e32 v11, v30, v31
	v_add_f32_e32 v30, v30, v31
	v_cmp_eq_u32_e64 s[0:1], 1, v177
	s_nop 1
	v_cndmask_b32_e64 v30, v3, v30, s[0:1]
	v_cndmask_b32_e32 v11, v11, v30, vcc
	ds_bpermute_b32 v31, v36, v4
	v_mul_f32_e32 v30, v4, v32
	v_cmp_lt_i32_e32 vcc, 0, v177
	s_waitcnt lgkmcnt(0)
	v_mul_f32_e32 v31, v12, v31
	v_sub_f32_e32 v12, v30, v31
	v_add_f32_e32 v30, v30, v31
	v_cmp_eq_u32_e64 s[0:1], 1, v177
	s_nop 1
	v_cndmask_b32_e64 v30, v4, v30, s[0:1]
	v_cndmask_b32_e32 v12, v12, v30, vcc
	ds_bpermute_b32 v31, v36, v5
	v_mul_f32_e32 v30, v5, v33
	v_cmp_lt_i32_e32 vcc, 0, v177
	s_waitcnt lgkmcnt(0)
	v_mul_f32_e32 v31, v13, v31
	v_sub_f32_e32 v13, v30, v31
	v_add_f32_e32 v30, v30, v31
	v_cmp_eq_u32_e64 s[0:1], 1, v177
	s_nop 1
	v_cndmask_b32_e64 v30, v5, v30, s[0:1]
	v_cndmask_b32_e32 v13, v13, v30, vcc
	ds_bpermute_b32 v30, v36, v6
	s_waitcnt vmcnt(0)
	v_mul_f32_e32 v26, v6, v26
	v_cmp_lt_i32_e32 vcc, 0, v177
	s_waitcnt lgkmcnt(0)
	v_mul_f32_e32 v30, v14, v30
	v_sub_f32_e32 v14, v26, v30
	v_add_f32_e32 v26, v26, v30
	v_cmp_eq_u32_e64 s[0:1], 1, v177
	s_nop 1
	v_cndmask_b32_e64 v26, v6, v26, s[0:1]
	v_cndmask_b32_e32 v14, v14, v26, vcc
	ds_bpermute_b32 v30, v36, v7
	v_mul_f32_e32 v26, v7, v27
	v_cmp_lt_i32_e32 vcc, 0, v177
	s_waitcnt lgkmcnt(0)
	v_mul_f32_e32 v27, v15, v30
	v_sub_f32_e32 v15, v26, v27
	v_add_f32_e32 v26, v26, v27
	v_cmp_eq_u32_e64 s[0:1], 1, v177
	s_nop 1
	v_cndmask_b32_e64 v26, v7, v26, s[0:1]
	v_cndmask_b32_e32 v15, v15, v26, vcc
	ds_bpermute_b32 v27, v36, v8
	v_mul_f32_e32 v26, v8, v28
	v_cmp_lt_i32_e32 vcc, 0, v177
	s_waitcnt lgkmcnt(0)
	v_mul_f32_e32 v27, v16, v27
	v_sub_f32_e32 v16, v26, v27
	v_add_f32_e32 v26, v26, v27
	v_cmp_eq_u32_e64 s[0:1], 1, v177
	s_nop 1
	v_cndmask_b32_e64 v26, v8, v26, s[0:1]
	v_cndmask_b32_e32 v16, v16, v26, vcc
	ds_bpermute_b32 v27, v36, v9
	v_mul_f32_e32 v26, v9, v29
	v_cmp_lt_i32_e32 vcc, 0, v177
	s_waitcnt lgkmcnt(0)
	v_mul_f32_e32 v27, v17, v27
	v_sub_f32_e32 v17, v26, v27
	v_add_f32_e32 v26, v26, v27
	v_cmp_eq_u32_e64 s[0:1], 1, v177
	s_nop 1
	v_cndmask_b32_e64 v26, v9, v26, s[0:1]
	v_cndmask_b32_e32 v17, v17, v26, vcc

; DI void rope8(float (&v)[8], const float* __restrict__ rope, int s, int fq) {
;     const f32x4 c0 = *(const f32x4*)(rope + s * 16), c1 = *(const f32x4*)(rope + s * 16 + 4), s0 = *(const f32x4*)(rope + s * 16 + 8), s1 = *(const f32x4*)(rope + s * 16 + 12);
;     const float cs[8] = {c0[0], c0[1], c0[2], c0[3], c1[0], c1[1], c1[2], c1[3]}, sn[8] = {s0[0], s0[1], s0[2], s0[3], s1[0], s1[1], s1[2], s1[3]};
; #pragma unroll
;     for (int e = 0; e < 8; ++e) {
;         const float other = __shfl_xor(v[e], 16);
;         const float a = v[e] * cs[e], bq = other * sn[e];
;         v[e] = (fq == 0) ? (a - bq) : ((fq == 1) ? (a + bq) : v[e]);
;     }
;     DI void operator()(const pg8::f32x4 (&acc)[2][2][4][2], const pg8::Unit& u, int wr, int wc, int fr, int fq) const {
;     ...
;                         if ((wc & 1) == 0) rope8(v, rope, s, fq);
.LBB0_2474:
	s_andn2_b64 vcc, exec, s[6:7]
	s_cbranch_vccnz .LBB0_2524
	v_and_b32_e32 v11, 64, v188
	v_xor_b32_e32 v10, 16, v188
	v_add_u32_e32 v11, 64, v11
	v_cmp_lt_i32_e32 vcc, v10, v11
	v_lshlrev_b32_e32 v18, 6, v27
	s_nop 0
	v_cndmask_b32_e32 v10, v188, v10, vcc
	v_lshlrev_b32_e32 v28, 2, v10
	global_load_dwordx4 v[22:25], v18, s[68:69]
	global_load_dwordx4 v[10:13], v18, s[68:69] offset:32
	global_load_dwordx4 v[14:17], v18, s[68:69] offset:48
	s_nop 0
	global_load_dwordx4 v[18:21], v18, s[68:69] offset:16
	ds_bpermute_b32 v29, v28, v2
	v_cmp_lt_i32_e32 vcc, 0, v177
	s_waitcnt vmcnt(3)
	v_mul_f32_e32 v22, v2, v22
	s_waitcnt vmcnt(2) lgkmcnt(0)
	v_mul_f32_e32 v29, v10, v29
	v_sub_f32_e32 v10, v22, v29
	v_add_f32_e32 v22, v22, v29
	v_cmp_eq_u32_e64 s[0:1], 1, v177
	s_nop 1
	v_cndmask_b32_e64 v22, v2, v22, s[0:1]
	v_cndmask_b32_e32 v10, v10, v22, vcc
	ds_bpermute_b32 v29, v28, v3
	v_mul_f32_e32 v22, v3, v23
	v_cmp_lt_i32_e32 vcc, 0, v177
	s_waitcnt lgkmcnt(0)
	v_mul_f32_e32 v23, v11, v29
	v_sub_f32_e32 v11, v22, v23
	v_add_f32_e32 v22, v22, v23
	v_cmp_eq_u32_e64 s[0:1], 1, v177
	s_nop 1
	v_cndmask_b32_e64 v22, v3, v22, s[0:1]
	v_cndmask_b32_e32 v11, v11, v22, vcc
	ds_bpermute_b32 v23, v28, v4
	v_mul_f32_e32 v22, v4, v24
	v_cmp_lt_i32_e32 vcc, 0, v177
	s_waitcnt lgkmcnt(0)
	v_mul_f32_e32 v23, v12, v23
	v_sub_f32_e32 v12, v22, v23
	v_add_f32_e32 v22, v22, v23
	v_cmp_eq_u32_e64 s[0:1], 1, v177
	s_nop 1
	v_cndmask_b32_e64 v22, v4, v22, s[0:1]
	v_cndmask_b32_e32 v12, v12, v22, vcc
	ds_bpermute_b32 v23, v28, v5
	v_mul_f32_e32 v22, v5, v25
	v_cmp_lt_i32_e32 vcc, 0, v177
	s_waitcnt lgkmcnt(0)
	v_mul_f32_e32 v23, v13, v23
	v_sub_f32_e32 v13, v22, v23
	v_add_f32_e32 v22, v22, v23
	v_cmp_eq_u32_e64 s[0:1], 1, v177
	s_nop 1
	v_cndmask_b32_e64 v22, v5, v22, s[0:1]
	v_cndmask_b32_e32 v13, v13, v22, vcc
	ds_bpermute_b32 v22, v28, v6
	s_waitcnt vmcnt(0)
	v_mul_f32_e32 v18, v6, v18
	v_cmp_lt_i32_e32 vcc, 0, v177
	s_waitcnt lgkmcnt(0)
	v_mul_f32_e32 v22, v14, v22
	v_sub_f32_e32 v14, v18, v22
	v_add_f32_e32 v18, v18, v22
	v_cmp_eq_u32_e64 s[0:1], 1, v177
	s_nop 1
	v_cndmask_b32_e64 v18, v6, v18, s[0:1]
	v_cndmask_b32_e32 v14, v14, v18, vcc
	ds_bpermute_b32 v22, v28, v7
	v_mul_f32_e32 v18, v7, v19
	v_cmp_lt_i32_e32 vcc, 0, v177
	s_waitcnt lgkmcnt(0)
	v_mul_f32_e32 v19, v15, v22
	v_sub_f32_e32 v15, v18, v19
	v_add_f32_e32 v18, v18, v19
	v_cmp_eq_u32_e64 s[0:1], 1, v177
	s_nop 1
	v_cndmask_b32_e64 v18, v7, v18, s[0:1]
	v_cndmask_b32_e32 v15, v15, v18, vcc
	ds_bpermute_b32 v19, v28, v8
	v_mul_f32_e32 v18, v8, v20
	v_cmp_lt_i32_e32 vcc, 0, v177
	s_waitcnt lgkmcnt(0)
	v_mul_f32_e32 v19, v16, v19
	v_sub_f32_e32 v16, v18, v19
	v_add_f32_e32 v18, v18, v19
	v_cmp_eq_u32_e64 s[0:1], 1, v177
	s_nop 1
	v_cndmask_b32_e64 v18, v8, v18, s[0:1]
	v_cndmask_b32_e32 v16, v16, v18, vcc
	ds_bpermute_b32 v19, v28, v9
	v_mul_f32_e32 v18, v9, v21
	v_cmp_lt_i32_e32 vcc, 0, v177
	s_waitcnt lgkmcnt(0)
	v_mul_f32_e32 v19, v17, v19
	v_sub_f32_e32 v17, v18, v19
	v_add_f32_e32 v18, v18, v19
	v_cmp_eq_u32_e64 s[0:1], 1, v177
	s_nop 1
	v_cndmask_b32_e64 v18, v9, v18, s[0:1]
	v_cndmask_b32_e32 v17, v17, v18, vcc
